# GEMM mainloops: removed the 36 compiler-duplicated s_waitcnt lgkmcnt(0) right after the inline-asm lgkmcnt(0) (6 per loop, 6 loops)
# speedup vs baseline: 1.0188x; 1.0111x over previous
; #define PG8_STAGE(bufoff, gbase, voff) do { _Pragma("unroll") for (int _i = 0; _i < 2; ++_i) \
;         __builtin_amdgcn_global_load_lds((const unsigned*)((const char*)(gbase) + (voff)[_i]), (LAS unsigned*)(lds + (bufoff) + ldsw + _i * 8192), 16, 0, 0); } while (0)
; #define PG8_LDA(dst, b, h) do { _Pragma("unroll") for (int m = 0; m < 4; ++m) _Pragma("unroll") for (int k = 0; k < 2; ++k) dst[m][k] = *(const LAS bf16x8*)(lds + PG8_SA(b, h) + aoff + m * 2048 + k * 1024); } while (0)
; #define PG8_LDB(dst, b, h) do { _Pragma("unroll") for (int n = 0; n < 2; ++n) _Pragma("unroll") for (int k = 0; k < 2; ++k) dst[n][k] = *(const LAS bf16x8*)(lds + PG8_SB(b, h) + boff + n * 2048 + k * 1024); } while (0)
; #define PG8_MMA(ai, bj, At, Bt) do { __builtin_amdgcn_s_setprio(1); _Pragma("unroll") for (int m = 0; m < 4; ++m) _Pragma("unroll") for (int n = 0; n < 2; ++n) _Pragma("unroll") for (int k = 0; k < 2; ++k) \
;         acc[ai][bj][m][n] = __builtin_amdgcn_mfma_f32_16x16x32_bf16(Bt[n][k], At[m][k], acc[ai][bj][m][n], 0, 0, 0); __builtin_amdgcn_s_setprio(0); } while (0)
; #define PG8_WAIT_L(n) asm volatile("s_waitcnt lgkmcnt(" #n ")" ::: "memory")
; #define PG8_BAR __builtin_amdgcn_s_barrier()
; #define PG8_SCHED __builtin_amdgcn_sched_barrier(0)
; template <class Epi>
; __device__ __forceinline__ void gemm_phase(LAS unsigned char* lds, const Gemm g, const StaticOrder& S, const Epi& E, const int tid) {
;     ...
;             PG8_LDB(B0, 0, 0); PG8_SCHED; PG8_LDA(At, 0, 0); PG8_STAGE(PG8_SA(1, 1), a1 + hstep, voffA);
;             PG8_WAIT_L(8); PG8_BAR; PG8_WAIT_L(0); PG8_MMA(0, 0, At, B0); PG8_BAR; PG8_SCHED;
;             PG8_LDB(B1, 0, 1); PG8_STAGE(PG8_SB(0, 0), b2, voffB);
;             PG8_BAR; PG8_WAIT_L(0); PG8_MMA(0, 1, At, B1); PG8_BAR;
;             PG8_LDA(At, 0, 1); PG8_STAGE(PG8_SA(0, 0), a2, voffA);
;             PG8_BAR; PG8_WAIT_L(0); PG8_MMA(1, 0, At, B0); PG8_BAR; PG8_SCHED;
.LBB0_40:
	s_add_u32 s20, s18, 0xffe00080
	s_addc_u32 s21, s19, -1
	s_add_i32 s50, 0, 0x10000
	v_add_u32_e32 v70, s50, v173
	ds_read_b128 v[50:53], v70
	ds_read_b128 v[54:57], v70 offset:1024
	ds_read_b128 v[66:69], v70 offset:2048
	ds_read_b128 v[70:73], v70 offset:3072
	s_cmpk_eq_i32 s49, 0x7c
	s_cselect_b32 s23, s13, s21
	s_cselect_b32 s22, s44, s20
	s_cselect_b32 s21, s11, s48
	s_cselect_b32 s20, s45, s47
	v_lshl_add_u64 v[170:171], s[18:19], 0, v[168:169]
	s_add_i32 m0, s3, 0xc000
	ds_read_b128 v[176:179], v174
	ds_read_b128 v[180:183], v174 offset:1024
	ds_read_b128 v[184:187], v174 offset:2048
	ds_read_b128 v[188:191], v174 offset:3072
	ds_read_b128 v[192:195], v174 offset:4096
	ds_read_b128 v[196:199], v174 offset:5120
	ds_read_b128 v[210:213], v174 offset:6144
	ds_read_b128 v[214:217], v174 offset:7168
	global_load_lds_dwordx4 v[170:171], off
	v_lshl_add_u64 v[170:171], s[18:19], 0, v[166:167]
	s_add_i32 m0, s3, 0xe000
	s_nop 0
	global_load_lds_dwordx4 v[170:171], off
	s_waitcnt lgkmcnt(8)
	s_barrier
	s_waitcnt lgkmcnt(0)
	s_setprio 1
	v_mfma_f32_16x16x32_bf16 v[142:145], v[50:53], v[176:179], v[142:145]
	v_mfma_f32_16x16x32_bf16 v[138:141], v[66:69], v[176:179], v[138:141]
	v_mfma_f32_16x16x32_bf16 v[126:129], v[50:53], v[184:187], v[126:129]
	v_mfma_f32_16x16x32_bf16 v[122:125], v[66:69], v[184:187], v[122:125]
	v_mfma_f32_16x16x32_bf16 v[110:113], v[50:53], v[192:195], v[110:113]
	v_mfma_f32_16x16x32_bf16 v[106:109], v[66:69], v[192:195], v[106:109]
	v_mfma_f32_16x16x32_bf16 v[94:97], v[50:53], v[210:213], v[94:97]
	v_mfma_f32_16x16x32_bf16 v[90:93], v[66:69], v[210:213], v[90:93]
	v_mfma_f32_16x16x32_bf16 v[142:145], v[54:57], v[180:183], v[142:145]
	v_mfma_f32_16x16x32_bf16 v[138:141], v[70:73], v[180:183], v[138:141]
	v_mfma_f32_16x16x32_bf16 v[126:129], v[54:57], v[188:191], v[126:129]
	v_mfma_f32_16x16x32_bf16 v[122:125], v[70:73], v[188:191], v[122:125]
	v_mfma_f32_16x16x32_bf16 v[110:113], v[54:57], v[196:199], v[110:113]
	v_mfma_f32_16x16x32_bf16 v[106:109], v[70:73], v[196:199], v[106:109]
	v_mfma_f32_16x16x32_bf16 v[94:97], v[54:57], v[214:217], v[94:97]
	v_mfma_f32_16x16x32_bf16 v[90:93], v[70:73], v[214:217], v[90:93]
	s_setprio 0
	s_barrier
	s_add_i32 s54, 0, 0x14000
	v_add_u32_e32 v170, s54, v173
	s_add_i32 s50, s50, s31
	ds_read_b128 v[218:221], v170
	ds_read_b128 v[222:225], v170 offset:1024
	ds_read_b128 v[226:229], v170 offset:2048
	ds_read_b128 v[230:233], v170 offset:3072
	v_lshl_add_u64 v[170:171], s[20:21], 0, v[0:1]
	s_mov_b32 m0, s50
	v_lshl_add_u64 v[200:201], s[20:21], 0, v[164:165]
	global_load_lds_dwordx4 v[170:171], off
	s_add_i32 m0, s50, 0x2000
	s_nop 0
	global_load_lds_dwordx4 v[200:201], off
	s_barrier
	s_waitcnt lgkmcnt(0)
	s_setprio 1
	v_mfma_f32_16x16x32_bf16 v[134:137], v[218:221], v[176:179], v[134:137]
	v_mfma_f32_16x16x32_bf16 v[130:133], v[226:229], v[176:179], v[130:133]
	v_mfma_f32_16x16x32_bf16 v[118:121], v[218:221], v[184:187], v[118:121]
	v_mfma_f32_16x16x32_bf16 v[114:117], v[226:229], v[184:187], v[114:117]
	v_mfma_f32_16x16x32_bf16 v[102:105], v[218:221], v[192:195], v[102:105]
	v_mfma_f32_16x16x32_bf16 v[98:101], v[226:229], v[192:195], v[98:101]
	v_mfma_f32_16x16x32_bf16 v[86:89], v[218:221], v[210:213], v[86:89]
	v_mfma_f32_16x16x32_bf16 v[82:85], v[226:229], v[210:213], v[82:85]
	v_mfma_f32_16x16x32_bf16 v[134:137], v[222:225], v[180:183], v[134:137]
	v_mfma_f32_16x16x32_bf16 v[130:133], v[230:233], v[180:183], v[130:133]
	v_mfma_f32_16x16x32_bf16 v[118:121], v[222:225], v[188:191], v[118:121]
	v_mfma_f32_16x16x32_bf16 v[114:117], v[230:233], v[188:191], v[114:117]
	v_mfma_f32_16x16x32_bf16 v[102:105], v[222:225], v[196:199], v[102:105]
	v_mfma_f32_16x16x32_bf16 v[98:101], v[230:233], v[196:199], v[98:101]
	v_mfma_f32_16x16x32_bf16 v[86:89], v[222:225], v[214:217], v[86:89]
	v_mfma_f32_16x16x32_bf16 v[82:85], v[230:233], v[214:217], v[82:85]
	s_setprio 0
	s_mov_b32 m0, s3
	v_lshl_add_u64 v[234:235], s[22:23], 0, v[160:161]
	s_barrier
	ds_read_b128 v[176:179], v174 offset:16384
	ds_read_b128 v[180:183], v174 offset:17408
	ds_read_b128 v[184:187], v174 offset:18432
	ds_read_b128 v[188:191], v174 offset:19456
	ds_read_b128 v[192:195], v174 offset:20480
	ds_read_b128 v[196:199], v174 offset:21504
	ds_read_b128 v[210:213], v174 offset:22528
	ds_read_b128 v[214:217], v174 offset:23552
	global_load_lds_dwordx4 v[234:235], off
	v_lshl_add_u64 v[236:237], s[22:23], 0, v[162:163]
	s_mov_b32 m0, s34
	s_nop 0
	global_load_lds_dwordx4 v[236:237], off
	s_barrier
	s_waitcnt lgkmcnt(0)
	s_setprio 1
	v_mfma_f32_16x16x32_bf16 v[78:81], v[50:53], v[176:179], v[78:81]
	v_mfma_f32_16x16x32_bf16 v[74:77], v[66:69], v[176:179], v[74:77]
	v_mfma_f32_16x16x32_bf16 v[46:49], v[50:53], v[184:187], v[46:49]
	v_mfma_f32_16x16x32_bf16 v[42:45], v[66:69], v[184:187], v[42:45]
	v_mfma_f32_16x16x32_bf16 v[30:33], v[50:53], v[192:195], v[30:33]
	v_mfma_f32_16x16x32_bf16 v[26:29], v[66:69], v[192:195], v[26:29]
	v_mfma_f32_16x16x32_bf16 v[14:17], v[50:53], v[210:213], v[14:17]
	v_mfma_f32_16x16x32_bf16 v[10:13], v[66:69], v[210:213], v[10:13]
	v_mfma_f32_16x16x32_bf16 v[78:81], v[54:57], v[180:183], v[78:81]
	v_mfma_f32_16x16x32_bf16 v[74:77], v[70:73], v[180:183], v[74:77]
	v_mfma_f32_16x16x32_bf16 v[46:49], v[54:57], v[188:191], v[46:49]
	v_mfma_f32_16x16x32_bf16 v[42:45], v[70:73], v[188:191], v[42:45]
	v_mfma_f32_16x16x32_bf16 v[30:33], v[54:57], v[196:199], v[30:33]
	v_mfma_f32_16x16x32_bf16 v[26:29], v[70:73], v[196:199], v[26:29]
	v_mfma_f32_16x16x32_bf16 v[14:17], v[54:57], v[214:217], v[14:17]
	v_mfma_f32_16x16x32_bf16 v[10:13], v[70:73], v[214:217], v[10:13]
	s_setprio 0
	s_barrier
; #define PG8_STAGE(bufoff, gbase, voff) do { _Pragma("unroll") for (int _i = 0; _i < 2; ++_i) \
;         __builtin_amdgcn_global_load_lds((const unsigned*)((const char*)(gbase) + (voff)[_i]), (LAS unsigned*)(lds + (bufoff) + ldsw + _i * 8192), 16, 0, 0); } while (0)
; #define PG8_LDA(dst, b, h) do { _Pragma("unroll") for (int m = 0; m < 4; ++m) _Pragma("unroll") for (int k = 0; k < 2; ++k) dst[m][k] = *(const LAS bf16x8*)(lds + PG8_SA(b, h) + aoff + m * 2048 + k * 1024); } while (0)
; #define PG8_LDB(dst, b, h) do { _Pragma("unroll") for (int n = 0; n < 2; ++n) _Pragma("unroll") for (int k = 0; k < 2; ++k) dst[n][k] = *(const LAS bf16x8*)(lds + PG8_SB(b, h) + boff + n * 2048 + k * 1024); } while (0)
; #define PG8_MMA(ai, bj, At, Bt) do { __builtin_amdgcn_s_setprio(1); _Pragma("unroll") for (int m = 0; m < 4; ++m) _Pragma("unroll") for (int n = 0; n < 2; ++n) _Pragma("unroll") for (int k = 0; k < 2; ++k) \
;         acc[ai][bj][m][n] = __builtin_amdgcn_mfma_f32_16x16x32_bf16(Bt[n][k], At[m][k], acc[ai][bj][m][n], 0, 0, 0); __builtin_amdgcn_s_setprio(0); } while (0)
; #define PG8_WAIT_V(n) asm volatile("s_waitcnt vmcnt(" #n ")" ::: "memory")
; #define PG8_WAIT_L(n) asm volatile("s_waitcnt lgkmcnt(" #n ")" ::: "memory")
; #define PG8_BAR __builtin_amdgcn_s_barrier()
; #define PG8_SCHED __builtin_amdgcn_sched_barrier(0)
; template <class Epi>
; __device__ __forceinline__ void gemm_phase(LAS unsigned char* lds, const Gemm g, const StaticOrder& S, const Epi& E, const int tid) {
;     ...
;             PG8_STAGE(PG8_SB(0, 1), b2 + hstep, voffB);
;             PG8_WAIT_V(6); PG8_BAR; PG8_MMA(1, 1, At, B1); PG8_BAR;
;             PG8_LDB(B0, 1, 0); PG8_SCHED; PG8_LDA(At, 1, 0); PG8_STAGE(PG8_SA(0, 1), a2 + hstep, voffA);
;             PG8_WAIT_L(8); PG8_BAR; PG8_WAIT_L(0); PG8_MMA(0, 0, At, B0); PG8_BAR; PG8_SCHED;
;             PG8_LDB(B1, 1, 1); PG8_STAGE(PG8_SB(1, 0), b3, voffB);
;             PG8_BAR; PG8_WAIT_L(0); PG8_MMA(0, 1, At, B1); PG8_BAR;
;             PG8_LDA(At, 1, 1); PG8_STAGE(PG8_SA(1, 0), a3, voffA);
;             PG8_BAR; PG8_WAIT_L(0); PG8_MMA(1, 0, At, B0); PG8_BAR; PG8_SCHED;
	s_add_u32 s52, s20, 0x200000
	s_addc_u32 s53, s21, 0
	s_add_i32 s50, s54, s31
	v_lshl_add_u64 v[50:51], s[52:53], 0, v[0:1]
	s_mov_b32 m0, s50
	s_nop 0
	global_load_lds_dwordx4 v[50:51], off
	v_lshl_add_u64 v[50:51], s[52:53], 0, v[164:165]
	s_add_i32 m0, s50, 0x2000
	s_nop 0
	global_load_lds_dwordx4 v[50:51], off
	s_waitcnt vmcnt(6)
	s_barrier
	s_setprio 1
	v_mfma_f32_16x16x32_bf16 v[38:41], v[218:221], v[184:187], v[38:41]
	v_mfma_f32_16x16x32_bf16 v[34:37], v[226:229], v[184:187], v[34:37]
	v_mfma_f32_16x16x32_bf16 v[22:25], v[218:221], v[192:195], v[22:25]
	v_mfma_f32_16x16x32_bf16 v[18:21], v[226:229], v[192:195], v[18:21]
	v_mfma_f32_16x16x32_bf16 v[6:9], v[218:221], v[210:213], v[6:9]
	v_mfma_f32_16x16x32_bf16 v[2:5], v[226:229], v[210:213], v[2:5]
	v_mfma_f32_16x16x32_bf16 v[50:53], v[218:221], v[176:179], v[62:65]
	v_mfma_f32_16x16x32_bf16 v[54:57], v[226:229], v[176:179], v[58:61]
	v_mfma_f32_16x16x32_bf16 v[38:41], v[222:225], v[188:191], v[38:41]
	v_mfma_f32_16x16x32_bf16 v[34:37], v[230:233], v[188:191], v[34:37]
	v_mfma_f32_16x16x32_bf16 v[22:25], v[222:225], v[196:199], v[22:25]
	v_mfma_f32_16x16x32_bf16 v[18:21], v[230:233], v[196:199], v[18:21]
	v_mfma_f32_16x16x32_bf16 v[6:9], v[222:225], v[214:217], v[6:9]
	v_mfma_f32_16x16x32_bf16 v[2:5], v[230:233], v[214:217], v[2:5]
	v_mfma_f32_16x16x32_bf16 v[50:53], v[222:225], v[180:183], v[50:53]
	v_mfma_f32_16x16x32_bf16 v[54:57], v[230:233], v[180:183], v[54:57]
	s_setprio 0
	s_add_i32 s50, 0, 0x18000
	v_add_u32_e32 v70, s50, v173
	s_barrier
	ds_read_b128 v[58:61], v70
	ds_read_b128 v[62:65], v70 offset:1024
	ds_read_b128 v[66:69], v70 offset:2048
	ds_read_b128 v[70:73], v70 offset:3072
	s_add_u32 s22, s22, 0x200000
	s_addc_u32 s23, s23, 0
	s_mov_b32 m0, s35
	v_lshl_add_u64 v[218:219], s[22:23], 0, v[160:161]
	ds_read_b128 v[176:179], v174 offset:32768
	ds_read_b128 v[180:183], v174 offset:33792
	ds_read_b128 v[184:187], v174 offset:34816
	ds_read_b128 v[188:191], v174 offset:35840
	ds_read_b128 v[192:195], v174 offset:36864
	ds_read_b128 v[196:199], v174 offset:37888
	ds_read_b128 v[210:213], v174 offset:38912
	ds_read_b128 v[214:217], v174 offset:39936
	global_load_lds_dwordx4 v[218:219], off
	v_lshl_add_u64 v[218:219], s[22:23], 0, v[162:163]
	s_mov_b32 m0, s36
	s_nop 0
	global_load_lds_dwordx4 v[218:219], off
	s_waitcnt lgkmcnt(8)
	s_barrier
	s_waitcnt lgkmcnt(0)
	s_setprio 1
	v_mfma_f32_16x16x32_bf16 v[142:145], v[58:61], v[176:179], v[142:145]
	v_mfma_f32_16x16x32_bf16 v[138:141], v[66:69], v[176:179], v[138:141]
	v_mfma_f32_16x16x32_bf16 v[126:129], v[58:61], v[184:187], v[126:129]
	v_mfma_f32_16x16x32_bf16 v[122:125], v[66:69], v[184:187], v[122:125]
	v_mfma_f32_16x16x32_bf16 v[110:113], v[58:61], v[192:195], v[110:113]
	v_mfma_f32_16x16x32_bf16 v[106:109], v[66:69], v[192:195], v[106:109]
	v_mfma_f32_16x16x32_bf16 v[94:97], v[58:61], v[210:213], v[94:97]
	v_mfma_f32_16x16x32_bf16 v[90:93], v[66:69], v[210:213], v[90:93]
	v_mfma_f32_16x16x32_bf16 v[142:145], v[62:65], v[180:183], v[142:145]
	v_mfma_f32_16x16x32_bf16 v[138:141], v[70:73], v[180:183], v[138:141]
	v_mfma_f32_16x16x32_bf16 v[126:129], v[62:65], v[188:191], v[126:129]
	v_mfma_f32_16x16x32_bf16 v[122:125], v[70:73], v[188:191], v[122:125]
	v_mfma_f32_16x16x32_bf16 v[110:113], v[62:65], v[196:199], v[110:113]
	v_mfma_f32_16x16x32_bf16 v[106:109], v[70:73], v[196:199], v[106:109]
	v_mfma_f32_16x16x32_bf16 v[94:97], v[62:65], v[214:217], v[94:97]
	v_mfma_f32_16x16x32_bf16 v[90:93], v[70:73], v[214:217], v[90:93]
	s_setprio 0
	s_barrier
	s_add_i32 s22, 0, 0x1c000
	s_add_i32 s23, s50, s31
	v_add_u32_e32 v175, s22, v173
	v_lshl_add_u64 v[170:171], v[170:171], 0, s[56:57]
	s_mov_b32 m0, s23
	ds_read_b128 v[218:221], v175
	ds_read_b128 v[222:225], v175 offset:1024
	ds_read_b128 v[226:229], v175 offset:2048
	ds_read_b128 v[230:233], v175 offset:3072
	global_load_lds_dwordx4 v[170:171], off
	v_lshl_add_u64 v[170:171], v[200:201], 0, s[56:57]
	s_add_i32 m0, s23, 0x2000
	s_nop 0
	global_load_lds_dwordx4 v[170:171], off
	s_barrier
	s_waitcnt lgkmcnt(0)
	s_setprio 1
	v_mfma_f32_16x16x32_bf16 v[134:137], v[218:221], v[176:179], v[134:137]
	v_mfma_f32_16x16x32_bf16 v[130:133], v[226:229], v[176:179], v[130:133]
	v_mfma_f32_16x16x32_bf16 v[118:121], v[218:221], v[184:187], v[118:121]
	v_mfma_f32_16x16x32_bf16 v[114:117], v[226:229], v[184:187], v[114:117]
	v_mfma_f32_16x16x32_bf16 v[102:105], v[218:221], v[192:195], v[102:105]
	v_mfma_f32_16x16x32_bf16 v[98:101], v[226:229], v[192:195], v[98:101]
	v_mfma_f32_16x16x32_bf16 v[86:89], v[218:221], v[210:213], v[86:89]
	v_mfma_f32_16x16x32_bf16 v[82:85], v[226:229], v[210:213], v[82:85]
	v_mfma_f32_16x16x32_bf16 v[134:137], v[222:225], v[180:183], v[134:137]
	v_mfma_f32_16x16x32_bf16 v[130:133], v[230:233], v[180:183], v[130:133]
	v_mfma_f32_16x16x32_bf16 v[118:121], v[222:225], v[188:191], v[118:121]
	v_mfma_f32_16x16x32_bf16 v[114:117], v[230:233], v[188:191], v[114:117]
	v_mfma_f32_16x16x32_bf16 v[102:105], v[222:225], v[196:199], v[102:105]
	v_mfma_f32_16x16x32_bf16 v[98:101], v[230:233], v[196:199], v[98:101]
	v_mfma_f32_16x16x32_bf16 v[86:89], v[222:225], v[214:217], v[86:89]
	v_mfma_f32_16x16x32_bf16 v[82:85], v[230:233], v[214:217], v[82:85]
	s_setprio 0
	s_mov_b32 m0, s39
	v_lshl_add_u64 v[170:171], v[234:235], 0, s[56:57]
	s_barrier
	ds_read_b128 v[176:179], v174 offset:49152
	ds_read_b128 v[180:183], v174 offset:50176
	ds_read_b128 v[184:187], v174 offset:51200
	ds_read_b128 v[188:191], v174 offset:52224
	ds_read_b128 v[192:195], v174 offset:53248
	ds_read_b128 v[196:199], v174 offset:54272
	ds_read_b128 v[210:213], v174 offset:55296
	ds_read_b128 v[214:217], v174 offset:56320
	global_load_lds_dwordx4 v[170:171], off
	v_lshl_add_u64 v[170:171], v[236:237], 0, s[56:57]
	s_mov_b32 m0, s40
	s_nop 0
	global_load_lds_dwordx4 v[170:171], off
	s_barrier
; __device__ __forceinline__ unsigned pk2(float lo, float hi) { f32x2 v = {lo, hi}; return __builtin_bit_cast(unsigned, __builtin_convertvector(v, bf16x2_t)); }
; __device__ __forceinline__ float bf_lo(unsigned w) { return __uint_as_float(w << 16); }
; __device__ __forceinline__ float bf_hi(unsigned w) { return __uint_as_float(w & 0xffff0000u); }
;     __device__ __forceinline__ void operator()(const f32x4 (&acc)[2][2][4][2], const Unit& u, int wr, int wc, int fr, int fq) const {
;     ...
;         const int row0 = u.pm * BM + wr * 64 + fr, col0 = u.pn * BM + wc * 32 + 8 * fq;
;         const float* gp = gate + (size_t)(u.pm >> 5) * 12288 + col0;
;         f32x4 gv[2][2];
; #pragma unroll
;         for (int bj = 0; bj < 2; ++bj)
; #pragma unroll
;             for (int n = 0; n < 2; ++n) gv[bj][n] = *(const f32x4*)(gp + bj * HALF + 4 * n);
; #pragma unroll
;         for (int ai = 0; ai < 2; ++ai)
; #pragma unroll
;             for (int m = 0; m < 4; ++m) {
;                 const size_t ro = (size_t)(row0 + ai * HALF + m * 16) * DM + col0;
; #pragma unroll
;                 for (int bj = 0; bj < 2; ++bj) {
;                     f32x4 r0, r1;
;                     if (RB) { const u32x4 rw = *(const u32x4*)((const bf16_t*)resid + ro + bj * HALF);
;                         r0 = (f32x4){bf_lo(rw.x), bf_hi(rw.x), bf_lo(rw.y), bf_hi(rw.y)}; r1 = (f32x4){bf_lo(rw.z), bf_hi(rw.z), bf_lo(rw.w), bf_hi(rw.w)}; }
;                     else { r0 = *(const f32x4*)((const float*)resid + ro + bj * HALF); r1 = *(const f32x4*)((const float*)resid + ro + bj * HALF + 4); }
;                     const f32x4 v0 = r0 + gv[bj][0] * acc[ai][bj][m][0], v1 = r1 + gv[bj][1] * acc[ai][bj][m][1];
;                     if (OB) { u32x4 w; w.x = pk2(v0[0], v0[1]); w.y = pk2(v0[2], v0[3]); w.z = pk2(v1[0], v1[1]); w.w = pk2(v1[2], v1[3]); *(u32x4*)((bf16_t*)out + ro + bj * HALF) = w; }
;                     else { *(f32x4*)((float*)out + ro + bj * HALF) = v0; *(f32x4*)((float*)out + ro + bj * HALF + 4) = v1; }
; template <class Epi>
; __device__ __forceinline__ void gemm_phase(LAS unsigned char* lds, const Gemm g, const StaticOrder& S, const Epi& E, const int tid) {
;     ...
;             PG8_BAR; PG8_WAIT_L(0); PG8_MMA(1, 0, At, B0); PG8_BAR; PG8_SCHED;
;             PG8_STAGE(PG8_SB(1, 1), b3 + hstep, voffB);
;             PG8_WAIT_V(6); PG8_BAR; PG8_MMA(1, 1, At, B1); PG8_BAR;
	s_waitcnt lgkmcnt(0)
	s_setprio 1
	v_mfma_f32_16x16x32_bf16 v[78:81], v[58:61], v[176:179], v[78:81]
	v_mfma_f32_16x16x32_bf16 v[74:77], v[66:69], v[176:179], v[74:77]
	v_mfma_f32_16x16x32_bf16 v[46:49], v[58:61], v[184:187], v[46:49]
	v_mfma_f32_16x16x32_bf16 v[42:45], v[66:69], v[184:187], v[42:45]
	v_mfma_f32_16x16x32_bf16 v[30:33], v[58:61], v[192:195], v[30:33]
	v_mfma_f32_16x16x32_bf16 v[26:29], v[66:69], v[192:195], v[26:29]
	v_mfma_f32_16x16x32_bf16 v[14:17], v[58:61], v[210:213], v[14:17]
	v_mfma_f32_16x16x32_bf16 v[10:13], v[66:69], v[210:213], v[10:13]
	v_mfma_f32_16x16x32_bf16 v[78:81], v[62:65], v[180:183], v[78:81]
	v_mfma_f32_16x16x32_bf16 v[74:77], v[70:73], v[180:183], v[74:77]
	v_mfma_f32_16x16x32_bf16 v[46:49], v[62:65], v[188:191], v[46:49]
	v_mfma_f32_16x16x32_bf16 v[42:45], v[70:73], v[188:191], v[42:45]
	v_mfma_f32_16x16x32_bf16 v[30:33], v[62:65], v[196:199], v[30:33]
	v_mfma_f32_16x16x32_bf16 v[26:29], v[70:73], v[196:199], v[26:29]
	v_mfma_f32_16x16x32_bf16 v[14:17], v[62:65], v[214:217], v[14:17]
	v_mfma_f32_16x16x32_bf16 v[10:13], v[70:73], v[214:217], v[10:13]
	s_setprio 0
	s_barrier
	s_add_u32 s20, s20, 0x200080
	s_addc_u32 s21, s21, 0
	s_add_i32 s22, s22, s31
	v_lshl_add_u64 v[58:59], s[20:21], 0, v[0:1]
	s_mov_b32 m0, s22
	s_nop 0
	global_load_lds_dwordx4 v[58:59], off
	v_lshl_add_u64 v[58:59], s[20:21], 0, v[164:165]
	s_add_i32 m0, s22, 0x2000
	s_nop 0
	global_load_lds_dwordx4 v[58:59], off
	s_waitcnt vmcnt(6)
	s_barrier
	s_setprio 1
	v_mfma_f32_16x16x32_bf16 v[50:53], v[218:221], v[176:179], v[50:53]
	v_mfma_f32_16x16x32_bf16 v[62:65], v[222:225], v[180:183], v[50:53]
	v_mfma_f32_16x16x32_bf16 v[50:53], v[226:229], v[176:179], v[54:57]
	v_mfma_f32_16x16x32_bf16 v[38:41], v[218:221], v[184:187], v[38:41]
	v_mfma_f32_16x16x32_bf16 v[34:37], v[226:229], v[184:187], v[34:37]
	v_mfma_f32_16x16x32_bf16 v[22:25], v[218:221], v[192:195], v[22:25]
	v_mfma_f32_16x16x32_bf16 v[18:21], v[226:229], v[192:195], v[18:21]
	v_mfma_f32_16x16x32_bf16 v[6:9], v[218:221], v[210:213], v[6:9]
	v_mfma_f32_16x16x32_bf16 v[2:5], v[226:229], v[210:213], v[2:5]
	v_mfma_f32_16x16x32_bf16 v[58:61], v[230:233], v[180:183], v[50:53]
	v_mfma_f32_16x16x32_bf16 v[38:41], v[222:225], v[188:191], v[38:41]
	v_mfma_f32_16x16x32_bf16 v[34:37], v[230:233], v[188:191], v[34:37]
	v_mfma_f32_16x16x32_bf16 v[22:25], v[222:225], v[196:199], v[22:25]
	v_mfma_f32_16x16x32_bf16 v[18:21], v[230:233], v[196:199], v[18:21]
	v_mfma_f32_16x16x32_bf16 v[6:9], v[222:225], v[214:217], v[6:9]
	v_mfma_f32_16x16x32_bf16 v[2:5], v[230:233], v[214:217], v[2:5]
	s_setprio 0
	s_add_i32 s49, s49, 2
	s_add_u32 s47, s47, 0x100
	s_addc_u32 s48, s48, 0
	s_add_u32 s18, s18, 0x100
	s_addc_u32 s19, s19, 0
	s_cmpk_gt_u32 s49, 0x7d
	s_barrier
	s_cbranch_scc0 .LBB0_40
	s_lshl_b32 s11, s2, 8
	s_lshl_b32 s13, s43, 8
	v_mov_b32_e32 v50, v172
	v_mov_b32_e32 v175, v159
	s_add_i32 s11, s11, s37
	s_or_b32 s13, s13, s38
	s_ashr_i32 s2, s2, 5
	s_mov_b32 s43, s10
	v_lshl_add_u32 v170, v50, 3, s13
	s_mul_hi_i32 s13, s2, 0xc000
	s_mul_i32 s2, s2, 0xc000
	v_add_u32_e32 v176, s11, v175
	s_add_u32 s18, s27, s2
	v_ashrrev_i32_e32 v177, 31, v176
	s_addc_u32 s19, s28, s13
	v_ashrrev_i32_e32 v171, 31, v170
	v_lshlrev_b64 v[176:177], 11, v[176:177]
	v_lshl_add_u64 v[54:55], v[170:171], 2, s[18:19]
	v_lshl_add_u64 v[170:171], v[176:177], 0, v[170:171]
	v_lshl_add_u64 v[180:181], v[170:171], 1, s[8:9]
	global_load_dwordx4 v[66:69], v[54:55], off offset:16
	global_load_dwordx4 v[70:73], v[54:55], off
	global_load_dwordx4 v[50:53], v[54:55], off offset:528
	s_nop 0
	global_load_dwordx4 v[54:57], v[54:55], off offset:512
	v_lshlrev_b32_e32 v175, 1, v170
	v_lshlrev_b32_e32 v200, 2, v170
	s_mov_b64 s[92:93], s[8:9]
	s_mov_b64 s[94:95], s[6:7]
	global_load_dwordx4 v[184:187], v175, s[92:93]
	global_load_dwordx4 v[188:191], v175, s[92:93] offset:256
	s_add_u32 s92, s92, 0x10000
	s_addc_u32 s93, s93, 0
	global_load_dwordx4 v[192:195], v175, s[92:93]
	global_load_dwordx4 v[196:199], v175, s[92:93] offset:256
	s_add_u32 s92, s92, 0x10000
	s_addc_u32 s93, s93, 0
	global_load_dwordx4 v[210:213], v175, s[92:93]
	global_load_dwordx4 v[214:217], v175, s[92:93] offset:256
	s_add_u32 s92, s92, 0x10000
	s_addc_u32 s93, s93, 0
	global_load_dwordx4 v[218:221], v175, s[92:93]
	global_load_dwordx4 v[222:225], v175, s[92:93] offset:256
	s_add_u32 s92, s92, 0x50000
	s_addc_u32 s93, s93, 0
	global_load_dwordx4 v[226:229], v175, s[92:93]
	global_load_dwordx4 v[230:233], v175, s[92:93] offset:256
	s_add_u32 s92, s92, 0x10000
	s_addc_u32 s93, s93, 0
	global_load_dwordx4 v[234:237], v175, s[92:93]
	s_waitcnt vmcnt(10)
	v_lshlrev_b32_e32 v176, 16, v184
	v_and_b32_e32 v177, 0xffff0000, v184
	v_lshlrev_b32_e32 v178, 16, v185
	v_and_b32_e32 v179, 0xffff0000, v185
	v_lshlrev_b32_e32 v180, 16, v186
	v_and_b32_e32 v181, 0xffff0000, v186
	v_lshlrev_b32_e32 v182, 16, v187
	v_and_b32_e32 v183, 0xffff0000, v187
	v_pk_fma_f32 v[142:143], v[142:143], v[70:71], v[176:177]
	v_pk_fma_f32 v[144:145], v[144:145], v[72:73], v[178:179]
	v_pk_fma_f32 v[138:139], v[138:139], v[66:67], v[180:181]
	v_pk_fma_f32 v[140:141], v[140:141], v[68:69], v[182:183]
	global_load_dwordx4 v[184:187], v175, s[92:93] offset:256
	global_store_dwordx4 v200, v[142:145], s[94:95]
	global_store_dwordx4 v200, v[138:141], s[94:95] offset:16
	s_waitcnt vmcnt(12)
; __device__ __forceinline__ unsigned pk2(float lo, float hi) { f32x2 v = {lo, hi}; return __builtin_bit_cast(unsigned, __builtin_convertvector(v, bf16x2_t)); }
; __device__ __forceinline__ float bf_lo(unsigned w) { return __uint_as_float(w << 16); }
; __device__ __forceinline__ float bf_hi(unsigned w) { return __uint_as_float(w & 0xffff0000u); }
;     __device__ __forceinline__ void operator()(const f32x4 (&acc)[2][2][4][2], const Unit& u, int wr, int wc, int fr, int fq) const {
;     ...
;             for (int m = 0; m < 4; ++m) {
;                 const size_t ro = (size_t)(row0 + ai * HALF + m * 16) * DM + col0;
; #pragma unroll
;                 for (int bj = 0; bj < 2; ++bj) {
;                     f32x4 r0, r1;
;                     if (RB) { const u32x4 rw = *(const u32x4*)((const bf16_t*)resid + ro + bj * HALF);
;                         r0 = (f32x4){bf_lo(rw.x), bf_hi(rw.x), bf_lo(rw.y), bf_hi(rw.y)}; r1 = (f32x4){bf_lo(rw.z), bf_hi(rw.z), bf_lo(rw.w), bf_hi(rw.w)}; }
;                     else { r0 = *(const f32x4*)((const float*)resid + ro + bj * HALF); r1 = *(const f32x4*)((const float*)resid + ro + bj * HALF + 4); }
;                     const f32x4 v0 = r0 + gv[bj][0] * acc[ai][bj][m][0], v1 = r1 + gv[bj][1] * acc[ai][bj][m][1];
;                     if (OB) { u32x4 w; w.x = pk2(v0[0], v0[1]); w.y = pk2(v0[2], v0[3]); w.z = pk2(v1[0], v1[1]); w.w = pk2(v1[2], v1[3]); *(u32x4*)((bf16_t*)out + ro + bj * HALF) = w; }
;                     else { *(f32x4*)((float*)out + ro + bj * HALF) = v0; *(f32x4*)((float*)out + ro + bj * HALF + 4) = v1; }
;                 }
	v_lshlrev_b32_e32 v176, 16, v188
	v_and_b32_e32 v177, 0xffff0000, v188
	v_lshlrev_b32_e32 v178, 16, v189
	v_and_b32_e32 v179, 0xffff0000, v189
	v_lshlrev_b32_e32 v180, 16, v190
	v_and_b32_e32 v181, 0xffff0000, v190
	v_lshlrev_b32_e32 v182, 16, v191
	v_and_b32_e32 v183, 0xffff0000, v191
	v_pk_fma_f32 v[134:135], v[134:135], v[54:55], v[176:177]
	v_pk_fma_f32 v[136:137], v[136:137], v[56:57], v[178:179]
	v_pk_fma_f32 v[130:131], v[130:131], v[50:51], v[180:181]
	v_pk_fma_f32 v[132:133], v[132:133], v[52:53], v[182:183]
	s_add_u32 s92, s92, 0x10000
	s_addc_u32 s93, s93, 0
	global_load_dwordx4 v[188:191], v175, s[92:93]
	global_store_dwordx4 v200, v[134:137], s[94:95] offset:512
	global_store_dwordx4 v200, v[130:133], s[94:95] offset:528
	s_waitcnt vmcnt(14)
	v_lshlrev_b32_e32 v176, 16, v192
	v_and_b32_e32 v177, 0xffff0000, v192
	v_lshlrev_b32_e32 v178, 16, v193
	v_and_b32_e32 v179, 0xffff0000, v193
	v_lshlrev_b32_e32 v180, 16, v194
	v_and_b32_e32 v181, 0xffff0000, v194
	v_lshlrev_b32_e32 v182, 16, v195
	v_and_b32_e32 v183, 0xffff0000, v195
	v_pk_fma_f32 v[126:127], v[126:127], v[70:71], v[176:177]
	v_pk_fma_f32 v[128:129], v[128:129], v[72:73], v[178:179]
	v_pk_fma_f32 v[122:123], v[122:123], v[66:67], v[180:181]
	v_pk_fma_f32 v[124:125], v[124:125], v[68:69], v[182:183]
	global_load_dwordx4 v[192:195], v175, s[92:93] offset:256
	s_add_u32 s94, s94, 0x20000
	s_addc_u32 s95, s95, 0
	global_store_dwordx4 v200, v[126:129], s[94:95]
	global_store_dwordx4 v200, v[122:125], s[94:95] offset:16
	s_waitcnt vmcnt(16)
	v_lshlrev_b32_e32 v176, 16, v196
	v_and_b32_e32 v177, 0xffff0000, v196
	v_lshlrev_b32_e32 v178, 16, v197
	v_and_b32_e32 v179, 0xffff0000, v197
	v_lshlrev_b32_e32 v180, 16, v198
	v_and_b32_e32 v181, 0xffff0000, v198
	v_lshlrev_b32_e32 v182, 16, v199
	v_and_b32_e32 v183, 0xffff0000, v199
	v_pk_fma_f32 v[118:119], v[118:119], v[54:55], v[176:177]
	v_pk_fma_f32 v[120:121], v[120:121], v[56:57], v[178:179]
	v_pk_fma_f32 v[114:115], v[114:115], v[50:51], v[180:181]
	v_pk_fma_f32 v[116:117], v[116:117], v[52:53], v[182:183]
	s_add_u32 s92, s92, 0x10000
	s_addc_u32 s93, s93, 0
	global_load_dwordx4 v[196:199], v175, s[92:93]
	global_store_dwordx4 v200, v[118:121], s[94:95] offset:512
	global_store_dwordx4 v200, v[114:117], s[94:95] offset:528
	s_waitcnt vmcnt(18)
	v_lshlrev_b32_e32 v176, 16, v210
	v_and_b32_e32 v177, 0xffff0000, v210
	v_lshlrev_b32_e32 v178, 16, v211
	v_and_b32_e32 v179, 0xffff0000, v211
	v_lshlrev_b32_e32 v180, 16, v212
	v_and_b32_e32 v181, 0xffff0000, v212
	v_lshlrev_b32_e32 v182, 16, v213
	v_and_b32_e32 v183, 0xffff0000, v213
	v_pk_fma_f32 v[110:111], v[110:111], v[70:71], v[176:177]
	v_pk_fma_f32 v[112:113], v[112:113], v[72:73], v[178:179]
	v_pk_fma_f32 v[106:107], v[106:107], v[66:67], v[180:181]
	v_pk_fma_f32 v[108:109], v[108:109], v[68:69], v[182:183]
	global_load_dwordx4 v[210:213], v175, s[92:93] offset:256
	s_add_u32 s94, s94, 0x20000
	s_addc_u32 s95, s95, 0
	global_store_dwordx4 v200, v[110:113], s[94:95]
	global_store_dwordx4 v200, v[106:109], s[94:95] offset:16
	s_waitcnt vmcnt(20)
	v_lshlrev_b32_e32 v176, 16, v214
	v_and_b32_e32 v177, 0xffff0000, v214
	v_lshlrev_b32_e32 v178, 16, v215
	v_and_b32_e32 v179, 0xffff0000, v215
	v_lshlrev_b32_e32 v180, 16, v216
	v_and_b32_e32 v181, 0xffff0000, v216
	v_lshlrev_b32_e32 v182, 16, v217
	v_and_b32_e32 v183, 0xffff0000, v217
	v_pk_fma_f32 v[102:103], v[102:103], v[54:55], v[176:177]
	v_pk_fma_f32 v[104:105], v[104:105], v[56:57], v[178:179]
	v_pk_fma_f32 v[98:99], v[98:99], v[50:51], v[180:181]
	v_pk_fma_f32 v[100:101], v[100:101], v[52:53], v[182:183]
	global_store_dwordx4 v200, v[102:105], s[94:95] offset:512
	global_store_dwordx4 v200, v[98:101], s[94:95] offset:528
	s_waitcnt vmcnt(21)
	v_lshlrev_b32_e32 v176, 16, v218
	v_and_b32_e32 v177, 0xffff0000, v218
	v_lshlrev_b32_e32 v178, 16, v219
	v_and_b32_e32 v179, 0xffff0000, v219
	v_lshlrev_b32_e32 v180, 16, v220
	v_and_b32_e32 v181, 0xffff0000, v220
	v_lshlrev_b32_e32 v182, 16, v221
	v_and_b32_e32 v183, 0xffff0000, v221
	v_pk_fma_f32 v[94:95], v[94:95], v[70:71], v[176:177]
	v_pk_fma_f32 v[96:97], v[96:97], v[72:73], v[178:179]
	v_pk_fma_f32 v[90:91], v[90:91], v[66:67], v[180:181]
	v_pk_fma_f32 v[92:93], v[92:93], v[68:69], v[182:183]
	s_add_u32 s94, s94, 0x20000
	s_addc_u32 s95, s95, 0
	global_store_dwordx4 v200, v[94:97], s[94:95]
	global_store_dwordx4 v200, v[90:93], s[94:95] offset:16
	s_waitcnt vmcnt(22)
	v_lshlrev_b32_e32 v176, 16, v222
	v_and_b32_e32 v177, 0xffff0000, v222
	v_lshlrev_b32_e32 v178, 16, v223
	v_and_b32_e32 v179, 0xffff0000, v223
	v_lshlrev_b32_e32 v180, 16, v224
	v_and_b32_e32 v181, 0xffff0000, v224
	v_lshlrev_b32_e32 v182, 16, v225
	v_and_b32_e32 v183, 0xffff0000, v225
	v_pk_fma_f32 v[86:87], v[86:87], v[54:55], v[176:177]
	v_pk_fma_f32 v[88:89], v[88:89], v[56:57], v[178:179]
	v_pk_fma_f32 v[82:83], v[82:83], v[50:51], v[180:181]
	v_pk_fma_f32 v[84:85], v[84:85], v[52:53], v[182:183]
	global_store_dwordx4 v200, v[86:89], s[94:95] offset:512
	global_store_dwordx4 v200, v[82:85], s[94:95] offset:528
	s_waitcnt vmcnt(23)
; __device__ __forceinline__ unsigned pk2(float lo, float hi) { f32x2 v = {lo, hi}; return __builtin_bit_cast(unsigned, __builtin_convertvector(v, bf16x2_t)); }
; __device__ __forceinline__ float bf_lo(unsigned w) { return __uint_as_float(w << 16); }
; __device__ __forceinline__ float bf_hi(unsigned w) { return __uint_as_float(w & 0xffff0000u); }
; #define PG8_WAIT_V(n) asm volatile("s_waitcnt vmcnt(" #n ")" ::: "memory")
; #define PG8_BAR __builtin_amdgcn_s_barrier()
;     __device__ __forceinline__ void operator()(const f32x4 (&acc)[2][2][4][2], const Unit& u, int wr, int wc, int fr, int fq) const {
;     ...
;             for (int m = 0; m < 4; ++m) {
;                 const size_t ro = (size_t)(row0 + ai * HALF + m * 16) * DM + col0;
; #pragma unroll
;                 for (int bj = 0; bj < 2; ++bj) {
;                     f32x4 r0, r1;
;                     if (RB) { const u32x4 rw = *(const u32x4*)((const bf16_t*)resid + ro + bj * HALF);
;                         r0 = (f32x4){bf_lo(rw.x), bf_hi(rw.x), bf_lo(rw.y), bf_hi(rw.y)}; r1 = (f32x4){bf_lo(rw.z), bf_hi(rw.z), bf_lo(rw.w), bf_hi(rw.w)}; }
;                     else { r0 = *(const f32x4*)((const float*)resid + ro + bj * HALF); r1 = *(const f32x4*)((const float*)resid + ro + bj * HALF + 4); }
;                     const f32x4 v0 = r0 + gv[bj][0] * acc[ai][bj][m][0], v1 = r1 + gv[bj][1] * acc[ai][bj][m][1];
;                     if (OB) { u32x4 w; w.x = pk2(v0[0], v0[1]); w.y = pk2(v0[2], v0[3]); w.z = pk2(v1[0], v1[1]); w.w = pk2(v1[2], v1[3]); *(u32x4*)((bf16_t*)out + ro + bj * HALF) = w; }
;                     else { *(f32x4*)((float*)out + ro + bj * HALF) = v0; *(f32x4*)((float*)out + ro + bj * HALF + 4) = v1; }
;                 }
; template <class Epi>
; __device__ __forceinline__ void gemm_phase(LAS unsigned char* lds, const Gemm g, const StaticOrder& S, const Epi& E, const int tid) {
;     ...
;         if (!has_next) break;
; #pragma unroll
;         for (int a = 0; a < 2; ++a)
; #pragma unroll
;             for (int b = 0; b < 2; ++b)
; #pragma unroll
;                 for (int m = 0; m < 4; ++m)
; #pragma unroll
;                     for (int n = 0; n < 2; ++n) acc[a][b][m][n] = (f32x4){0.f, 0.f, 0.f, 0.f};
;         cur = nxt; cA = nA; cB = nB; ++ui;
;     }
;     PG8_WAIT_V(0);
;     if (wr == 0) PG8_BAR;
;     PG8_BAR;
	v_lshlrev_b32_e32 v176, 16, v226
	v_and_b32_e32 v177, 0xffff0000, v226
	v_lshlrev_b32_e32 v178, 16, v227
	v_and_b32_e32 v179, 0xffff0000, v227
	v_lshlrev_b32_e32 v180, 16, v228
	v_and_b32_e32 v181, 0xffff0000, v228
	v_lshlrev_b32_e32 v182, 16, v229
	v_and_b32_e32 v183, 0xffff0000, v229
	v_pk_fma_f32 v[78:79], v[78:79], v[70:71], v[176:177]
	v_pk_fma_f32 v[80:81], v[80:81], v[72:73], v[178:179]
	v_pk_fma_f32 v[74:75], v[74:75], v[66:67], v[180:181]
	v_pk_fma_f32 v[76:77], v[76:77], v[68:69], v[182:183]
	s_add_u32 s94, s94, 0xa0000
	s_addc_u32 s95, s95, 0
	global_store_dwordx4 v200, v[78:81], s[94:95]
	global_store_dwordx4 v200, v[74:77], s[94:95] offset:16
	s_waitcnt vmcnt(24)
	v_lshlrev_b32_e32 v176, 16, v230
	v_and_b32_e32 v177, 0xffff0000, v230
	v_lshlrev_b32_e32 v178, 16, v231
	v_and_b32_e32 v179, 0xffff0000, v231
	v_lshlrev_b32_e32 v180, 16, v232
	v_and_b32_e32 v181, 0xffff0000, v232
	v_lshlrev_b32_e32 v182, 16, v233
	v_and_b32_e32 v183, 0xffff0000, v233
	v_pk_fma_f32 v[62:63], v[62:63], v[54:55], v[176:177]
	v_pk_fma_f32 v[64:65], v[64:65], v[56:57], v[178:179]
	v_pk_fma_f32 v[58:59], v[58:59], v[50:51], v[180:181]
	v_pk_fma_f32 v[60:61], v[60:61], v[52:53], v[182:183]
	global_store_dwordx4 v200, v[62:65], s[94:95] offset:512
	global_store_dwordx4 v200, v[58:61], s[94:95] offset:528
	s_waitcnt vmcnt(25)
	v_lshlrev_b32_e32 v176, 16, v234
	v_and_b32_e32 v177, 0xffff0000, v234
	v_lshlrev_b32_e32 v178, 16, v235
	v_and_b32_e32 v179, 0xffff0000, v235
	v_lshlrev_b32_e32 v180, 16, v236
	v_and_b32_e32 v181, 0xffff0000, v236
	v_lshlrev_b32_e32 v182, 16, v237
	v_and_b32_e32 v183, 0xffff0000, v237
	v_pk_fma_f32 v[46:47], v[46:47], v[70:71], v[176:177]
	v_pk_fma_f32 v[48:49], v[48:49], v[72:73], v[178:179]
	v_pk_fma_f32 v[42:43], v[42:43], v[66:67], v[180:181]
	v_pk_fma_f32 v[44:45], v[44:45], v[68:69], v[182:183]
	s_add_u32 s94, s94, 0x20000
	s_addc_u32 s95, s95, 0
	global_store_dwordx4 v200, v[46:49], s[94:95]
	global_store_dwordx4 v200, v[42:45], s[94:95] offset:16
	s_waitcnt vmcnt(26)
	v_lshlrev_b32_e32 v176, 16, v184
	v_and_b32_e32 v177, 0xffff0000, v184
	v_lshlrev_b32_e32 v178, 16, v185
	v_and_b32_e32 v179, 0xffff0000, v185
	v_lshlrev_b32_e32 v180, 16, v186
	v_and_b32_e32 v181, 0xffff0000, v186
	v_lshlrev_b32_e32 v182, 16, v187
	v_and_b32_e32 v183, 0xffff0000, v187
	v_pk_fma_f32 v[38:39], v[38:39], v[54:55], v[176:177]
	v_pk_fma_f32 v[40:41], v[40:41], v[56:57], v[178:179]
	v_pk_fma_f32 v[34:35], v[34:35], v[50:51], v[180:181]
	v_pk_fma_f32 v[36:37], v[36:37], v[52:53], v[182:183]
	global_store_dwordx4 v200, v[38:41], s[94:95] offset:512
	global_store_dwordx4 v200, v[34:37], s[94:95] offset:528
	s_waitcnt vmcnt(25)
	v_lshlrev_b32_e32 v176, 16, v188
	v_and_b32_e32 v177, 0xffff0000, v188
	v_lshlrev_b32_e32 v178, 16, v189
	v_and_b32_e32 v179, 0xffff0000, v189
	v_lshlrev_b32_e32 v180, 16, v190
	v_and_b32_e32 v181, 0xffff0000, v190
	v_lshlrev_b32_e32 v182, 16, v191
	v_and_b32_e32 v183, 0xffff0000, v191
	v_pk_fma_f32 v[30:31], v[30:31], v[70:71], v[176:177]
	v_pk_fma_f32 v[32:33], v[32:33], v[72:73], v[178:179]
	v_pk_fma_f32 v[26:27], v[26:27], v[66:67], v[180:181]
	v_pk_fma_f32 v[28:29], v[28:29], v[68:69], v[182:183]
	s_add_u32 s94, s94, 0x20000
	s_addc_u32 s95, s95, 0
	global_store_dwordx4 v200, v[30:33], s[94:95]
	global_store_dwordx4 v200, v[26:29], s[94:95] offset:16
	s_waitcnt vmcnt(24)
	v_lshlrev_b32_e32 v176, 16, v192
	v_and_b32_e32 v177, 0xffff0000, v192
	v_lshlrev_b32_e32 v178, 16, v193
	v_and_b32_e32 v179, 0xffff0000, v193
	v_lshlrev_b32_e32 v180, 16, v194
	v_and_b32_e32 v181, 0xffff0000, v194
	v_lshlrev_b32_e32 v182, 16, v195
	v_and_b32_e32 v183, 0xffff0000, v195
	v_pk_fma_f32 v[22:23], v[22:23], v[54:55], v[176:177]
	v_pk_fma_f32 v[24:25], v[24:25], v[56:57], v[178:179]
	v_pk_fma_f32 v[18:19], v[18:19], v[50:51], v[180:181]
	v_pk_fma_f32 v[20:21], v[20:21], v[52:53], v[182:183]
	global_store_dwordx4 v200, v[22:25], s[94:95] offset:512
	global_store_dwordx4 v200, v[18:21], s[94:95] offset:528
	s_waitcnt vmcnt(23)
	v_lshlrev_b32_e32 v176, 16, v196
	v_and_b32_e32 v177, 0xffff0000, v196
	v_lshlrev_b32_e32 v178, 16, v197
	v_and_b32_e32 v179, 0xffff0000, v197
	v_lshlrev_b32_e32 v180, 16, v198
	v_and_b32_e32 v181, 0xffff0000, v198
	v_lshlrev_b32_e32 v182, 16, v199
	v_and_b32_e32 v183, 0xffff0000, v199
	v_pk_fma_f32 v[14:15], v[14:15], v[70:71], v[176:177]
	v_pk_fma_f32 v[16:17], v[16:17], v[72:73], v[178:179]
	v_pk_fma_f32 v[10:11], v[10:11], v[66:67], v[180:181]
	v_pk_fma_f32 v[12:13], v[12:13], v[68:69], v[182:183]
	s_add_u32 s94, s94, 0x20000
	s_addc_u32 s95, s95, 0
	global_store_dwordx4 v200, v[14:17], s[94:95]
	global_store_dwordx4 v200, v[10:13], s[94:95] offset:16
	s_waitcnt vmcnt(22)
	v_lshlrev_b32_e32 v176, 16, v210
	v_and_b32_e32 v177, 0xffff0000, v210
	v_lshlrev_b32_e32 v178, 16, v211
	v_and_b32_e32 v179, 0xffff0000, v211
	v_lshlrev_b32_e32 v180, 16, v212
	v_and_b32_e32 v181, 0xffff0000, v212
	v_lshlrev_b32_e32 v182, 16, v213
	v_and_b32_e32 v183, 0xffff0000, v213
	v_pk_fma_f32 v[6:7], v[6:7], v[54:55], v[176:177]
	v_pk_fma_f32 v[8:9], v[8:9], v[56:57], v[178:179]
	v_pk_fma_f32 v[2:3], v[2:3], v[50:51], v[180:181]
	v_pk_fma_f32 v[4:5], v[4:5], v[52:53], v[182:183]
	global_store_dwordx4 v200, v[6:9], s[94:95] offset:512
	global_store_dwordx4 v200, v[2:5], s[94:95] offset:528
	s_mov_b32 s2, s12
	s_mov_b64 s[20:21], s[14:15]
	s_mov_b64 s[18:19], s[16:17]
	s_and_b64 vcc, exec, s[4:5]
	s_nop 1
	s_cbranch_vccz .LBB0_33
	s_waitcnt vmcnt(0)
	s_cmpk_gt_u32 s29, 0xff
	s_cbranch_scc1 .LBB0_44
	s_barrier

; #define PG8_STAGE(bufoff, gbase, voff) do { _Pragma("unroll") for (int _i = 0; _i < 2; ++_i) \
;         __builtin_amdgcn_global_load_lds((const unsigned*)((const char*)(gbase) + (voff)[_i]), (LAS unsigned*)(lds + (bufoff) + ldsw + _i * 8192), 16, 0, 0); } while (0)
; #define PG8_LDA(dst, b, h) do { _Pragma("unroll") for (int m = 0; m < 4; ++m) _Pragma("unroll") for (int k = 0; k < 2; ++k) dst[m][k] = *(const LAS bf16x8*)(lds + PG8_SA(b, h) + aoff + m * 2048 + k * 1024); } while (0)
; #define PG8_LDB(dst, b, h) do { _Pragma("unroll") for (int n = 0; n < 2; ++n) _Pragma("unroll") for (int k = 0; k < 2; ++k) dst[n][k] = *(const LAS bf16x8*)(lds + PG8_SB(b, h) + boff + n * 2048 + k * 1024); } while (0)
; #define PG8_MMA(ai, bj, At, Bt) do { __builtin_amdgcn_s_setprio(1); _Pragma("unroll") for (int m = 0; m < 4; ++m) _Pragma("unroll") for (int n = 0; n < 2; ++n) _Pragma("unroll") for (int k = 0; k < 2; ++k) \
;         acc[ai][bj][m][n] = __builtin_amdgcn_mfma_f32_16x16x32_bf16(Bt[n][k], At[m][k], acc[ai][bj][m][n], 0, 0, 0); __builtin_amdgcn_s_setprio(0); } while (0)
; #define PG8_WAIT_L(n) asm volatile("s_waitcnt lgkmcnt(" #n ")" ::: "memory")
; #define PG8_BAR __builtin_amdgcn_s_barrier()
; #define PG8_SCHED __builtin_amdgcn_sched_barrier(0)
; template <class Epi>
; __device__ __forceinline__ void gemm_phase(LAS unsigned char* lds, const Gemm g, const StaticOrder& S, const Epi& E, const int tid) {
;     ...
;             PG8_LDB(B0, 0, 0); PG8_SCHED; PG8_LDA(At, 0, 0); PG8_STAGE(PG8_SA(1, 1), a1 + hstep, voffA);
;             PG8_WAIT_L(8); PG8_BAR; PG8_WAIT_L(0); PG8_MMA(0, 0, At, B0); PG8_BAR; PG8_SCHED;
;             PG8_LDB(B1, 0, 1); PG8_STAGE(PG8_SB(0, 0), b2, voffB);
;             PG8_BAR; PG8_WAIT_L(0); PG8_MMA(0, 1, At, B1); PG8_BAR;
;             PG8_LDA(At, 0, 1); PG8_STAGE(PG8_SA(0, 0), a2, voffA);
;             PG8_BAR; PG8_WAIT_L(0); PG8_MMA(1, 0, At, B0); PG8_BAR; PG8_SCHED;
.LBB0_62:
	s_add_u32 s20, s18, 0xffe00080
	s_addc_u32 s21, s19, -1
	s_add_i32 s50, 0, 0x10000
	v_add_u32_e32 v62, s50, v173
	ds_read_b128 v[42:45], v62
	ds_read_b128 v[46:49], v62 offset:1024
	ds_read_b128 v[58:61], v62 offset:2048
	ds_read_b128 v[62:65], v62 offset:3072
	s_cmpk_eq_i32 s49, 0x7c
	s_cselect_b32 s23, s13, s21
	s_cselect_b32 s22, s44, s20
	s_cselect_b32 s21, s11, s48
	s_cselect_b32 s20, s45, s47
	v_lshl_add_u64 v[170:171], s[18:19], 0, v[168:169]
	s_add_i32 m0, s3, 0xc000
	ds_read_b128 v[176:179], v174
	ds_read_b128 v[180:183], v174 offset:1024
	ds_read_b128 v[184:187], v174 offset:2048
	ds_read_b128 v[188:191], v174 offset:3072
	ds_read_b128 v[192:195], v174 offset:4096
	ds_read_b128 v[196:199], v174 offset:5120
	ds_read_b128 v[210:213], v174 offset:6144
	ds_read_b128 v[214:217], v174 offset:7168
	global_load_lds_dwordx4 v[170:171], off
	v_lshl_add_u64 v[170:171], s[18:19], 0, v[166:167]
	s_add_i32 m0, s3, 0xe000
	s_nop 0
	global_load_lds_dwordx4 v[170:171], off
	s_waitcnt lgkmcnt(8)
	s_barrier
	s_waitcnt lgkmcnt(0)
	s_setprio 1
	v_mfma_f32_16x16x32_bf16 v[142:145], v[42:45], v[176:179], v[142:145]
	v_mfma_f32_16x16x32_bf16 v[138:141], v[58:61], v[176:179], v[138:141]
	v_mfma_f32_16x16x32_bf16 v[126:129], v[42:45], v[184:187], v[126:129]
	v_mfma_f32_16x16x32_bf16 v[122:125], v[58:61], v[184:187], v[122:125]
	v_mfma_f32_16x16x32_bf16 v[110:113], v[42:45], v[192:195], v[110:113]
	v_mfma_f32_16x16x32_bf16 v[106:109], v[58:61], v[192:195], v[106:109]
	v_mfma_f32_16x16x32_bf16 v[94:97], v[42:45], v[210:213], v[94:97]
	v_mfma_f32_16x16x32_bf16 v[90:93], v[58:61], v[210:213], v[90:93]
	v_mfma_f32_16x16x32_bf16 v[142:145], v[46:49], v[180:183], v[142:145]
	v_mfma_f32_16x16x32_bf16 v[138:141], v[62:65], v[180:183], v[138:141]
	v_mfma_f32_16x16x32_bf16 v[126:129], v[46:49], v[188:191], v[126:129]
	v_mfma_f32_16x16x32_bf16 v[122:125], v[62:65], v[188:191], v[122:125]
	v_mfma_f32_16x16x32_bf16 v[110:113], v[46:49], v[196:199], v[110:113]
	v_mfma_f32_16x16x32_bf16 v[106:109], v[62:65], v[196:199], v[106:109]
	v_mfma_f32_16x16x32_bf16 v[94:97], v[46:49], v[214:217], v[94:97]
	v_mfma_f32_16x16x32_bf16 v[90:93], v[62:65], v[214:217], v[90:93]
	s_setprio 0
	s_barrier
	s_add_i32 s54, 0, 0x14000
	v_add_u32_e32 v170, s54, v173
	s_add_i32 s50, s50, s31
	ds_read_b128 v[218:221], v170
	ds_read_b128 v[222:225], v170 offset:1024
	ds_read_b128 v[226:229], v170 offset:2048
	ds_read_b128 v[230:233], v170 offset:3072
	v_lshl_add_u64 v[170:171], s[20:21], 0, v[0:1]
	s_mov_b32 m0, s50
	v_lshl_add_u64 v[200:201], s[20:21], 0, v[164:165]
	global_load_lds_dwordx4 v[170:171], off
	s_add_i32 m0, s50, 0x2000
	s_nop 0
	global_load_lds_dwordx4 v[200:201], off
	s_barrier
	s_waitcnt lgkmcnt(0)
	s_setprio 1
	v_mfma_f32_16x16x32_bf16 v[134:137], v[218:221], v[176:179], v[134:137]
	v_mfma_f32_16x16x32_bf16 v[130:133], v[226:229], v[176:179], v[130:133]
	v_mfma_f32_16x16x32_bf16 v[118:121], v[218:221], v[184:187], v[118:121]
	v_mfma_f32_16x16x32_bf16 v[114:117], v[226:229], v[184:187], v[114:117]
	v_mfma_f32_16x16x32_bf16 v[102:105], v[218:221], v[192:195], v[102:105]
	v_mfma_f32_16x16x32_bf16 v[98:101], v[226:229], v[192:195], v[98:101]
	v_mfma_f32_16x16x32_bf16 v[86:89], v[218:221], v[210:213], v[86:89]
	v_mfma_f32_16x16x32_bf16 v[82:85], v[226:229], v[210:213], v[82:85]
	v_mfma_f32_16x16x32_bf16 v[134:137], v[222:225], v[180:183], v[134:137]
	v_mfma_f32_16x16x32_bf16 v[130:133], v[230:233], v[180:183], v[130:133]
	v_mfma_f32_16x16x32_bf16 v[118:121], v[222:225], v[188:191], v[118:121]
	v_mfma_f32_16x16x32_bf16 v[114:117], v[230:233], v[188:191], v[114:117]
	v_mfma_f32_16x16x32_bf16 v[102:105], v[222:225], v[196:199], v[102:105]
	v_mfma_f32_16x16x32_bf16 v[98:101], v[230:233], v[196:199], v[98:101]
	v_mfma_f32_16x16x32_bf16 v[86:89], v[222:225], v[214:217], v[86:89]
	v_mfma_f32_16x16x32_bf16 v[82:85], v[230:233], v[214:217], v[82:85]
	s_setprio 0
	s_mov_b32 m0, s3
	v_lshl_add_u64 v[234:235], s[22:23], 0, v[160:161]
	s_barrier
	ds_read_b128 v[176:179], v174 offset:16384
	ds_read_b128 v[180:183], v174 offset:17408
	ds_read_b128 v[184:187], v174 offset:18432
	ds_read_b128 v[188:191], v174 offset:19456
	ds_read_b128 v[192:195], v174 offset:20480
	ds_read_b128 v[196:199], v174 offset:21504
	ds_read_b128 v[210:213], v174 offset:22528
	ds_read_b128 v[214:217], v174 offset:23552
	global_load_lds_dwordx4 v[234:235], off
	v_lshl_add_u64 v[236:237], s[22:23], 0, v[162:163]
	s_mov_b32 m0, s34
	s_nop 0
	global_load_lds_dwordx4 v[236:237], off
	s_barrier
	s_waitcnt lgkmcnt(0)
	s_setprio 1
	v_mfma_f32_16x16x32_bf16 v[78:81], v[42:45], v[176:179], v[78:81]
	v_mfma_f32_16x16x32_bf16 v[74:77], v[58:61], v[176:179], v[74:77]
	v_mfma_f32_16x16x32_bf16 v[54:57], v[42:45], v[184:187], v[54:57]
	v_mfma_f32_16x16x32_bf16 v[50:53], v[58:61], v[184:187], v[50:53]
	v_mfma_f32_16x16x32_bf16 v[30:33], v[42:45], v[192:195], v[30:33]
	v_mfma_f32_16x16x32_bf16 v[26:29], v[58:61], v[192:195], v[26:29]
	v_mfma_f32_16x16x32_bf16 v[14:17], v[42:45], v[210:213], v[14:17]
	v_mfma_f32_16x16x32_bf16 v[10:13], v[58:61], v[210:213], v[10:13]
	v_mfma_f32_16x16x32_bf16 v[78:81], v[46:49], v[180:183], v[78:81]
	v_mfma_f32_16x16x32_bf16 v[74:77], v[62:65], v[180:183], v[74:77]
	v_mfma_f32_16x16x32_bf16 v[54:57], v[46:49], v[188:191], v[54:57]
	v_mfma_f32_16x16x32_bf16 v[50:53], v[62:65], v[188:191], v[50:53]
	v_mfma_f32_16x16x32_bf16 v[30:33], v[46:49], v[196:199], v[30:33]
	v_mfma_f32_16x16x32_bf16 v[26:29], v[62:65], v[196:199], v[26:29]
	v_mfma_f32_16x16x32_bf16 v[14:17], v[46:49], v[214:217], v[14:17]
	v_mfma_f32_16x16x32_bf16 v[10:13], v[62:65], v[214:217], v[10:13]
	s_setprio 0
	s_barrier
; #define PG8_STAGE(bufoff, gbase, voff) do { _Pragma("unroll") for (int _i = 0; _i < 2; ++_i) \
;         __builtin_amdgcn_global_load_lds((const unsigned*)((const char*)(gbase) + (voff)[_i]), (LAS unsigned*)(lds + (bufoff) + ldsw + _i * 8192), 16, 0, 0); } while (0)
; #define PG8_LDA(dst, b, h) do { _Pragma("unroll") for (int m = 0; m < 4; ++m) _Pragma("unroll") for (int k = 0; k < 2; ++k) dst[m][k] = *(const LAS bf16x8*)(lds + PG8_SA(b, h) + aoff + m * 2048 + k * 1024); } while (0)
; #define PG8_LDB(dst, b, h) do { _Pragma("unroll") for (int n = 0; n < 2; ++n) _Pragma("unroll") for (int k = 0; k < 2; ++k) dst[n][k] = *(const LAS bf16x8*)(lds + PG8_SB(b, h) + boff + n * 2048 + k * 1024); } while (0)
; #define PG8_MMA(ai, bj, At, Bt) do { __builtin_amdgcn_s_setprio(1); _Pragma("unroll") for (int m = 0; m < 4; ++m) _Pragma("unroll") for (int n = 0; n < 2; ++n) _Pragma("unroll") for (int k = 0; k < 2; ++k) \
;         acc[ai][bj][m][n] = __builtin_amdgcn_mfma_f32_16x16x32_bf16(Bt[n][k], At[m][k], acc[ai][bj][m][n], 0, 0, 0); __builtin_amdgcn_s_setprio(0); } while (0)
; #define PG8_WAIT_V(n) asm volatile("s_waitcnt vmcnt(" #n ")" ::: "memory")
; #define PG8_WAIT_L(n) asm volatile("s_waitcnt lgkmcnt(" #n ")" ::: "memory")
; #define PG8_BAR __builtin_amdgcn_s_barrier()
; #define PG8_SCHED __builtin_amdgcn_sched_barrier(0)
; template <class Epi>
; __device__ __forceinline__ void gemm_phase(LAS unsigned char* lds, const Gemm g, const StaticOrder& S, const Epi& E, const int tid) {
;     ...
;             PG8_STAGE(PG8_SB(0, 1), b2 + hstep, voffB);
;             PG8_WAIT_V(6); PG8_BAR; PG8_MMA(1, 1, At, B1); PG8_BAR;
;             PG8_LDB(B0, 1, 0); PG8_SCHED; PG8_LDA(At, 1, 0); PG8_STAGE(PG8_SA(0, 1), a2 + hstep, voffA);
;             PG8_WAIT_L(8); PG8_BAR; PG8_WAIT_L(0); PG8_MMA(0, 0, At, B0); PG8_BAR; PG8_SCHED;
;             PG8_LDB(B1, 1, 1); PG8_STAGE(PG8_SB(1, 0), b3, voffB);
;             PG8_BAR; PG8_WAIT_L(0); PG8_MMA(0, 1, At, B1); PG8_BAR;
	s_add_u32 s52, s20, 0x200000
	s_addc_u32 s53, s21, 0
	s_add_i32 s50, s54, s31
	v_lshl_add_u64 v[42:43], s[52:53], 0, v[0:1]
	s_mov_b32 m0, s50
	s_nop 0
	global_load_lds_dwordx4 v[42:43], off
	v_lshl_add_u64 v[42:43], s[52:53], 0, v[164:165]
	s_add_i32 m0, s50, 0x2000
	s_nop 0
	global_load_lds_dwordx4 v[42:43], off
	s_waitcnt vmcnt(6)
	s_barrier
	s_setprio 1
	v_mfma_f32_16x16x32_bf16 v[38:41], v[218:221], v[184:187], v[38:41]
	v_mfma_f32_16x16x32_bf16 v[34:37], v[226:229], v[184:187], v[34:37]
	v_mfma_f32_16x16x32_bf16 v[22:25], v[218:221], v[192:195], v[22:25]
	v_mfma_f32_16x16x32_bf16 v[18:21], v[226:229], v[192:195], v[18:21]
	v_mfma_f32_16x16x32_bf16 v[6:9], v[218:221], v[210:213], v[6:9]
	v_mfma_f32_16x16x32_bf16 v[2:5], v[226:229], v[210:213], v[2:5]
	v_mfma_f32_16x16x32_bf16 v[42:45], v[218:221], v[176:179], v[70:73]
	v_mfma_f32_16x16x32_bf16 v[46:49], v[226:229], v[176:179], v[66:69]
	v_mfma_f32_16x16x32_bf16 v[38:41], v[222:225], v[188:191], v[38:41]
	v_mfma_f32_16x16x32_bf16 v[34:37], v[230:233], v[188:191], v[34:37]
	v_mfma_f32_16x16x32_bf16 v[22:25], v[222:225], v[196:199], v[22:25]
	v_mfma_f32_16x16x32_bf16 v[18:21], v[230:233], v[196:199], v[18:21]
	v_mfma_f32_16x16x32_bf16 v[6:9], v[222:225], v[214:217], v[6:9]
	v_mfma_f32_16x16x32_bf16 v[2:5], v[230:233], v[214:217], v[2:5]
	v_mfma_f32_16x16x32_bf16 v[42:45], v[222:225], v[180:183], v[42:45]
	v_mfma_f32_16x16x32_bf16 v[46:49], v[230:233], v[180:183], v[46:49]
	s_setprio 0
	s_add_i32 s50, 0, 0x18000
	v_add_u32_e32 v70, s50, v173
	s_barrier
	ds_read_b128 v[58:61], v70
	ds_read_b128 v[62:65], v70 offset:1024
	ds_read_b128 v[66:69], v70 offset:2048
	ds_read_b128 v[70:73], v70 offset:3072
	s_add_u32 s22, s22, 0x200000
	s_addc_u32 s23, s23, 0
	s_mov_b32 m0, s35
	v_lshl_add_u64 v[218:219], s[22:23], 0, v[160:161]
	ds_read_b128 v[176:179], v174 offset:32768
	ds_read_b128 v[180:183], v174 offset:33792
	ds_read_b128 v[184:187], v174 offset:34816
	ds_read_b128 v[188:191], v174 offset:35840
	ds_read_b128 v[192:195], v174 offset:36864
	ds_read_b128 v[196:199], v174 offset:37888
	ds_read_b128 v[210:213], v174 offset:38912
	ds_read_b128 v[214:217], v174 offset:39936
	global_load_lds_dwordx4 v[218:219], off
	v_lshl_add_u64 v[218:219], s[22:23], 0, v[162:163]
	s_mov_b32 m0, s36
	s_nop 0
	global_load_lds_dwordx4 v[218:219], off
	s_waitcnt lgkmcnt(8)
	s_barrier
	s_waitcnt lgkmcnt(0)
	s_setprio 1
	v_mfma_f32_16x16x32_bf16 v[142:145], v[58:61], v[176:179], v[142:145]
	v_mfma_f32_16x16x32_bf16 v[138:141], v[66:69], v[176:179], v[138:141]
	v_mfma_f32_16x16x32_bf16 v[126:129], v[58:61], v[184:187], v[126:129]
	v_mfma_f32_16x16x32_bf16 v[122:125], v[66:69], v[184:187], v[122:125]
	v_mfma_f32_16x16x32_bf16 v[110:113], v[58:61], v[192:195], v[110:113]
	v_mfma_f32_16x16x32_bf16 v[106:109], v[66:69], v[192:195], v[106:109]
	v_mfma_f32_16x16x32_bf16 v[94:97], v[58:61], v[210:213], v[94:97]
	v_mfma_f32_16x16x32_bf16 v[90:93], v[66:69], v[210:213], v[90:93]
	v_mfma_f32_16x16x32_bf16 v[142:145], v[62:65], v[180:183], v[142:145]
	v_mfma_f32_16x16x32_bf16 v[138:141], v[70:73], v[180:183], v[138:141]
	v_mfma_f32_16x16x32_bf16 v[126:129], v[62:65], v[188:191], v[126:129]
	v_mfma_f32_16x16x32_bf16 v[122:125], v[70:73], v[188:191], v[122:125]
	v_mfma_f32_16x16x32_bf16 v[110:113], v[62:65], v[196:199], v[110:113]
	v_mfma_f32_16x16x32_bf16 v[106:109], v[70:73], v[196:199], v[106:109]
	v_mfma_f32_16x16x32_bf16 v[94:97], v[62:65], v[214:217], v[94:97]
	v_mfma_f32_16x16x32_bf16 v[90:93], v[70:73], v[214:217], v[90:93]
	s_setprio 0
	s_barrier
	s_add_i32 s22, 0, 0x1c000
	s_add_i32 s23, s50, s31
	v_add_u32_e32 v175, s22, v173
	v_lshl_add_u64 v[170:171], v[170:171], 0, s[56:57]
	s_mov_b32 m0, s23
	ds_read_b128 v[218:221], v175
	ds_read_b128 v[222:225], v175 offset:1024
	ds_read_b128 v[226:229], v175 offset:2048
	ds_read_b128 v[230:233], v175 offset:3072
	global_load_lds_dwordx4 v[170:171], off
	v_lshl_add_u64 v[170:171], v[200:201], 0, s[56:57]
	s_add_i32 m0, s23, 0x2000
	s_nop 0
	global_load_lds_dwordx4 v[170:171], off
	s_barrier
	s_waitcnt lgkmcnt(0)
	s_setprio 1
	v_mfma_f32_16x16x32_bf16 v[134:137], v[218:221], v[176:179], v[134:137]
	v_mfma_f32_16x16x32_bf16 v[130:133], v[226:229], v[176:179], v[130:133]
	v_mfma_f32_16x16x32_bf16 v[118:121], v[218:221], v[184:187], v[118:121]
	v_mfma_f32_16x16x32_bf16 v[114:117], v[226:229], v[184:187], v[114:117]
	v_mfma_f32_16x16x32_bf16 v[102:105], v[218:221], v[192:195], v[102:105]
	v_mfma_f32_16x16x32_bf16 v[98:101], v[226:229], v[192:195], v[98:101]
	v_mfma_f32_16x16x32_bf16 v[86:89], v[218:221], v[210:213], v[86:89]
	v_mfma_f32_16x16x32_bf16 v[82:85], v[226:229], v[210:213], v[82:85]
	v_mfma_f32_16x16x32_bf16 v[134:137], v[222:225], v[180:183], v[134:137]
	v_mfma_f32_16x16x32_bf16 v[130:133], v[230:233], v[180:183], v[130:133]
	v_mfma_f32_16x16x32_bf16 v[118:121], v[222:225], v[188:191], v[118:121]
	v_mfma_f32_16x16x32_bf16 v[114:117], v[230:233], v[188:191], v[114:117]
	v_mfma_f32_16x16x32_bf16 v[102:105], v[222:225], v[196:199], v[102:105]
	v_mfma_f32_16x16x32_bf16 v[98:101], v[230:233], v[196:199], v[98:101]
	v_mfma_f32_16x16x32_bf16 v[86:89], v[222:225], v[214:217], v[86:89]
	v_mfma_f32_16x16x32_bf16 v[82:85], v[230:233], v[214:217], v[82:85]
	s_setprio 0
	s_mov_b32 m0, s39
	v_lshl_add_u64 v[170:171], v[234:235], 0, s[56:57]
	s_barrier
	ds_read_b128 v[176:179], v174 offset:49152
	ds_read_b128 v[180:183], v174 offset:50176
	ds_read_b128 v[184:187], v174 offset:51200
	ds_read_b128 v[188:191], v174 offset:52224
	ds_read_b128 v[192:195], v174 offset:53248
	ds_read_b128 v[196:199], v174 offset:54272
	ds_read_b128 v[210:213], v174 offset:55296
	ds_read_b128 v[214:217], v174 offset:56320
	global_load_lds_dwordx4 v[170:171], off
	v_lshl_add_u64 v[170:171], v[236:237], 0, s[56:57]
	s_mov_b32 m0, s40
	s_nop 0
	global_load_lds_dwordx4 v[170:171], off
	s_barrier
; __device__ __forceinline__ unsigned pk2(float lo, float hi) { f32x2 v = {lo, hi}; return __builtin_bit_cast(unsigned, __builtin_convertvector(v, bf16x2_t)); }
; __device__ __forceinline__ float bf_lo(unsigned w) { return __uint_as_float(w << 16); }
; __device__ __forceinline__ float bf_hi(unsigned w) { return __uint_as_float(w & 0xffff0000u); }
;     __device__ __forceinline__ void operator()(const f32x4 (&acc)[2][2][4][2], const Unit& u, int wr, int wc, int fr, int fq) const {
;         asm volatile("" : "+v"(fr), "+v"(fq));
;         const int row0 = u.pm * BM + wr * 64 + fr, col0 = u.pn * BM + wc * 32 + 8 * fq;
;         const float* gp = gate + (size_t)(u.pm >> 5) * 12288 + col0;
;         f32x4 gv[2][2];
; #pragma unroll
;         for (int bj = 0; bj < 2; ++bj)
; #pragma unroll
;             for (int n = 0; n < 2; ++n) gv[bj][n] = *(const f32x4*)(gp + bj * HALF + 4 * n);
; #pragma unroll
;         for (int ai = 0; ai < 2; ++ai)
; #pragma unroll
;             for (int m = 0; m < 4; ++m) {
;                 const size_t ro = (size_t)(row0 + ai * HALF + m * 16) * DM + col0;
; #pragma unroll
;                 for (int bj = 0; bj < 2; ++bj) {
;                     f32x4 r0, r1;
;                     if (RB) { const u32x4 rw = *(const u32x4*)((const bf16_t*)resid + ro + bj * HALF);
;                         r0 = (f32x4){bf_lo(rw.x), bf_hi(rw.x), bf_lo(rw.y), bf_hi(rw.y)}; r1 = (f32x4){bf_lo(rw.z), bf_hi(rw.z), bf_lo(rw.w), bf_hi(rw.w)}; }
;                     else { r0 = *(const f32x4*)((const float*)resid + ro + bj * HALF); r1 = *(const f32x4*)((const float*)resid + ro + bj * HALF + 4); }
;                     const f32x4 v0 = r0 + gv[bj][0] * acc[ai][bj][m][0], v1 = r1 + gv[bj][1] * acc[ai][bj][m][1];
;                     if (OB) { u32x4 w; w.x = pk2(v0[0], v0[1]); w.y = pk2(v0[2], v0[3]); w.z = pk2(v1[0], v1[1]); w.w = pk2(v1[2], v1[3]); *(u32x4*)((bf16_t*)out + ro + bj * HALF) = w; }
; template <class Epi>
; __device__ __forceinline__ void gemm_phase(LAS unsigned char* lds, const Gemm g, const StaticOrder& S, const Epi& E, const int tid) {
;     ...
;             PG8_LDA(At, 1, 1); PG8_STAGE(PG8_SA(1, 0), a3, voffA);
;             PG8_BAR; PG8_WAIT_L(0); PG8_MMA(1, 0, At, B0); PG8_BAR; PG8_SCHED;
;             PG8_STAGE(PG8_SB(1, 1), b3 + hstep, voffB);
;             PG8_WAIT_V(6); PG8_BAR; PG8_MMA(1, 1, At, B1); PG8_BAR;
	s_waitcnt lgkmcnt(0)
	s_setprio 1
	v_mfma_f32_16x16x32_bf16 v[78:81], v[58:61], v[176:179], v[78:81]
	v_mfma_f32_16x16x32_bf16 v[74:77], v[66:69], v[176:179], v[74:77]
	v_mfma_f32_16x16x32_bf16 v[54:57], v[58:61], v[184:187], v[54:57]
	v_mfma_f32_16x16x32_bf16 v[50:53], v[66:69], v[184:187], v[50:53]
	v_mfma_f32_16x16x32_bf16 v[30:33], v[58:61], v[192:195], v[30:33]
	v_mfma_f32_16x16x32_bf16 v[26:29], v[66:69], v[192:195], v[26:29]
	v_mfma_f32_16x16x32_bf16 v[14:17], v[58:61], v[210:213], v[14:17]
	v_mfma_f32_16x16x32_bf16 v[10:13], v[66:69], v[210:213], v[10:13]
	v_mfma_f32_16x16x32_bf16 v[78:81], v[62:65], v[180:183], v[78:81]
	v_mfma_f32_16x16x32_bf16 v[74:77], v[70:73], v[180:183], v[74:77]
	v_mfma_f32_16x16x32_bf16 v[54:57], v[62:65], v[188:191], v[54:57]
	v_mfma_f32_16x16x32_bf16 v[50:53], v[70:73], v[188:191], v[50:53]
	v_mfma_f32_16x16x32_bf16 v[30:33], v[62:65], v[196:199], v[30:33]
	v_mfma_f32_16x16x32_bf16 v[26:29], v[70:73], v[196:199], v[26:29]
	v_mfma_f32_16x16x32_bf16 v[14:17], v[62:65], v[214:217], v[14:17]
	v_mfma_f32_16x16x32_bf16 v[10:13], v[70:73], v[214:217], v[10:13]
	s_setprio 0
	s_barrier
	s_add_u32 s20, s20, 0x200080
	s_addc_u32 s21, s21, 0
	s_add_i32 s22, s22, s31
	v_lshl_add_u64 v[58:59], s[20:21], 0, v[0:1]
	s_mov_b32 m0, s22
	s_nop 0
	global_load_lds_dwordx4 v[58:59], off
	v_lshl_add_u64 v[58:59], s[20:21], 0, v[164:165]
	s_add_i32 m0, s22, 0x2000
	s_nop 0
	global_load_lds_dwordx4 v[58:59], off
	s_waitcnt vmcnt(6)
	s_barrier
	s_setprio 1
	v_mfma_f32_16x16x32_bf16 v[42:45], v[218:221], v[176:179], v[42:45]
	v_mfma_f32_16x16x32_bf16 v[70:73], v[222:225], v[180:183], v[42:45]
	v_mfma_f32_16x16x32_bf16 v[42:45], v[226:229], v[176:179], v[46:49]
	v_mfma_f32_16x16x32_bf16 v[38:41], v[218:221], v[184:187], v[38:41]
	v_mfma_f32_16x16x32_bf16 v[34:37], v[226:229], v[184:187], v[34:37]
	v_mfma_f32_16x16x32_bf16 v[22:25], v[218:221], v[192:195], v[22:25]
	v_mfma_f32_16x16x32_bf16 v[18:21], v[226:229], v[192:195], v[18:21]
	v_mfma_f32_16x16x32_bf16 v[6:9], v[218:221], v[210:213], v[6:9]
	v_mfma_f32_16x16x32_bf16 v[2:5], v[226:229], v[210:213], v[2:5]
	v_mfma_f32_16x16x32_bf16 v[66:69], v[230:233], v[180:183], v[42:45]
	v_mfma_f32_16x16x32_bf16 v[38:41], v[222:225], v[188:191], v[38:41]
	v_mfma_f32_16x16x32_bf16 v[34:37], v[230:233], v[188:191], v[34:37]
	v_mfma_f32_16x16x32_bf16 v[22:25], v[222:225], v[196:199], v[22:25]
	v_mfma_f32_16x16x32_bf16 v[18:21], v[230:233], v[196:199], v[18:21]
	v_mfma_f32_16x16x32_bf16 v[6:9], v[222:225], v[214:217], v[6:9]
	v_mfma_f32_16x16x32_bf16 v[2:5], v[230:233], v[214:217], v[2:5]
	s_setprio 0
	s_add_i32 s49, s49, 2
	s_add_u32 s47, s47, 0x100
	s_addc_u32 s48, s48, 0
	s_add_u32 s18, s18, 0x100
	s_addc_u32 s19, s19, 0
	s_cmpk_gt_u32 s49, 0x7d
	s_barrier
	s_cbranch_scc0 .LBB0_62
	s_lshl_b32 s11, s2, 8
	s_lshl_b32 s13, s43, 8
	v_mov_b32_e32 v175, v172
	v_mov_b32_e32 v42, v159
	s_add_i32 s11, s11, s37
	s_or_b32 s13, s13, s38
	s_ashr_i32 s2, s2, 5
	s_mov_b32 s43, s10
	v_lshl_add_u32 v170, v42, 3, s13
	s_mul_hi_i32 s13, s2, 0xc000
	s_mul_i32 s2, s2, 0xc000
	v_add_u32_e32 v176, s11, v175
	s_add_u32 s18, s27, s2
	v_ashrrev_i32_e32 v177, 31, v176
	s_addc_u32 s19, s28, s13
	v_ashrrev_i32_e32 v171, 31, v170
	v_lshlrev_b64 v[176:177], 11, v[176:177]
	v_lshl_add_u64 v[46:47], v[170:171], 2, s[18:19]
	v_lshl_add_u64 v[170:171], v[176:177], 0, v[170:171]
	v_lshlrev_b64 v[170:171], 1, v[170:171]
	v_lshl_add_u64 v[180:181], s[8:9], 0, v[170:171]
	global_load_dwordx4 v[58:61], v[46:47], off offset:16
	global_load_dwordx4 v[62:65], v[46:47], off
	global_load_dwordx4 v[42:45], v[46:47], off offset:528
	s_nop 0
	global_load_dwordx4 v[46:49], v[46:47], off offset:512
	s_mov_b64 s[92:93], s[8:9]
	s_mov_b64 s[94:95], s[6:7]
	global_load_dwordx4 v[184:187], v170, s[92:93]
	global_load_dwordx4 v[188:191], v170, s[92:93] offset:256
	s_add_u32 s92, s92, 0x10000
	s_addc_u32 s93, s93, 0
	global_load_dwordx4 v[192:195], v170, s[92:93]
	global_load_dwordx4 v[196:199], v170, s[92:93] offset:256
	s_add_u32 s92, s92, 0x10000
	s_addc_u32 s93, s93, 0
	global_load_dwordx4 v[210:213], v170, s[92:93]
	global_load_dwordx4 v[214:217], v170, s[92:93] offset:256
	s_add_u32 s92, s92, 0x10000
	s_addc_u32 s93, s93, 0
	global_load_dwordx4 v[218:221], v170, s[92:93]
	global_load_dwordx4 v[222:225], v170, s[92:93] offset:256
	s_add_u32 s92, s92, 0x50000
	s_addc_u32 s93, s93, 0
	global_load_dwordx4 v[226:229], v170, s[92:93]
	global_load_dwordx4 v[230:233], v170, s[92:93] offset:256
	s_add_u32 s92, s92, 0x10000
	s_addc_u32 s93, s93, 0
	global_load_dwordx4 v[234:237], v170, s[92:93]
	s_waitcnt vmcnt(10)
	v_lshlrev_b32_e32 v176, 16, v184
	v_and_b32_e32 v177, 0xffff0000, v184
	v_lshlrev_b32_e32 v178, 16, v185
	v_and_b32_e32 v179, 0xffff0000, v185
	v_lshlrev_b32_e32 v180, 16, v186
	v_and_b32_e32 v181, 0xffff0000, v186
	v_lshlrev_b32_e32 v182, 16, v187
	v_and_b32_e32 v183, 0xffff0000, v187
	v_pk_fma_f32 v[142:143], v[142:143], v[62:63], v[176:177]
	v_pk_fma_f32 v[144:145], v[144:145], v[64:65], v[178:179]
	v_pk_fma_f32 v[138:139], v[138:139], v[58:59], v[180:181]
	v_pk_fma_f32 v[140:141], v[140:141], v[60:61], v[182:183]
	global_load_dwordx4 v[184:187], v170, s[92:93] offset:256
	v_cvt_pk_bf16_f32 v142, v142, v143
	v_cvt_pk_bf16_f32 v143, v144, v145
	v_cvt_pk_bf16_f32 v144, v138, v139
	v_cvt_pk_bf16_f32 v145, v140, v141
	global_store_dwordx4 v170, v[142:145], s[94:95]
	s_waitcnt vmcnt(11)
; __device__ __forceinline__ unsigned pk2(float lo, float hi) { f32x2 v = {lo, hi}; return __builtin_bit_cast(unsigned, __builtin_convertvector(v, bf16x2_t)); }
; __device__ __forceinline__ float bf_lo(unsigned w) { return __uint_as_float(w << 16); }
; __device__ __forceinline__ float bf_hi(unsigned w) { return __uint_as_float(w & 0xffff0000u); }
;     __device__ __forceinline__ void operator()(const f32x4 (&acc)[2][2][4][2], const Unit& u, int wr, int wc, int fr, int fq) const {
;     ...
;             for (int m = 0; m < 4; ++m) {
;                 const size_t ro = (size_t)(row0 + ai * HALF + m * 16) * DM + col0;
; #pragma unroll
;                 for (int bj = 0; bj < 2; ++bj) {
;                     f32x4 r0, r1;
;                     if (RB) { const u32x4 rw = *(const u32x4*)((const bf16_t*)resid + ro + bj * HALF);
;                         r0 = (f32x4){bf_lo(rw.x), bf_hi(rw.x), bf_lo(rw.y), bf_hi(rw.y)}; r1 = (f32x4){bf_lo(rw.z), bf_hi(rw.z), bf_lo(rw.w), bf_hi(rw.w)}; }
;                     else { r0 = *(const f32x4*)((const float*)resid + ro + bj * HALF); r1 = *(const f32x4*)((const float*)resid + ro + bj * HALF + 4); }
;                     const f32x4 v0 = r0 + gv[bj][0] * acc[ai][bj][m][0], v1 = r1 + gv[bj][1] * acc[ai][bj][m][1];
;                     if (OB) { u32x4 w; w.x = pk2(v0[0], v0[1]); w.y = pk2(v0[2], v0[3]); w.z = pk2(v1[0], v1[1]); w.w = pk2(v1[2], v1[3]); *(u32x4*)((bf16_t*)out + ro + bj * HALF) = w; }
;                     else { *(f32x4*)((float*)out + ro + bj * HALF) = v0; *(f32x4*)((float*)out + ro + bj * HALF + 4) = v1; }
;                 }
	v_lshlrev_b32_e32 v176, 16, v188
	v_and_b32_e32 v177, 0xffff0000, v188
	v_lshlrev_b32_e32 v178, 16, v189
	v_and_b32_e32 v179, 0xffff0000, v189
	v_lshlrev_b32_e32 v180, 16, v190
	v_and_b32_e32 v181, 0xffff0000, v190
	v_lshlrev_b32_e32 v182, 16, v191
	v_and_b32_e32 v183, 0xffff0000, v191
	v_pk_fma_f32 v[134:135], v[134:135], v[46:47], v[176:177]
	v_pk_fma_f32 v[136:137], v[136:137], v[48:49], v[178:179]
	v_pk_fma_f32 v[130:131], v[130:131], v[42:43], v[180:181]
	v_pk_fma_f32 v[132:133], v[132:133], v[44:45], v[182:183]
	s_add_u32 s92, s92, 0x10000
	s_addc_u32 s93, s93, 0
	global_load_dwordx4 v[188:191], v170, s[92:93]
	v_cvt_pk_bf16_f32 v134, v134, v135
	v_cvt_pk_bf16_f32 v135, v136, v137
	v_cvt_pk_bf16_f32 v136, v130, v131
	v_cvt_pk_bf16_f32 v137, v132, v133
	global_store_dwordx4 v170, v[134:137], s[94:95] offset:256
	s_waitcnt vmcnt(12)
	v_lshlrev_b32_e32 v176, 16, v192
	v_and_b32_e32 v177, 0xffff0000, v192
	v_lshlrev_b32_e32 v178, 16, v193
	v_and_b32_e32 v179, 0xffff0000, v193
	v_lshlrev_b32_e32 v180, 16, v194
	v_and_b32_e32 v181, 0xffff0000, v194
	v_lshlrev_b32_e32 v182, 16, v195
	v_and_b32_e32 v183, 0xffff0000, v195
	v_pk_fma_f32 v[126:127], v[126:127], v[62:63], v[176:177]
	v_pk_fma_f32 v[128:129], v[128:129], v[64:65], v[178:179]
	v_pk_fma_f32 v[122:123], v[122:123], v[58:59], v[180:181]
	v_pk_fma_f32 v[124:125], v[124:125], v[60:61], v[182:183]
	global_load_dwordx4 v[192:195], v170, s[92:93] offset:256
	s_add_u32 s94, s94, 0x10000
	s_addc_u32 s95, s95, 0
	v_cvt_pk_bf16_f32 v126, v126, v127
	v_cvt_pk_bf16_f32 v127, v128, v129
	v_cvt_pk_bf16_f32 v128, v122, v123
	v_cvt_pk_bf16_f32 v129, v124, v125
	global_store_dwordx4 v170, v[126:129], s[94:95]
	s_waitcnt vmcnt(13)
	v_lshlrev_b32_e32 v176, 16, v196
	v_and_b32_e32 v177, 0xffff0000, v196
	v_lshlrev_b32_e32 v178, 16, v197
	v_and_b32_e32 v179, 0xffff0000, v197
	v_lshlrev_b32_e32 v180, 16, v198
	v_and_b32_e32 v181, 0xffff0000, v198
	v_lshlrev_b32_e32 v182, 16, v199
	v_and_b32_e32 v183, 0xffff0000, v199
	v_pk_fma_f32 v[118:119], v[118:119], v[46:47], v[176:177]
	v_pk_fma_f32 v[120:121], v[120:121], v[48:49], v[178:179]
	v_pk_fma_f32 v[114:115], v[114:115], v[42:43], v[180:181]
	v_pk_fma_f32 v[116:117], v[116:117], v[44:45], v[182:183]
	s_add_u32 s92, s92, 0x10000
	s_addc_u32 s93, s93, 0
	global_load_dwordx4 v[196:199], v170, s[92:93]
	v_cvt_pk_bf16_f32 v118, v118, v119
	v_cvt_pk_bf16_f32 v119, v120, v121
	v_cvt_pk_bf16_f32 v120, v114, v115
	v_cvt_pk_bf16_f32 v121, v116, v117
	global_store_dwordx4 v170, v[118:121], s[94:95] offset:256
	s_waitcnt vmcnt(14)
	v_lshlrev_b32_e32 v176, 16, v210
	v_and_b32_e32 v177, 0xffff0000, v210
	v_lshlrev_b32_e32 v178, 16, v211
	v_and_b32_e32 v179, 0xffff0000, v211
	v_lshlrev_b32_e32 v180, 16, v212
	v_and_b32_e32 v181, 0xffff0000, v212
	v_lshlrev_b32_e32 v182, 16, v213
	v_and_b32_e32 v183, 0xffff0000, v213
	v_pk_fma_f32 v[110:111], v[110:111], v[62:63], v[176:177]
	v_pk_fma_f32 v[112:113], v[112:113], v[64:65], v[178:179]
	v_pk_fma_f32 v[106:107], v[106:107], v[58:59], v[180:181]
	v_pk_fma_f32 v[108:109], v[108:109], v[60:61], v[182:183]
	global_load_dwordx4 v[210:213], v170, s[92:93] offset:256
	s_add_u32 s94, s94, 0x10000
	s_addc_u32 s95, s95, 0
	v_cvt_pk_bf16_f32 v110, v110, v111
	v_cvt_pk_bf16_f32 v111, v112, v113
	v_cvt_pk_bf16_f32 v112, v106, v107
	v_cvt_pk_bf16_f32 v113, v108, v109
	global_store_dwordx4 v170, v[110:113], s[94:95]
	s_waitcnt vmcnt(15)
	v_lshlrev_b32_e32 v176, 16, v214
	v_and_b32_e32 v177, 0xffff0000, v214
	v_lshlrev_b32_e32 v178, 16, v215
	v_and_b32_e32 v179, 0xffff0000, v215
	v_lshlrev_b32_e32 v180, 16, v216
	v_and_b32_e32 v181, 0xffff0000, v216
	v_lshlrev_b32_e32 v182, 16, v217
	v_and_b32_e32 v183, 0xffff0000, v217
	v_pk_fma_f32 v[102:103], v[102:103], v[46:47], v[176:177]
	v_pk_fma_f32 v[104:105], v[104:105], v[48:49], v[178:179]
	v_pk_fma_f32 v[98:99], v[98:99], v[42:43], v[180:181]
	v_pk_fma_f32 v[100:101], v[100:101], v[44:45], v[182:183]
	v_cvt_pk_bf16_f32 v102, v102, v103
	v_cvt_pk_bf16_f32 v103, v104, v105
	v_cvt_pk_bf16_f32 v104, v98, v99
	v_cvt_pk_bf16_f32 v105, v100, v101
	global_store_dwordx4 v170, v[102:105], s[94:95] offset:256
	s_waitcnt vmcnt(15)
	v_lshlrev_b32_e32 v176, 16, v218
	v_and_b32_e32 v177, 0xffff0000, v218
	v_lshlrev_b32_e32 v178, 16, v219
	v_and_b32_e32 v179, 0xffff0000, v219
	v_lshlrev_b32_e32 v180, 16, v220
	v_and_b32_e32 v181, 0xffff0000, v220
	v_lshlrev_b32_e32 v182, 16, v221
	v_and_b32_e32 v183, 0xffff0000, v221
	v_pk_fma_f32 v[94:95], v[94:95], v[62:63], v[176:177]
	v_pk_fma_f32 v[96:97], v[96:97], v[64:65], v[178:179]
	v_pk_fma_f32 v[90:91], v[90:91], v[58:59], v[180:181]
	v_pk_fma_f32 v[92:93], v[92:93], v[60:61], v[182:183]
	s_add_u32 s94, s94, 0x10000
	s_addc_u32 s95, s95, 0
	v_cvt_pk_bf16_f32 v94, v94, v95
	v_cvt_pk_bf16_f32 v95, v96, v97
	v_cvt_pk_bf16_f32 v96, v90, v91
	v_cvt_pk_bf16_f32 v97, v92, v93
	global_store_dwordx4 v170, v[94:97], s[94:95]
	s_waitcnt vmcnt(15)
	v_lshlrev_b32_e32 v176, 16, v222
	v_and_b32_e32 v177, 0xffff0000, v222
	v_lshlrev_b32_e32 v178, 16, v223
	v_and_b32_e32 v179, 0xffff0000, v223
	v_lshlrev_b32_e32 v180, 16, v224
	v_and_b32_e32 v181, 0xffff0000, v224
	v_lshlrev_b32_e32 v182, 16, v225
	v_and_b32_e32 v183, 0xffff0000, v225
	v_pk_fma_f32 v[86:87], v[86:87], v[46:47], v[176:177]
	v_pk_fma_f32 v[88:89], v[88:89], v[48:49], v[178:179]
	v_pk_fma_f32 v[82:83], v[82:83], v[42:43], v[180:181]
	v_pk_fma_f32 v[84:85], v[84:85], v[44:45], v[182:183]
	v_cvt_pk_bf16_f32 v86, v86, v87
	v_cvt_pk_bf16_f32 v87, v88, v89
	v_cvt_pk_bf16_f32 v88, v82, v83
	v_cvt_pk_bf16_f32 v89, v84, v85
	global_store_dwordx4 v170, v[86:89], s[94:95] offset:256
	s_waitcnt vmcnt(15)
; __device__ __forceinline__ unsigned pk2(float lo, float hi) { f32x2 v = {lo, hi}; return __builtin_bit_cast(unsigned, __builtin_convertvector(v, bf16x2_t)); }
; __device__ __forceinline__ float bf_lo(unsigned w) { return __uint_as_float(w << 16); }
; __device__ __forceinline__ float bf_hi(unsigned w) { return __uint_as_float(w & 0xffff0000u); }
; #define PG8_WAIT_V(n) asm volatile("s_waitcnt vmcnt(" #n ")" ::: "memory")
; #define PG8_BAR __builtin_amdgcn_s_barrier()
;     __device__ __forceinline__ void operator()(const f32x4 (&acc)[2][2][4][2], const Unit& u, int wr, int wc, int fr, int fq) const {
;     ...
;             for (int m = 0; m < 4; ++m) {
;                 const size_t ro = (size_t)(row0 + ai * HALF + m * 16) * DM + col0;
; #pragma unroll
;                 for (int bj = 0; bj < 2; ++bj) {
;                     f32x4 r0, r1;
;                     if (RB) { const u32x4 rw = *(const u32x4*)((const bf16_t*)resid + ro + bj * HALF);
;                         r0 = (f32x4){bf_lo(rw.x), bf_hi(rw.x), bf_lo(rw.y), bf_hi(rw.y)}; r1 = (f32x4){bf_lo(rw.z), bf_hi(rw.z), bf_lo(rw.w), bf_hi(rw.w)}; }
;                     else { r0 = *(const f32x4*)((const float*)resid + ro + bj * HALF); r1 = *(const f32x4*)((const float*)resid + ro + bj * HALF + 4); }
;                     const f32x4 v0 = r0 + gv[bj][0] * acc[ai][bj][m][0], v1 = r1 + gv[bj][1] * acc[ai][bj][m][1];
;                     if (OB) { u32x4 w; w.x = pk2(v0[0], v0[1]); w.y = pk2(v0[2], v0[3]); w.z = pk2(v1[0], v1[1]); w.w = pk2(v1[2], v1[3]); *(u32x4*)((bf16_t*)out + ro + bj * HALF) = w; }
;                     else { *(f32x4*)((float*)out + ro + bj * HALF) = v0; *(f32x4*)((float*)out + ro + bj * HALF + 4) = v1; }
;                 }
; template <class Epi>
; __device__ __forceinline__ void gemm_phase(LAS unsigned char* lds, const Gemm g, const StaticOrder& S, const Epi& E, const int tid) {
;     ...
;         if (!has_next) break;
; #pragma unroll
;         for (int a = 0; a < 2; ++a)
; #pragma unroll
;             for (int b = 0; b < 2; ++b)
; #pragma unroll
;                 for (int m = 0; m < 4; ++m)
; #pragma unroll
;                     for (int n = 0; n < 2; ++n) acc[a][b][m][n] = (f32x4){0.f, 0.f, 0.f, 0.f};
;         cur = nxt; cA = nA; cB = nB; ++ui;
;     }
;     PG8_WAIT_V(0);
;     if (wr == 0) PG8_BAR;
;     PG8_BAR;
	v_lshlrev_b32_e32 v176, 16, v226
	v_and_b32_e32 v177, 0xffff0000, v226
	v_lshlrev_b32_e32 v178, 16, v227
	v_and_b32_e32 v179, 0xffff0000, v227
	v_lshlrev_b32_e32 v180, 16, v228
	v_and_b32_e32 v181, 0xffff0000, v228
	v_lshlrev_b32_e32 v182, 16, v229
	v_and_b32_e32 v183, 0xffff0000, v229
	v_pk_fma_f32 v[78:79], v[78:79], v[62:63], v[176:177]
	v_pk_fma_f32 v[80:81], v[80:81], v[64:65], v[178:179]
	v_pk_fma_f32 v[74:75], v[74:75], v[58:59], v[180:181]
	v_pk_fma_f32 v[76:77], v[76:77], v[60:61], v[182:183]
	s_add_u32 s94, s94, 0x50000
	s_addc_u32 s95, s95, 0
	v_cvt_pk_bf16_f32 v78, v78, v79
	v_cvt_pk_bf16_f32 v79, v80, v81
	v_cvt_pk_bf16_f32 v80, v74, v75
	v_cvt_pk_bf16_f32 v81, v76, v77
	global_store_dwordx4 v170, v[78:81], s[94:95]
	s_waitcnt vmcnt(15)
	v_lshlrev_b32_e32 v176, 16, v230
	v_and_b32_e32 v177, 0xffff0000, v230
	v_lshlrev_b32_e32 v178, 16, v231
	v_and_b32_e32 v179, 0xffff0000, v231
	v_lshlrev_b32_e32 v180, 16, v232
	v_and_b32_e32 v181, 0xffff0000, v232
	v_lshlrev_b32_e32 v182, 16, v233
	v_and_b32_e32 v183, 0xffff0000, v233
	v_pk_fma_f32 v[70:71], v[70:71], v[46:47], v[176:177]
	v_pk_fma_f32 v[72:73], v[72:73], v[48:49], v[178:179]
	v_pk_fma_f32 v[66:67], v[66:67], v[42:43], v[180:181]
	v_pk_fma_f32 v[68:69], v[68:69], v[44:45], v[182:183]
	v_cvt_pk_bf16_f32 v70, v70, v71
	v_cvt_pk_bf16_f32 v71, v72, v73
	v_cvt_pk_bf16_f32 v72, v66, v67
	v_cvt_pk_bf16_f32 v73, v68, v69
	global_store_dwordx4 v170, v[70:73], s[94:95] offset:256
	s_waitcnt vmcnt(15)
	v_lshlrev_b32_e32 v176, 16, v234
	v_and_b32_e32 v177, 0xffff0000, v234
	v_lshlrev_b32_e32 v178, 16, v235
	v_and_b32_e32 v179, 0xffff0000, v235
	v_lshlrev_b32_e32 v180, 16, v236
	v_and_b32_e32 v181, 0xffff0000, v236
	v_lshlrev_b32_e32 v182, 16, v237
	v_and_b32_e32 v183, 0xffff0000, v237
	v_pk_fma_f32 v[54:55], v[54:55], v[62:63], v[176:177]
	v_pk_fma_f32 v[56:57], v[56:57], v[64:65], v[178:179]
	v_pk_fma_f32 v[50:51], v[50:51], v[58:59], v[180:181]
	v_pk_fma_f32 v[52:53], v[52:53], v[60:61], v[182:183]
	s_add_u32 s94, s94, 0x10000
	s_addc_u32 s95, s95, 0
	v_cvt_pk_bf16_f32 v54, v54, v55
	v_cvt_pk_bf16_f32 v55, v56, v57
	v_cvt_pk_bf16_f32 v56, v50, v51
	v_cvt_pk_bf16_f32 v57, v52, v53
	global_store_dwordx4 v170, v[54:57], s[94:95]
	s_waitcnt vmcnt(15)
	v_lshlrev_b32_e32 v176, 16, v184
	v_and_b32_e32 v177, 0xffff0000, v184
	v_lshlrev_b32_e32 v178, 16, v185
	v_and_b32_e32 v179, 0xffff0000, v185
	v_lshlrev_b32_e32 v180, 16, v186
	v_and_b32_e32 v181, 0xffff0000, v186
	v_lshlrev_b32_e32 v182, 16, v187
	v_and_b32_e32 v183, 0xffff0000, v187
	v_pk_fma_f32 v[38:39], v[38:39], v[46:47], v[176:177]
	v_pk_fma_f32 v[40:41], v[40:41], v[48:49], v[178:179]
	v_pk_fma_f32 v[34:35], v[34:35], v[42:43], v[180:181]
	v_pk_fma_f32 v[36:37], v[36:37], v[44:45], v[182:183]
	v_cvt_pk_bf16_f32 v38, v38, v39
	v_cvt_pk_bf16_f32 v39, v40, v41
	v_cvt_pk_bf16_f32 v40, v34, v35
	v_cvt_pk_bf16_f32 v41, v36, v37
	global_store_dwordx4 v170, v[38:41], s[94:95] offset:256
	s_waitcnt vmcnt(14)
	v_lshlrev_b32_e32 v176, 16, v188
	v_and_b32_e32 v177, 0xffff0000, v188
	v_lshlrev_b32_e32 v178, 16, v189
	v_and_b32_e32 v179, 0xffff0000, v189
	v_lshlrev_b32_e32 v180, 16, v190
	v_and_b32_e32 v181, 0xffff0000, v190
	v_lshlrev_b32_e32 v182, 16, v191
	v_and_b32_e32 v183, 0xffff0000, v191
	v_pk_fma_f32 v[30:31], v[30:31], v[62:63], v[176:177]
	v_pk_fma_f32 v[32:33], v[32:33], v[64:65], v[178:179]
	v_pk_fma_f32 v[26:27], v[26:27], v[58:59], v[180:181]
	v_pk_fma_f32 v[28:29], v[28:29], v[60:61], v[182:183]
	s_add_u32 s94, s94, 0x10000
	s_addc_u32 s95, s95, 0
	v_cvt_pk_bf16_f32 v30, v30, v31
	v_cvt_pk_bf16_f32 v31, v32, v33
	v_cvt_pk_bf16_f32 v32, v26, v27
	v_cvt_pk_bf16_f32 v33, v28, v29
	global_store_dwordx4 v170, v[30:33], s[94:95]
	s_waitcnt vmcnt(13)
	v_lshlrev_b32_e32 v176, 16, v192
	v_and_b32_e32 v177, 0xffff0000, v192
	v_lshlrev_b32_e32 v178, 16, v193
	v_and_b32_e32 v179, 0xffff0000, v193
	v_lshlrev_b32_e32 v180, 16, v194
	v_and_b32_e32 v181, 0xffff0000, v194
	v_lshlrev_b32_e32 v182, 16, v195
	v_and_b32_e32 v183, 0xffff0000, v195
	v_pk_fma_f32 v[22:23], v[22:23], v[46:47], v[176:177]
	v_pk_fma_f32 v[24:25], v[24:25], v[48:49], v[178:179]
	v_pk_fma_f32 v[18:19], v[18:19], v[42:43], v[180:181]
	v_pk_fma_f32 v[20:21], v[20:21], v[44:45], v[182:183]
	v_cvt_pk_bf16_f32 v22, v22, v23
	v_cvt_pk_bf16_f32 v23, v24, v25
	v_cvt_pk_bf16_f32 v24, v18, v19
	v_cvt_pk_bf16_f32 v25, v20, v21
	global_store_dwordx4 v170, v[22:25], s[94:95] offset:256
	s_waitcnt vmcnt(12)
	v_lshlrev_b32_e32 v176, 16, v196
	v_and_b32_e32 v177, 0xffff0000, v196
	v_lshlrev_b32_e32 v178, 16, v197
	v_and_b32_e32 v179, 0xffff0000, v197
	v_lshlrev_b32_e32 v180, 16, v198
	v_and_b32_e32 v181, 0xffff0000, v198
	v_lshlrev_b32_e32 v182, 16, v199
	v_and_b32_e32 v183, 0xffff0000, v199
	v_pk_fma_f32 v[14:15], v[14:15], v[62:63], v[176:177]
	v_pk_fma_f32 v[16:17], v[16:17], v[64:65], v[178:179]
	v_pk_fma_f32 v[10:11], v[10:11], v[58:59], v[180:181]
	v_pk_fma_f32 v[12:13], v[12:13], v[60:61], v[182:183]
	s_add_u32 s94, s94, 0x10000
	s_addc_u32 s95, s95, 0
	v_cvt_pk_bf16_f32 v14, v14, v15
	v_cvt_pk_bf16_f32 v15, v16, v17
	v_cvt_pk_bf16_f32 v16, v10, v11
	v_cvt_pk_bf16_f32 v17, v12, v13
	global_store_dwordx4 v170, v[14:17], s[94:95]
	s_waitcnt vmcnt(11)
	v_lshlrev_b32_e32 v176, 16, v210
	v_and_b32_e32 v177, 0xffff0000, v210
	v_lshlrev_b32_e32 v178, 16, v211
	v_and_b32_e32 v179, 0xffff0000, v211
	v_lshlrev_b32_e32 v180, 16, v212
	v_and_b32_e32 v181, 0xffff0000, v212
	v_lshlrev_b32_e32 v182, 16, v213
	v_and_b32_e32 v183, 0xffff0000, v213
	v_pk_fma_f32 v[6:7], v[6:7], v[46:47], v[176:177]
	v_pk_fma_f32 v[8:9], v[8:9], v[48:49], v[178:179]
	v_pk_fma_f32 v[2:3], v[2:3], v[42:43], v[180:181]
	v_pk_fma_f32 v[4:5], v[4:5], v[44:45], v[182:183]
	v_cvt_pk_bf16_f32 v6, v6, v7
	v_cvt_pk_bf16_f32 v7, v8, v9
	v_cvt_pk_bf16_f32 v8, v2, v3
	v_cvt_pk_bf16_f32 v9, v4, v5
	global_store_dwordx4 v170, v[6:9], s[94:95] offset:256
	s_mov_b32 s2, s12
	s_mov_b64 s[20:21], s[14:15]
	s_mov_b64 s[18:19], s[16:17]
	s_and_b64 vcc, exec, s[4:5]
	s_nop 1
	s_cbranch_vccz .LBB0_55
	s_waitcnt vmcnt(0)
	s_cmpk_gt_u32 s29, 0xff
	s_cbranch_scc1 .LBB0_66
	s_barrier

; #define PG8_STAGE(bufoff, gbase, voff) do { _Pragma("unroll") for (int _i = 0; _i < 2; ++_i) \
;         __builtin_amdgcn_global_load_lds((const unsigned*)((const char*)(gbase) + (voff)[_i]), (LAS unsigned*)(lds + (bufoff) + ldsw + _i * 8192), 16, 0, 0); } while (0)
; #define PG8_LDA(dst, b, h) do { _Pragma("unroll") for (int m = 0; m < 4; ++m) _Pragma("unroll") for (int k = 0; k < 2; ++k) dst[m][k] = *(const LAS bf16x8*)(lds + PG8_SA(b, h) + aoff + m * 2048 + k * 1024); } while (0)
; #define PG8_LDB(dst, b, h) do { _Pragma("unroll") for (int n = 0; n < 2; ++n) _Pragma("unroll") for (int k = 0; k < 2; ++k) dst[n][k] = *(const LAS bf16x8*)(lds + PG8_SB(b, h) + boff + n * 2048 + k * 1024); } while (0)
; #define PG8_MMA(ai, bj, At, Bt) do { __builtin_amdgcn_s_setprio(1); _Pragma("unroll") for (int m = 0; m < 4; ++m) _Pragma("unroll") for (int n = 0; n < 2; ++n) _Pragma("unroll") for (int k = 0; k < 2; ++k) \
;         acc[ai][bj][m][n] = __builtin_amdgcn_mfma_f32_16x16x32_bf16(Bt[n][k], At[m][k], acc[ai][bj][m][n], 0, 0, 0); __builtin_amdgcn_s_setprio(0); } while (0)
; #define PG8_WAIT_L(n) asm volatile("s_waitcnt lgkmcnt(" #n ")" ::: "memory")
; #define PG8_BAR __builtin_amdgcn_s_barrier()
; #define PG8_SCHED __builtin_amdgcn_sched_barrier(0)
; template <class Epi>
; __device__ __forceinline__ void gemm_phase(LAS unsigned char* lds, const Gemm g, const StaticOrder& S, const Epi& E, const int tid) {
;     ...
;             PG8_LDB(B0, 0, 0); PG8_SCHED; PG8_LDA(At, 0, 0); PG8_STAGE(PG8_SA(1, 1), a1 + hstep, voffA);
;             PG8_WAIT_L(8); PG8_BAR; PG8_WAIT_L(0); PG8_MMA(0, 0, At, B0); PG8_BAR; PG8_SCHED;
;             PG8_LDB(B1, 0, 1); PG8_STAGE(PG8_SB(0, 0), b2, voffB);
;             PG8_BAR; PG8_WAIT_L(0); PG8_MMA(0, 1, At, B1); PG8_BAR;
;             PG8_LDA(At, 0, 1); PG8_STAGE(PG8_SA(0, 0), a2, voffA);
;             PG8_BAR; PG8_WAIT_L(0); PG8_MMA(1, 0, At, B0); PG8_BAR; PG8_SCHED;
.LBB0_84:
	s_add_u32 s18, s16, 0xfff80080
	s_addc_u32 s19, s17, -1
	s_add_i32 s45, 0, 0x10000
	v_add_u32_e32 v140, s45, v144
	ds_read_b128 v[160:163], v140
	ds_read_b128 v[164:167], v140 offset:1024
	ds_read_b128 v[168:171], v140 offset:2048
	ds_read_b128 v[172:175], v140 offset:3072
	s_cmp_eq_u32 s44, 28
	s_cselect_b32 s21, s9, s19
	s_cselect_b32 s20, s40, s18
	s_cselect_b32 s19, s7, s43
	s_cselect_b32 s18, s41, s42
	v_lshl_add_u64 v[140:141], s[16:17], 0, v[138:139]
	s_add_i32 m0, s15, 0xc000
	ds_read_b128 v[176:179], v145
	ds_read_b128 v[180:183], v145 offset:1024
	ds_read_b128 v[184:187], v145 offset:2048
	ds_read_b128 v[188:191], v145 offset:3072
	ds_read_b128 v[192:195], v145 offset:4096
	ds_read_b128 v[196:199], v145 offset:5120
	ds_read_b128 v[210:213], v145 offset:6144
	ds_read_b128 v[214:217], v145 offset:7168
	global_load_lds_dwordx4 v[140:141], off
	v_lshl_add_u64 v[140:141], s[16:17], 0, v[136:137]
	s_add_i32 m0, s15, 0xe000
	s_nop 0
	global_load_lds_dwordx4 v[140:141], off
	s_waitcnt lgkmcnt(8)
	s_barrier
	s_waitcnt lgkmcnt(0)
	s_setprio 1
	v_mfma_f32_16x16x32_bf16 v[126:129], v[160:163], v[176:179], v[126:129]
	v_mfma_f32_16x16x32_bf16 v[122:125], v[168:171], v[176:179], v[122:125]
	v_mfma_f32_16x16x32_bf16 v[110:113], v[160:163], v[184:187], v[110:113]
	v_mfma_f32_16x16x32_bf16 v[106:109], v[168:171], v[184:187], v[106:109]
	v_mfma_f32_16x16x32_bf16 v[94:97], v[160:163], v[192:195], v[94:97]
	v_mfma_f32_16x16x32_bf16 v[90:93], v[168:171], v[192:195], v[90:93]
	v_mfma_f32_16x16x32_bf16 v[78:81], v[160:163], v[210:213], v[78:81]
	v_mfma_f32_16x16x32_bf16 v[74:77], v[168:171], v[210:213], v[74:77]
	v_mfma_f32_16x16x32_bf16 v[126:129], v[164:167], v[180:183], v[126:129]
	v_mfma_f32_16x16x32_bf16 v[122:125], v[172:175], v[180:183], v[122:125]
	v_mfma_f32_16x16x32_bf16 v[110:113], v[164:167], v[188:191], v[110:113]
	v_mfma_f32_16x16x32_bf16 v[106:109], v[172:175], v[188:191], v[106:109]
	v_mfma_f32_16x16x32_bf16 v[94:97], v[164:167], v[196:199], v[94:97]
	v_mfma_f32_16x16x32_bf16 v[90:93], v[172:175], v[196:199], v[90:93]
	v_mfma_f32_16x16x32_bf16 v[78:81], v[164:167], v[214:217], v[78:81]
	v_mfma_f32_16x16x32_bf16 v[74:77], v[172:175], v[214:217], v[74:77]
	s_setprio 0
	s_barrier
	s_add_i32 s47, 0, 0x14000
	v_add_u32_e32 v140, s47, v144
	s_add_i32 s45, s45, s26
	ds_read_b128 v[218:221], v140
	ds_read_b128 v[222:225], v140 offset:1024
	ds_read_b128 v[226:229], v140 offset:2048
	ds_read_b128 v[230:233], v140 offset:3072
	v_lshl_add_u64 v[140:141], s[18:19], 0, v[0:1]
	s_mov_b32 m0, s45
	v_lshl_add_u64 v[200:201], s[18:19], 0, v[134:135]
	global_load_lds_dwordx4 v[140:141], off
	s_add_i32 m0, s45, 0x2000
	s_nop 0
	global_load_lds_dwordx4 v[200:201], off
	s_barrier
	s_waitcnt lgkmcnt(0)
	s_setprio 1
	v_mfma_f32_16x16x32_bf16 v[118:121], v[218:221], v[176:179], v[118:121]
	v_mfma_f32_16x16x32_bf16 v[114:117], v[226:229], v[176:179], v[114:117]
	v_mfma_f32_16x16x32_bf16 v[102:105], v[218:221], v[184:187], v[102:105]
	v_mfma_f32_16x16x32_bf16 v[98:101], v[226:229], v[184:187], v[98:101]
	v_mfma_f32_16x16x32_bf16 v[86:89], v[218:221], v[192:195], v[86:89]
	v_mfma_f32_16x16x32_bf16 v[82:85], v[226:229], v[192:195], v[82:85]
	v_mfma_f32_16x16x32_bf16 v[70:73], v[218:221], v[210:213], v[70:73]
	v_mfma_f32_16x16x32_bf16 v[66:69], v[226:229], v[210:213], v[66:69]
	v_mfma_f32_16x16x32_bf16 v[118:121], v[222:225], v[180:183], v[118:121]
	v_mfma_f32_16x16x32_bf16 v[114:117], v[230:233], v[180:183], v[114:117]
	v_mfma_f32_16x16x32_bf16 v[102:105], v[222:225], v[188:191], v[102:105]
	v_mfma_f32_16x16x32_bf16 v[98:101], v[230:233], v[188:191], v[98:101]
	v_mfma_f32_16x16x32_bf16 v[86:89], v[222:225], v[196:199], v[86:89]
	v_mfma_f32_16x16x32_bf16 v[82:85], v[230:233], v[196:199], v[82:85]
	v_mfma_f32_16x16x32_bf16 v[70:73], v[222:225], v[214:217], v[70:73]
	v_mfma_f32_16x16x32_bf16 v[66:69], v[230:233], v[214:217], v[66:69]
	s_setprio 0
	s_mov_b32 m0, s15
	v_lshl_add_u64 v[234:235], s[20:21], 0, v[130:131]
	s_barrier
	ds_read_b128 v[176:179], v145 offset:16384
	ds_read_b128 v[180:183], v145 offset:17408
	ds_read_b128 v[184:187], v145 offset:18432
	ds_read_b128 v[188:191], v145 offset:19456
	ds_read_b128 v[192:195], v145 offset:20480
	ds_read_b128 v[196:199], v145 offset:21504
	ds_read_b128 v[210:213], v145 offset:22528
	ds_read_b128 v[214:217], v145 offset:23552
	global_load_lds_dwordx4 v[234:235], off
	v_lshl_add_u64 v[236:237], s[20:21], 0, v[132:133]
	s_mov_b32 m0, s27
	s_nop 0
	global_load_lds_dwordx4 v[236:237], off
	s_barrier
	s_waitcnt lgkmcnt(0)
	s_setprio 1
	v_mfma_f32_16x16x32_bf16 v[62:65], v[160:163], v[176:179], v[62:65]
	v_mfma_f32_16x16x32_bf16 v[58:61], v[168:171], v[176:179], v[58:61]
	v_mfma_f32_16x16x32_bf16 v[46:49], v[160:163], v[184:187], v[46:49]
	v_mfma_f32_16x16x32_bf16 v[42:45], v[168:171], v[184:187], v[42:45]
	v_mfma_f32_16x16x32_bf16 v[30:33], v[160:163], v[192:195], v[30:33]
	v_mfma_f32_16x16x32_bf16 v[26:29], v[168:171], v[192:195], v[26:29]
	v_mfma_f32_16x16x32_bf16 v[14:17], v[160:163], v[210:213], v[14:17]
	v_mfma_f32_16x16x32_bf16 v[10:13], v[168:171], v[210:213], v[10:13]
	v_mfma_f32_16x16x32_bf16 v[62:65], v[164:167], v[180:183], v[62:65]
	v_mfma_f32_16x16x32_bf16 v[58:61], v[172:175], v[180:183], v[58:61]
	v_mfma_f32_16x16x32_bf16 v[46:49], v[164:167], v[188:191], v[46:49]
	v_mfma_f32_16x16x32_bf16 v[42:45], v[172:175], v[188:191], v[42:45]
	v_mfma_f32_16x16x32_bf16 v[30:33], v[164:167], v[196:199], v[30:33]
	v_mfma_f32_16x16x32_bf16 v[26:29], v[172:175], v[196:199], v[26:29]
	v_mfma_f32_16x16x32_bf16 v[14:17], v[164:167], v[214:217], v[14:17]
	v_mfma_f32_16x16x32_bf16 v[10:13], v[172:175], v[214:217], v[10:13]
	s_setprio 0
	s_barrier
; #define PG8_STAGE(bufoff, gbase, voff) do { _Pragma("unroll") for (int _i = 0; _i < 2; ++_i) \
;         __builtin_amdgcn_global_load_lds((const unsigned*)((const char*)(gbase) + (voff)[_i]), (LAS unsigned*)(lds + (bufoff) + ldsw + _i * 8192), 16, 0, 0); } while (0)
; #define PG8_LDA(dst, b, h) do { _Pragma("unroll") for (int m = 0; m < 4; ++m) _Pragma("unroll") for (int k = 0; k < 2; ++k) dst[m][k] = *(const LAS bf16x8*)(lds + PG8_SA(b, h) + aoff + m * 2048 + k * 1024); } while (0)
; #define PG8_LDB(dst, b, h) do { _Pragma("unroll") for (int n = 0; n < 2; ++n) _Pragma("unroll") for (int k = 0; k < 2; ++k) dst[n][k] = *(const LAS bf16x8*)(lds + PG8_SB(b, h) + boff + n * 2048 + k * 1024); } while (0)
; #define PG8_MMA(ai, bj, At, Bt) do { __builtin_amdgcn_s_setprio(1); _Pragma("unroll") for (int m = 0; m < 4; ++m) _Pragma("unroll") for (int n = 0; n < 2; ++n) _Pragma("unroll") for (int k = 0; k < 2; ++k) \
;         acc[ai][bj][m][n] = __builtin_amdgcn_mfma_f32_16x16x32_bf16(Bt[n][k], At[m][k], acc[ai][bj][m][n], 0, 0, 0); __builtin_amdgcn_s_setprio(0); } while (0)
; #define PG8_WAIT_V(n) asm volatile("s_waitcnt vmcnt(" #n ")" ::: "memory")
; #define PG8_WAIT_L(n) asm volatile("s_waitcnt lgkmcnt(" #n ")" ::: "memory")
; #define PG8_BAR __builtin_amdgcn_s_barrier()
; #define PG8_SCHED __builtin_amdgcn_sched_barrier(0)
; template <class Epi>
; __device__ __forceinline__ void gemm_phase(LAS unsigned char* lds, const Gemm g, const StaticOrder& S, const Epi& E, const int tid) {
;     ...
;             PG8_STAGE(PG8_SB(0, 1), b2 + hstep, voffB);
;             PG8_WAIT_V(6); PG8_BAR; PG8_MMA(1, 1, At, B1); PG8_BAR;
;             PG8_LDB(B0, 1, 0); PG8_SCHED; PG8_LDA(At, 1, 0); PG8_STAGE(PG8_SA(0, 1), a2 + hstep, voffA);
;             PG8_WAIT_L(8); PG8_BAR; PG8_WAIT_L(0); PG8_MMA(0, 0, At, B0); PG8_BAR; PG8_SCHED;
;             PG8_LDB(B1, 1, 1); PG8_STAGE(PG8_SB(1, 0), b3, voffB);
;             PG8_BAR; PG8_WAIT_L(0); PG8_MMA(0, 1, At, B1); PG8_BAR;
	s_add_u32 s48, s18, 0x80000
	s_addc_u32 s49, s19, 0
	s_add_i32 s45, s47, s26
	v_lshl_add_u64 v[160:161], s[48:49], 0, v[0:1]
	s_mov_b32 m0, s45
	s_nop 0
	global_load_lds_dwordx4 v[160:161], off
	v_lshl_add_u64 v[160:161], s[48:49], 0, v[134:135]
	s_add_i32 m0, s45, 0x2000
	s_nop 0
	global_load_lds_dwordx4 v[160:161], off
	s_waitcnt vmcnt(6)
	s_barrier
	s_setprio 1
	v_mfma_f32_16x16x32_bf16 v[54:57], v[218:221], v[176:179], v[54:57]
	v_mfma_f32_16x16x32_bf16 v[50:53], v[226:229], v[176:179], v[50:53]
	v_mfma_f32_16x16x32_bf16 v[38:41], v[218:221], v[184:187], v[38:41]
	v_mfma_f32_16x16x32_bf16 v[34:37], v[226:229], v[184:187], v[34:37]
	v_mfma_f32_16x16x32_bf16 v[22:25], v[218:221], v[192:195], v[22:25]
	v_mfma_f32_16x16x32_bf16 v[18:21], v[226:229], v[192:195], v[18:21]
	v_mfma_f32_16x16x32_bf16 v[6:9], v[218:221], v[210:213], v[6:9]
	v_mfma_f32_16x16x32_bf16 v[2:5], v[226:229], v[210:213], v[2:5]
	v_mfma_f32_16x16x32_bf16 v[54:57], v[222:225], v[180:183], v[54:57]
	v_mfma_f32_16x16x32_bf16 v[50:53], v[230:233], v[180:183], v[50:53]
	v_mfma_f32_16x16x32_bf16 v[38:41], v[222:225], v[188:191], v[38:41]
	v_mfma_f32_16x16x32_bf16 v[34:37], v[230:233], v[188:191], v[34:37]
	v_mfma_f32_16x16x32_bf16 v[22:25], v[222:225], v[196:199], v[22:25]
	v_mfma_f32_16x16x32_bf16 v[18:21], v[230:233], v[196:199], v[18:21]
	v_mfma_f32_16x16x32_bf16 v[6:9], v[222:225], v[214:217], v[6:9]
	v_mfma_f32_16x16x32_bf16 v[2:5], v[230:233], v[214:217], v[2:5]
	s_setprio 0
	s_add_i32 s45, 0, 0x18000
	v_add_u32_e32 v159, s45, v144
	s_barrier
	ds_read_b128 v[160:163], v159
	ds_read_b128 v[164:167], v159 offset:1024
	ds_read_b128 v[168:171], v159 offset:2048
	ds_read_b128 v[172:175], v159 offset:3072
	s_add_u32 s20, s20, 0x80000
	s_addc_u32 s21, s21, 0
	s_mov_b32 m0, s28
	v_lshl_add_u64 v[218:219], s[20:21], 0, v[130:131]
	ds_read_b128 v[176:179], v145 offset:32768
	ds_read_b128 v[180:183], v145 offset:33792
	ds_read_b128 v[184:187], v145 offset:34816
	ds_read_b128 v[188:191], v145 offset:35840
	ds_read_b128 v[192:195], v145 offset:36864
	ds_read_b128 v[196:199], v145 offset:37888
	ds_read_b128 v[210:213], v145 offset:38912
	ds_read_b128 v[214:217], v145 offset:39936
	global_load_lds_dwordx4 v[218:219], off
	v_lshl_add_u64 v[218:219], s[20:21], 0, v[132:133]
	s_mov_b32 m0, s29
	s_nop 0
	global_load_lds_dwordx4 v[218:219], off
	s_waitcnt lgkmcnt(8)
	s_barrier
	s_waitcnt lgkmcnt(0)
	s_setprio 1
	v_mfma_f32_16x16x32_bf16 v[126:129], v[160:163], v[176:179], v[126:129]
	v_mfma_f32_16x16x32_bf16 v[122:125], v[168:171], v[176:179], v[122:125]
	v_mfma_f32_16x16x32_bf16 v[110:113], v[160:163], v[184:187], v[110:113]
	v_mfma_f32_16x16x32_bf16 v[106:109], v[168:171], v[184:187], v[106:109]
	v_mfma_f32_16x16x32_bf16 v[94:97], v[160:163], v[192:195], v[94:97]
	v_mfma_f32_16x16x32_bf16 v[90:93], v[168:171], v[192:195], v[90:93]
	v_mfma_f32_16x16x32_bf16 v[78:81], v[160:163], v[210:213], v[78:81]
	v_mfma_f32_16x16x32_bf16 v[74:77], v[168:171], v[210:213], v[74:77]
	v_mfma_f32_16x16x32_bf16 v[126:129], v[164:167], v[180:183], v[126:129]
	v_mfma_f32_16x16x32_bf16 v[122:125], v[172:175], v[180:183], v[122:125]
	v_mfma_f32_16x16x32_bf16 v[110:113], v[164:167], v[188:191], v[110:113]
	v_mfma_f32_16x16x32_bf16 v[106:109], v[172:175], v[188:191], v[106:109]
	v_mfma_f32_16x16x32_bf16 v[94:97], v[164:167], v[196:199], v[94:97]
	v_mfma_f32_16x16x32_bf16 v[90:93], v[172:175], v[196:199], v[90:93]
	v_mfma_f32_16x16x32_bf16 v[78:81], v[164:167], v[214:217], v[78:81]
	v_mfma_f32_16x16x32_bf16 v[74:77], v[172:175], v[214:217], v[74:77]
	s_setprio 0
	s_barrier
	s_add_i32 s20, 0, 0x1c000
	s_add_i32 s21, s45, s26
	v_add_u32_e32 v159, s20, v144
	v_lshl_add_u64 v[140:141], v[140:141], 0, s[56:57]
	s_mov_b32 m0, s21
	ds_read_b128 v[218:221], v159
	ds_read_b128 v[222:225], v159 offset:1024
	ds_read_b128 v[226:229], v159 offset:2048
	ds_read_b128 v[230:233], v159 offset:3072
	global_load_lds_dwordx4 v[140:141], off
	v_lshl_add_u64 v[140:141], v[200:201], 0, s[56:57]
	s_add_i32 m0, s21, 0x2000
	s_nop 0
	global_load_lds_dwordx4 v[140:141], off
	s_barrier
	s_waitcnt lgkmcnt(0)
	s_setprio 1
	v_mfma_f32_16x16x32_bf16 v[118:121], v[218:221], v[176:179], v[118:121]
	v_mfma_f32_16x16x32_bf16 v[114:117], v[226:229], v[176:179], v[114:117]
	v_mfma_f32_16x16x32_bf16 v[102:105], v[218:221], v[184:187], v[102:105]
	v_mfma_f32_16x16x32_bf16 v[98:101], v[226:229], v[184:187], v[98:101]
	v_mfma_f32_16x16x32_bf16 v[86:89], v[218:221], v[192:195], v[86:89]
	v_mfma_f32_16x16x32_bf16 v[82:85], v[226:229], v[192:195], v[82:85]
	v_mfma_f32_16x16x32_bf16 v[70:73], v[218:221], v[210:213], v[70:73]
	v_mfma_f32_16x16x32_bf16 v[66:69], v[226:229], v[210:213], v[66:69]
	v_mfma_f32_16x16x32_bf16 v[118:121], v[222:225], v[180:183], v[118:121]
	v_mfma_f32_16x16x32_bf16 v[114:117], v[230:233], v[180:183], v[114:117]
	v_mfma_f32_16x16x32_bf16 v[102:105], v[222:225], v[188:191], v[102:105]
	v_mfma_f32_16x16x32_bf16 v[98:101], v[230:233], v[188:191], v[98:101]
	v_mfma_f32_16x16x32_bf16 v[86:89], v[222:225], v[196:199], v[86:89]
	v_mfma_f32_16x16x32_bf16 v[82:85], v[230:233], v[196:199], v[82:85]
	v_mfma_f32_16x16x32_bf16 v[70:73], v[222:225], v[214:217], v[70:73]
	v_mfma_f32_16x16x32_bf16 v[66:69], v[230:233], v[214:217], v[66:69]
	s_setprio 0
	s_mov_b32 m0, s35
	v_lshl_add_u64 v[140:141], v[234:235], 0, s[56:57]
	s_barrier
	ds_read_b128 v[176:179], v145 offset:49152
	ds_read_b128 v[180:183], v145 offset:50176
	ds_read_b128 v[184:187], v145 offset:51200
	ds_read_b128 v[188:191], v145 offset:52224
	ds_read_b128 v[192:195], v145 offset:53248
	ds_read_b128 v[196:199], v145 offset:54272
	ds_read_b128 v[210:213], v145 offset:55296
	ds_read_b128 v[214:217], v145 offset:56320
	global_load_lds_dwordx4 v[140:141], off
	v_lshl_add_u64 v[140:141], v[236:237], 0, s[56:57]
	s_mov_b32 m0, s36
	s_nop 0
	global_load_lds_dwordx4 v[140:141], off
	s_barrier
; __device__ __forceinline__ unsigned pk2(float lo, float hi) { f32x2 v = {lo, hi}; return __builtin_bit_cast(unsigned, __builtin_convertvector(v, bf16x2_t)); }
; #define PG8_STAGE(bufoff, gbase, voff) do { _Pragma("unroll") for (int _i = 0; _i < 2; ++_i) \
;         __builtin_amdgcn_global_load_lds((const unsigned*)((const char*)(gbase) + (voff)[_i]), (LAS unsigned*)(lds + (bufoff) + ldsw + _i * 8192), 16, 0, 0); } while (0)
; #define PG8_LDA(dst, b, h) do { _Pragma("unroll") for (int m = 0; m < 4; ++m) _Pragma("unroll") for (int k = 0; k < 2; ++k) dst[m][k] = *(const LAS bf16x8*)(lds + PG8_SA(b, h) + aoff + m * 2048 + k * 1024); } while (0)
; #define PG8_WAIT_V(n) asm volatile("s_waitcnt vmcnt(" #n ")" ::: "memory")
; #define PG8_WAIT_L(n) asm volatile("s_waitcnt lgkmcnt(" #n ")" ::: "memory")
; #define PG8_BAR __builtin_amdgcn_s_barrier()
; #define PG8_SCHED __builtin_amdgcn_sched_barrier(0)
;     __device__ __forceinline__ void operator()(const f32x4 (&acc)[2][2][4][2], const Unit& u, int wr, int wc, int fr, int fq) const {
;     ...
;         const int row0 = u.pm * BM + wr * 64 + fr, col0 = u.pn * BM + wc * 32 + 8 * fq;
; #pragma unroll
;         for (int ai = 0; ai < 2; ++ai)
; #pragma unroll
;             for (int m = 0; m < 4; ++m) {
;                 bf16_t* rowp = O + (size_t)(row0 + ai * HALF + m * 16) * ldc + col0;
; #pragma unroll
;                 for (int bj = 0; bj < 2; ++bj) {
;                     f32x4 v0 = acc[ai][bj][m][0], v1 = acc[ai][bj][m][1];
; #pragma unroll
;                     for (int j = 0; j < 4; ++j) { const float a = fmaxf(v0[j], 0.f), b = fmaxf(v1[j], 0.f); v0[j] = a * a; v1[j] = b * b; }
;                     u32x4 w; w.x = pk2(v0[0], v0[1]); w.y = pk2(v0[2], v0[3]); w.z = pk2(v1[0], v1[1]); w.w = pk2(v1[2], v1[3]);
;                     *(u32x4*)(rowp + bj * HALF) = w;
;                 }
; template <class Epi>
; __device__ __forceinline__ void gemm_phase(LAS unsigned char* lds, const Gemm g, const StaticOrder& S, const Epi& E, const int tid) {
;     ...
;             PG8_LDA(At, 1, 1); PG8_STAGE(PG8_SA(1, 0), a3, voffA);
;             PG8_BAR; PG8_WAIT_L(0); PG8_MMA(1, 0, At, B0); PG8_BAR; PG8_SCHED;
;             PG8_STAGE(PG8_SB(1, 1), b3 + hstep, voffB);
;             PG8_WAIT_V(6); PG8_BAR; PG8_MMA(1, 1, At, B1); PG8_BAR;
	s_waitcnt lgkmcnt(0)
	s_setprio 1
	v_mfma_f32_16x16x32_bf16 v[62:65], v[160:163], v[176:179], v[62:65]
	v_mfma_f32_16x16x32_bf16 v[58:61], v[168:171], v[176:179], v[58:61]
	v_mfma_f32_16x16x32_bf16 v[46:49], v[160:163], v[184:187], v[46:49]
	v_mfma_f32_16x16x32_bf16 v[42:45], v[168:171], v[184:187], v[42:45]
	v_mfma_f32_16x16x32_bf16 v[30:33], v[160:163], v[192:195], v[30:33]
	v_mfma_f32_16x16x32_bf16 v[26:29], v[168:171], v[192:195], v[26:29]
	v_mfma_f32_16x16x32_bf16 v[14:17], v[160:163], v[210:213], v[14:17]
	v_mfma_f32_16x16x32_bf16 v[10:13], v[168:171], v[210:213], v[10:13]
	v_mfma_f32_16x16x32_bf16 v[62:65], v[164:167], v[180:183], v[62:65]
	v_mfma_f32_16x16x32_bf16 v[58:61], v[172:175], v[180:183], v[58:61]
	v_mfma_f32_16x16x32_bf16 v[46:49], v[164:167], v[188:191], v[46:49]
	v_mfma_f32_16x16x32_bf16 v[42:45], v[172:175], v[188:191], v[42:45]
	v_mfma_f32_16x16x32_bf16 v[30:33], v[164:167], v[196:199], v[30:33]
	v_mfma_f32_16x16x32_bf16 v[26:29], v[172:175], v[196:199], v[26:29]
	v_mfma_f32_16x16x32_bf16 v[14:17], v[164:167], v[214:217], v[14:17]
	v_mfma_f32_16x16x32_bf16 v[10:13], v[172:175], v[214:217], v[10:13]
	s_setprio 0
	s_barrier
	s_add_u32 s18, s18, 0x80080
	s_addc_u32 s19, s19, 0
	s_add_i32 s20, s20, s26
	v_lshl_add_u64 v[140:141], s[18:19], 0, v[0:1]
	s_mov_b32 m0, s20
	s_nop 0
	global_load_lds_dwordx4 v[140:141], off
	v_lshl_add_u64 v[140:141], s[18:19], 0, v[134:135]
	s_add_i32 m0, s20, 0x2000
	s_nop 0
	global_load_lds_dwordx4 v[140:141], off
	s_waitcnt vmcnt(6)
	s_barrier
	s_setprio 1
	v_mfma_f32_16x16x32_bf16 v[54:57], v[218:221], v[176:179], v[54:57]
	v_mfma_f32_16x16x32_bf16 v[50:53], v[226:229], v[176:179], v[50:53]
	v_mfma_f32_16x16x32_bf16 v[38:41], v[218:221], v[184:187], v[38:41]
	v_mfma_f32_16x16x32_bf16 v[34:37], v[226:229], v[184:187], v[34:37]
	v_mfma_f32_16x16x32_bf16 v[22:25], v[218:221], v[192:195], v[22:25]
	v_mfma_f32_16x16x32_bf16 v[18:21], v[226:229], v[192:195], v[18:21]
	v_mfma_f32_16x16x32_bf16 v[6:9], v[218:221], v[210:213], v[6:9]
	v_mfma_f32_16x16x32_bf16 v[2:5], v[226:229], v[210:213], v[2:5]
	v_mfma_f32_16x16x32_bf16 v[54:57], v[222:225], v[180:183], v[54:57]
	v_mfma_f32_16x16x32_bf16 v[50:53], v[230:233], v[180:183], v[50:53]
	v_mfma_f32_16x16x32_bf16 v[38:41], v[222:225], v[188:191], v[38:41]
	v_mfma_f32_16x16x32_bf16 v[34:37], v[230:233], v[188:191], v[34:37]
	v_mfma_f32_16x16x32_bf16 v[22:25], v[222:225], v[196:199], v[22:25]
	v_mfma_f32_16x16x32_bf16 v[18:21], v[230:233], v[196:199], v[18:21]
	v_mfma_f32_16x16x32_bf16 v[6:9], v[222:225], v[214:217], v[6:9]
	v_mfma_f32_16x16x32_bf16 v[2:5], v[230:233], v[214:217], v[2:5]
	s_setprio 0
	s_add_i32 s44, s44, 2
	s_add_u32 s42, s42, 0x100
	s_addc_u32 s43, s43, 0
	s_add_u32 s16, s16, 0x100
	s_addc_u32 s17, s17, 0
	s_cmp_gt_u32 s44, 29
	s_barrier
	s_cbranch_scc0 .LBB0_84
	v_mov_b32_e32 v141, v143
	v_mov_b32_e32 v140, v142
	s_lshl_b32 s7, s14, 8
	s_add_i32 s7, s7, s31
	v_add_u32_e32 v140, s7, v140
	s_lshl_b32 s7, s39, 8
	s_or_b32 s7, s7, s34
	v_lshl_add_u32 v160, v141, 3, s7
	v_ashrrev_i32_e32 v141, 31, v140
	v_lshlrev_b64 v[140:141], 14, v[140:141]
	v_max_f32_e32 v122, v122, v122
	v_max_f32_e32 v123, v123, v123
	v_ashrrev_i32_e32 v161, 31, v160
	v_lshl_add_u64 v[140:141], s[2:3], 0, v[140:141]
	v_max_f32_e32 v122, 0, v122
	v_max_f32_e32 v123, 0, v123
	v_lshl_add_u64 v[140:141], v[160:161], 1, v[140:141]
	v_pk_mul_f32 v[160:161], v[122:123], v[122:123]
	v_max_f32_e32 v123, v124, v124
	v_max_f32_e32 v126, v126, v126
	v_max_f32_e32 v127, v127, v127
	v_max_f32_e32 v122, v128, v128
	v_max_f32_e32 v124, 0, v123
	v_max_f32_e32 v123, v129, v129
	v_max_f32_e32 v125, v125, v125
	v_max_f32_e32 v126, 0, v126
	v_max_f32_e32 v127, 0, v127
	v_max_f32_e32 v122, 0, v122
	v_max_f32_e32 v123, 0, v123
	v_max_f32_e32 v125, 0, v125
	v_pk_mul_f32 v[126:127], v[126:127], v[126:127]
	v_pk_mul_f32 v[128:129], v[122:123], v[122:123]
	v_pk_mul_f32 v[162:163], v[124:125], v[124:125]
	v_max_f32_e32 v114, v114, v114
	v_max_f32_e32 v115, v115, v115
	v_cvt_pk_bf16_f32 v122, v126, v127
	v_cvt_pk_bf16_f32 v123, v128, v129
	v_cvt_pk_bf16_f32 v124, v160, v161
	v_cvt_pk_bf16_f32 v125, v162, v163
	v_max_f32_e32 v114, 0, v114
	v_max_f32_e32 v115, 0, v115
	global_store_dwordx4 v[140:141], v[122:125], off
	v_max_f32_e32 v118, v118, v118
	v_max_f32_e32 v119, v119, v119
	v_pk_mul_f32 v[122:123], v[114:115], v[114:115]
	v_max_f32_e32 v115, v116, v116
	v_max_f32_e32 v114, v120, v120
	v_max_f32_e32 v116, 0, v115
	v_max_f32_e32 v115, v121, v121
	v_max_f32_e32 v117, v117, v117
	v_max_f32_e32 v118, 0, v118
	v_max_f32_e32 v119, 0, v119
	v_max_f32_e32 v114, 0, v114
	v_max_f32_e32 v115, 0, v115
	v_max_f32_e32 v117, 0, v117
	v_pk_mul_f32 v[118:119], v[118:119], v[118:119]
	v_pk_mul_f32 v[120:121], v[114:115], v[114:115]
	v_pk_mul_f32 v[124:125], v[116:117], v[116:117]
	v_max_f32_e32 v106, v106, v106
	v_max_f32_e32 v107, v107, v107
	v_cvt_pk_bf16_f32 v114, v118, v119
	v_cvt_pk_bf16_f32 v115, v120, v121
	v_cvt_pk_bf16_f32 v116, v122, v123
	v_cvt_pk_bf16_f32 v117, v124, v125
	v_max_f32_e32 v106, 0, v106
	v_max_f32_e32 v107, 0, v107
	global_store_dwordx4 v[140:141], v[114:117], off offset:256
	v_max_f32_e32 v110, v110, v110
	v_max_f32_e32 v111, v111, v111
	v_pk_mul_f32 v[116:117], v[106:107], v[106:107]
	v_max_f32_e32 v107, v108, v108
	v_max_f32_e32 v110, 0, v110
	v_max_f32_e32 v111, 0, v111
	v_max_f32_e32 v106, v112, v112
	v_max_f32_e32 v108, 0, v107
	v_max_f32_e32 v107, v113, v113
	v_max_f32_e32 v109, v109, v109
	v_pk_mul_f32 v[110:111], v[110:111], v[110:111]
	v_max_f32_e32 v106, 0, v106
	v_max_f32_e32 v107, 0, v107
	v_max_f32_e32 v109, 0, v109
	s_mov_b32 s7, 0x40000
	v_pk_mul_f32 v[112:113], v[106:107], v[106:107]
; __device__ __forceinline__ unsigned pk2(float lo, float hi) { f32x2 v = {lo, hi}; return __builtin_bit_cast(unsigned, __builtin_convertvector(v, bf16x2_t)); }
;     __device__ __forceinline__ void operator()(const f32x4 (&acc)[2][2][4][2], const Unit& u, int wr, int wc, int fr, int fq) const {
;     ...
;         for (int ai = 0; ai < 2; ++ai)
; #pragma unroll
;             for (int m = 0; m < 4; ++m) {
;                 bf16_t* rowp = O + (size_t)(row0 + ai * HALF + m * 16) * ldc + col0;
; #pragma unroll
;                 for (int bj = 0; bj < 2; ++bj) {
;                     f32x4 v0 = acc[ai][bj][m][0], v1 = acc[ai][bj][m][1];
; #pragma unroll
;                     for (int j = 0; j < 4; ++j) { const float a = fmaxf(v0[j], 0.f), b = fmaxf(v1[j], 0.f); v0[j] = a * a; v1[j] = b * b; }
;                     u32x4 w; w.x = pk2(v0[0], v0[1]); w.y = pk2(v0[2], v0[3]); w.z = pk2(v1[0], v1[1]); w.w = pk2(v1[2], v1[3]);
;                     *(u32x4*)(rowp + bj * HALF) = w;
;                 }
	v_pk_mul_f32 v[118:119], v[108:109], v[108:109]
	v_cvt_pk_bf16_f32 v106, v110, v111
	v_add_co_u32_e32 v110, vcc, s7, v140
	v_max_f32_e32 v98, v98, v98
	v_max_f32_e32 v99, v99, v99
	v_cvt_pk_bf16_f32 v107, v112, v113
	v_cvt_pk_bf16_f32 v108, v116, v117
	v_cvt_pk_bf16_f32 v109, v118, v119
	v_addc_co_u32_e32 v111, vcc, 0, v141, vcc
	v_max_f32_e32 v98, 0, v98
	v_max_f32_e32 v99, 0, v99
	global_store_dwordx4 v[110:111], v[106:109], off
	v_max_f32_e32 v102, v102, v102
	v_max_f32_e32 v103, v103, v103
	v_pk_mul_f32 v[106:107], v[98:99], v[98:99]
	v_max_f32_e32 v99, v100, v100
	v_max_f32_e32 v98, v104, v104
	v_max_f32_e32 v100, 0, v99
	v_max_f32_e32 v99, v105, v105
	v_max_f32_e32 v101, v101, v101
	v_max_f32_e32 v102, 0, v102
	v_max_f32_e32 v103, 0, v103
	v_max_f32_e32 v98, 0, v98
	v_max_f32_e32 v99, 0, v99
	v_max_f32_e32 v101, 0, v101
	s_mov_b64 s[16:17], 0x40000
	v_pk_mul_f32 v[102:103], v[102:103], v[102:103]
	v_pk_mul_f32 v[104:105], v[98:99], v[98:99]
	v_pk_mul_f32 v[108:109], v[100:101], v[100:101]
	v_max_f32_e32 v90, v90, v90
	v_max_f32_e32 v91, v91, v91
	v_lshl_add_u64 v[114:115], v[140:141], 0, s[16:17]
	v_cvt_pk_bf16_f32 v98, v102, v103
	v_cvt_pk_bf16_f32 v99, v104, v105
	v_cvt_pk_bf16_f32 v100, v106, v107
	v_cvt_pk_bf16_f32 v101, v108, v109
	v_max_f32_e32 v90, 0, v90
	v_max_f32_e32 v91, 0, v91
	global_store_dwordx4 v[114:115], v[98:101], off offset:256
	v_max_f32_e32 v94, v94, v94
	v_max_f32_e32 v95, v95, v95
	v_pk_mul_f32 v[100:101], v[90:91], v[90:91]
	v_max_f32_e32 v91, v92, v92
	v_max_f32_e32 v94, 0, v94
	v_max_f32_e32 v95, 0, v95
	v_max_f32_e32 v90, v96, v96
	v_max_f32_e32 v92, 0, v91
	v_max_f32_e32 v91, v97, v97
	v_max_f32_e32 v93, v93, v93
	v_pk_mul_f32 v[94:95], v[94:95], v[94:95]
	v_max_f32_e32 v90, 0, v90
	v_max_f32_e32 v91, 0, v91
	v_max_f32_e32 v93, 0, v93
	s_mov_b32 s7, 0x80000
	v_pk_mul_f32 v[96:97], v[90:91], v[90:91]
	v_pk_mul_f32 v[102:103], v[92:93], v[92:93]
	v_cvt_pk_bf16_f32 v90, v94, v95
	v_add_co_u32_e32 v94, vcc, s7, v140
	v_max_f32_e32 v82, v82, v82
	v_max_f32_e32 v83, v83, v83
	v_cvt_pk_bf16_f32 v91, v96, v97
	v_cvt_pk_bf16_f32 v92, v100, v101
	v_cvt_pk_bf16_f32 v93, v102, v103
	v_addc_co_u32_e32 v95, vcc, 0, v141, vcc
	v_max_f32_e32 v82, 0, v82
	v_max_f32_e32 v83, 0, v83
	global_store_dwordx4 v[94:95], v[90:93], off
	v_max_f32_e32 v86, v86, v86
	v_max_f32_e32 v87, v87, v87
	v_pk_mul_f32 v[90:91], v[82:83], v[82:83]
	v_max_f32_e32 v83, v84, v84
	v_max_f32_e32 v82, v88, v88
	v_max_f32_e32 v84, 0, v83
	v_max_f32_e32 v83, v89, v89
	v_max_f32_e32 v85, v85, v85
	v_max_f32_e32 v86, 0, v86
	v_max_f32_e32 v87, 0, v87
	v_max_f32_e32 v82, 0, v82
	v_max_f32_e32 v83, 0, v83
	v_max_f32_e32 v85, 0, v85
	s_mov_b64 s[16:17], 0x80000
	v_pk_mul_f32 v[86:87], v[86:87], v[86:87]
	v_pk_mul_f32 v[88:89], v[82:83], v[82:83]
	v_pk_mul_f32 v[92:93], v[84:85], v[84:85]
	v_max_f32_e32 v74, v74, v74
	v_max_f32_e32 v75, v75, v75
	v_lshl_add_u64 v[98:99], v[140:141], 0, s[16:17]
	v_cvt_pk_bf16_f32 v82, v86, v87
	v_cvt_pk_bf16_f32 v83, v88, v89
	v_cvt_pk_bf16_f32 v84, v90, v91
	v_cvt_pk_bf16_f32 v85, v92, v93
	v_max_f32_e32 v74, 0, v74
	v_max_f32_e32 v75, 0, v75
	global_store_dwordx4 v[98:99], v[82:85], off offset:256
	v_max_f32_e32 v78, v78, v78
	v_max_f32_e32 v79, v79, v79
	v_pk_mul_f32 v[84:85], v[74:75], v[74:75]
	v_max_f32_e32 v75, v76, v76
	v_max_f32_e32 v78, 0, v78
	v_max_f32_e32 v79, 0, v79
	v_max_f32_e32 v74, v80, v80
	v_max_f32_e32 v76, 0, v75
	v_max_f32_e32 v75, v81, v81
	v_max_f32_e32 v77, v77, v77
	v_pk_mul_f32 v[78:79], v[78:79], v[78:79]
	v_max_f32_e32 v74, 0, v74
	v_max_f32_e32 v75, 0, v75
	v_max_f32_e32 v77, 0, v77
	s_mov_b32 s7, 0xc0000
	v_pk_mul_f32 v[80:81], v[74:75], v[74:75]
	v_pk_mul_f32 v[86:87], v[76:77], v[76:77]
	v_cvt_pk_bf16_f32 v74, v78, v79
	v_add_co_u32_e32 v78, vcc, s7, v140
	v_max_f32_e32 v66, v66, v66
	v_max_f32_e32 v67, v67, v67
	v_cvt_pk_bf16_f32 v75, v80, v81
	v_cvt_pk_bf16_f32 v76, v84, v85
	v_cvt_pk_bf16_f32 v77, v86, v87
	v_addc_co_u32_e32 v79, vcc, 0, v141, vcc
	v_max_f32_e32 v66, 0, v66
	v_max_f32_e32 v67, 0, v67
	global_store_dwordx4 v[78:79], v[74:77], off
	v_max_f32_e32 v70, v70, v70
	v_max_f32_e32 v71, v71, v71
	v_pk_mul_f32 v[74:75], v[66:67], v[66:67]
	v_max_f32_e32 v67, v68, v68
	v_max_f32_e32 v66, v72, v72
	v_max_f32_e32 v68, 0, v67
	v_max_f32_e32 v67, v73, v73
	v_max_f32_e32 v69, v69, v69
	v_max_f32_e32 v70, 0, v70
	v_max_f32_e32 v71, 0, v71
	v_max_f32_e32 v66, 0, v66
	v_max_f32_e32 v67, 0, v67
	v_max_f32_e32 v69, 0, v69
	s_mov_b64 s[16:17], 0xc0000
	v_pk_mul_f32 v[70:71], v[70:71], v[70:71]
	v_pk_mul_f32 v[72:73], v[66:67], v[66:67]
	v_pk_mul_f32 v[76:77], v[68:69], v[68:69]
	v_max_f32_e32 v58, v58, v58
	v_max_f32_e32 v59, v59, v59
	v_lshl_add_u64 v[82:83], v[140:141], 0, s[16:17]
	v_cvt_pk_bf16_f32 v66, v70, v71
	v_cvt_pk_bf16_f32 v67, v72, v73
	v_cvt_pk_bf16_f32 v68, v74, v75
	v_cvt_pk_bf16_f32 v69, v76, v77
	v_max_f32_e32 v58, 0, v58
	v_max_f32_e32 v59, 0, v59
	global_store_dwordx4 v[82:83], v[66:69], off offset:256
	v_max_f32_e32 v62, v62, v62
	v_max_f32_e32 v63, v63, v63
	v_pk_mul_f32 v[68:69], v[58:59], v[58:59]
	v_max_f32_e32 v59, v60, v60
	v_max_f32_e32 v62, 0, v62
	v_max_f32_e32 v63, 0, v63
	v_max_f32_e32 v58, v64, v64
	v_max_f32_e32 v60, 0, v59
	v_max_f32_e32 v59, v65, v65
	v_max_f32_e32 v61, v61, v61
	v_pk_mul_f32 v[62:63], v[62:63], v[62:63]
	v_max_f32_e32 v58, 0, v58
	v_max_f32_e32 v59, 0, v59
	v_max_f32_e32 v61, 0, v61
	s_mov_b32 s7, 0x200000
	v_pk_mul_f32 v[64:65], v[58:59], v[58:59]
	v_pk_mul_f32 v[70:71], v[60:61], v[60:61]
	v_cvt_pk_bf16_f32 v58, v62, v63
	v_add_co_u32_e32 v62, vcc, s7, v140
	v_max_f32_e32 v50, v50, v50
	v_max_f32_e32 v51, v51, v51
	v_cvt_pk_bf16_f32 v59, v64, v65
; __device__ __forceinline__ unsigned pk2(float lo, float hi) { f32x2 v = {lo, hi}; return __builtin_bit_cast(unsigned, __builtin_convertvector(v, bf16x2_t)); }
; #define PG8_WAIT_V(n) asm volatile("s_waitcnt vmcnt(" #n ")" ::: "memory")
; #define PG8_BAR __builtin_amdgcn_s_barrier()
;     __device__ __forceinline__ void operator()(const f32x4 (&acc)[2][2][4][2], const Unit& u, int wr, int wc, int fr, int fq) const {
;     ...
;         for (int ai = 0; ai < 2; ++ai)
; #pragma unroll
;             for (int m = 0; m < 4; ++m) {
;                 bf16_t* rowp = O + (size_t)(row0 + ai * HALF + m * 16) * ldc + col0;
; #pragma unroll
;                 for (int bj = 0; bj < 2; ++bj) {
;                     f32x4 v0 = acc[ai][bj][m][0], v1 = acc[ai][bj][m][1];
; #pragma unroll
;                     for (int j = 0; j < 4; ++j) { const float a = fmaxf(v0[j], 0.f), b = fmaxf(v1[j], 0.f); v0[j] = a * a; v1[j] = b * b; }
;                     u32x4 w; w.x = pk2(v0[0], v0[1]); w.y = pk2(v0[2], v0[3]); w.z = pk2(v1[0], v1[1]); w.w = pk2(v1[2], v1[3]);
;                     *(u32x4*)(rowp + bj * HALF) = w;
;                 }
; template <class Epi>
; __device__ __forceinline__ void gemm_phase(LAS unsigned char* lds, const Gemm g, const StaticOrder& S, const Epi& E, const int tid) {
;     ...
;         if (!has_next) break;
; #pragma unroll
;         for (int a = 0; a < 2; ++a)
; #pragma unroll
;             for (int b = 0; b < 2; ++b)
; #pragma unroll
;                 for (int m = 0; m < 4; ++m)
; #pragma unroll
;                     for (int n = 0; n < 2; ++n) acc[a][b][m][n] = (f32x4){0.f, 0.f, 0.f, 0.f};
;         cur = nxt; cA = nA; cB = nB; ++ui;
;     }
;     PG8_WAIT_V(0);
;     if (wr == 0) PG8_BAR;
;     PG8_BAR;
	v_cvt_pk_bf16_f32 v60, v68, v69
	v_cvt_pk_bf16_f32 v61, v70, v71
	v_addc_co_u32_e32 v63, vcc, 0, v141, vcc
	v_max_f32_e32 v50, 0, v50
	v_max_f32_e32 v51, 0, v51
	global_store_dwordx4 v[62:63], v[58:61], off
	v_max_f32_e32 v54, v54, v54
	v_max_f32_e32 v55, v55, v55
	v_pk_mul_f32 v[58:59], v[50:51], v[50:51]
	v_max_f32_e32 v51, v52, v52
	v_max_f32_e32 v50, v56, v56
	v_max_f32_e32 v52, 0, v51
	v_max_f32_e32 v51, v57, v57
	v_max_f32_e32 v53, v53, v53
	v_max_f32_e32 v54, 0, v54
	v_max_f32_e32 v55, 0, v55
	v_max_f32_e32 v50, 0, v50
	v_max_f32_e32 v51, 0, v51
	v_max_f32_e32 v53, 0, v53
	s_mov_b64 s[16:17], 0x200000
	v_pk_mul_f32 v[54:55], v[54:55], v[54:55]
	v_pk_mul_f32 v[56:57], v[50:51], v[50:51]
	v_pk_mul_f32 v[60:61], v[52:53], v[52:53]
	v_max_f32_e32 v42, v42, v42
	v_max_f32_e32 v43, v43, v43
	v_lshl_add_u64 v[66:67], v[140:141], 0, s[16:17]
	v_cvt_pk_bf16_f32 v50, v54, v55
	v_cvt_pk_bf16_f32 v51, v56, v57
	v_cvt_pk_bf16_f32 v52, v58, v59
	v_cvt_pk_bf16_f32 v53, v60, v61
	v_max_f32_e32 v42, 0, v42
	v_max_f32_e32 v43, 0, v43
	global_store_dwordx4 v[66:67], v[50:53], off offset:256
	v_max_f32_e32 v46, v46, v46
	v_max_f32_e32 v47, v47, v47
	v_pk_mul_f32 v[52:53], v[42:43], v[42:43]
	v_max_f32_e32 v43, v44, v44
	v_max_f32_e32 v46, 0, v46
	v_max_f32_e32 v47, 0, v47
	v_max_f32_e32 v42, v48, v48
	v_max_f32_e32 v44, 0, v43
	v_max_f32_e32 v43, v49, v49
	v_max_f32_e32 v45, v45, v45
	v_pk_mul_f32 v[46:47], v[46:47], v[46:47]
	v_max_f32_e32 v42, 0, v42
	v_max_f32_e32 v43, 0, v43
	v_max_f32_e32 v45, 0, v45
	s_mov_b32 s7, 0x240000
	v_pk_mul_f32 v[48:49], v[42:43], v[42:43]
	v_pk_mul_f32 v[54:55], v[44:45], v[44:45]
	v_cvt_pk_bf16_f32 v42, v46, v47
	v_add_co_u32_e32 v46, vcc, s7, v140
	v_max_f32_e32 v34, v34, v34
	v_max_f32_e32 v35, v35, v35
	v_cvt_pk_bf16_f32 v43, v48, v49
	v_cvt_pk_bf16_f32 v44, v52, v53
	v_cvt_pk_bf16_f32 v45, v54, v55
	v_addc_co_u32_e32 v47, vcc, 0, v141, vcc
	v_max_f32_e32 v34, 0, v34
	v_max_f32_e32 v35, 0, v35
	global_store_dwordx4 v[46:47], v[42:45], off
	v_max_f32_e32 v38, v38, v38
	v_max_f32_e32 v39, v39, v39
	v_pk_mul_f32 v[42:43], v[34:35], v[34:35]
	v_max_f32_e32 v35, v36, v36
	v_max_f32_e32 v34, v40, v40
	v_max_f32_e32 v36, 0, v35
	v_max_f32_e32 v35, v41, v41
	v_max_f32_e32 v37, v37, v37
	v_max_f32_e32 v38, 0, v38
	v_max_f32_e32 v39, 0, v39
	v_max_f32_e32 v34, 0, v34
	v_max_f32_e32 v35, 0, v35
	v_max_f32_e32 v37, 0, v37
	s_mov_b64 s[16:17], 0x240000
	v_pk_mul_f32 v[38:39], v[38:39], v[38:39]
	v_pk_mul_f32 v[40:41], v[34:35], v[34:35]
	v_pk_mul_f32 v[44:45], v[36:37], v[36:37]
	v_max_f32_e32 v26, v26, v26
	v_max_f32_e32 v27, v27, v27
	v_lshl_add_u64 v[50:51], v[140:141], 0, s[16:17]
	v_cvt_pk_bf16_f32 v34, v38, v39
	v_cvt_pk_bf16_f32 v35, v40, v41
	v_cvt_pk_bf16_f32 v36, v42, v43
	v_cvt_pk_bf16_f32 v37, v44, v45
	v_max_f32_e32 v26, 0, v26
	v_max_f32_e32 v27, 0, v27
	global_store_dwordx4 v[50:51], v[34:37], off offset:256
	v_max_f32_e32 v30, v30, v30
	v_max_f32_e32 v31, v31, v31
	v_pk_mul_f32 v[36:37], v[26:27], v[26:27]
	v_max_f32_e32 v27, v28, v28
	v_max_f32_e32 v30, 0, v30
	v_max_f32_e32 v31, 0, v31
	v_max_f32_e32 v26, v32, v32
	v_max_f32_e32 v28, 0, v27
	v_max_f32_e32 v27, v33, v33
	v_max_f32_e32 v29, v29, v29
	v_pk_mul_f32 v[30:31], v[30:31], v[30:31]
	v_max_f32_e32 v26, 0, v26
	v_max_f32_e32 v27, 0, v27
	v_max_f32_e32 v29, 0, v29
	s_mov_b32 s7, 0x280000
	v_pk_mul_f32 v[32:33], v[26:27], v[26:27]
	v_pk_mul_f32 v[38:39], v[28:29], v[28:29]
	v_cvt_pk_bf16_f32 v26, v30, v31
	v_add_co_u32_e32 v30, vcc, s7, v140
	v_max_f32_e32 v18, v18, v18
	v_max_f32_e32 v19, v19, v19
	v_cvt_pk_bf16_f32 v27, v32, v33
	v_cvt_pk_bf16_f32 v28, v36, v37
	v_cvt_pk_bf16_f32 v29, v38, v39
	v_addc_co_u32_e32 v31, vcc, 0, v141, vcc
	v_max_f32_e32 v18, 0, v18
	v_max_f32_e32 v19, 0, v19
	global_store_dwordx4 v[30:31], v[26:29], off
	v_max_f32_e32 v22, v22, v22
	v_max_f32_e32 v23, v23, v23
	v_pk_mul_f32 v[26:27], v[18:19], v[18:19]
	v_max_f32_e32 v19, v20, v20
	v_max_f32_e32 v18, v24, v24
	v_max_f32_e32 v20, 0, v19
	v_max_f32_e32 v19, v25, v25
	v_max_f32_e32 v21, v21, v21
	v_max_f32_e32 v22, 0, v22
	v_max_f32_e32 v23, 0, v23
	v_max_f32_e32 v18, 0, v18
	v_max_f32_e32 v19, 0, v19
	v_max_f32_e32 v21, 0, v21
	s_mov_b64 s[16:17], 0x280000
	v_pk_mul_f32 v[22:23], v[22:23], v[22:23]
	v_pk_mul_f32 v[24:25], v[18:19], v[18:19]
	v_pk_mul_f32 v[28:29], v[20:21], v[20:21]
	v_max_f32_e32 v10, v10, v10
	v_max_f32_e32 v11, v11, v11
	v_lshl_add_u64 v[34:35], v[140:141], 0, s[16:17]
	v_cvt_pk_bf16_f32 v18, v22, v23
	v_cvt_pk_bf16_f32 v19, v24, v25
	v_cvt_pk_bf16_f32 v20, v26, v27
	v_cvt_pk_bf16_f32 v21, v28, v29
	v_max_f32_e32 v10, 0, v10
	v_max_f32_e32 v11, 0, v11
	global_store_dwordx4 v[34:35], v[18:21], off offset:256
	v_max_f32_e32 v14, v14, v14
	v_max_f32_e32 v15, v15, v15
	v_pk_mul_f32 v[20:21], v[10:11], v[10:11]
	v_max_f32_e32 v11, v12, v12
	v_max_f32_e32 v14, 0, v14
	v_max_f32_e32 v15, 0, v15
	v_max_f32_e32 v10, v16, v16
	v_max_f32_e32 v12, 0, v11
	v_max_f32_e32 v11, v17, v17
	v_max_f32_e32 v13, v13, v13
	v_pk_mul_f32 v[14:15], v[14:15], v[14:15]
	v_max_f32_e32 v10, 0, v10
	v_max_f32_e32 v11, 0, v11
	v_max_f32_e32 v13, 0, v13
	s_mov_b32 s7, 0x2c0000
	v_pk_mul_f32 v[16:17], v[10:11], v[10:11]
	v_pk_mul_f32 v[22:23], v[12:13], v[12:13]
	v_cvt_pk_bf16_f32 v10, v14, v15
	v_add_co_u32_e32 v14, vcc, s7, v140
	v_max_f32_e32 v2, v2, v2
	v_max_f32_e32 v3, v3, v3
	v_cvt_pk_bf16_f32 v11, v16, v17
	v_cvt_pk_bf16_f32 v12, v20, v21
	v_cvt_pk_bf16_f32 v13, v22, v23
	v_addc_co_u32_e32 v15, vcc, 0, v141, vcc
	v_max_f32_e32 v2, 0, v2
	v_max_f32_e32 v3, 0, v3
	global_store_dwordx4 v[14:15], v[10:13], off
	v_max_f32_e32 v6, v6, v6
	v_max_f32_e32 v7, v7, v7
	v_pk_mul_f32 v[10:11], v[2:3], v[2:3]
	v_max_f32_e32 v3, v4, v4
	v_max_f32_e32 v2, v8, v8
	v_max_f32_e32 v4, 0, v3
	v_max_f32_e32 v3, v9, v9
	v_max_f32_e32 v5, v5, v5
	v_max_f32_e32 v6, 0, v6
	v_max_f32_e32 v7, 0, v7
	v_max_f32_e32 v2, 0, v2
	v_max_f32_e32 v3, 0, v3
	v_max_f32_e32 v5, 0, v5
	s_mov_b64 s[16:17], 0x2c0000
	v_pk_mul_f32 v[6:7], v[6:7], v[6:7]
	v_pk_mul_f32 v[8:9], v[2:3], v[2:3]
	v_pk_mul_f32 v[12:13], v[4:5], v[4:5]
	v_lshl_add_u64 v[18:19], v[140:141], 0, s[16:17]
	v_cvt_pk_bf16_f32 v2, v6, v7
	v_cvt_pk_bf16_f32 v3, v8, v9
	v_cvt_pk_bf16_f32 v4, v10, v11
	v_cvt_pk_bf16_f32 v5, v12, v13
	s_and_b64 vcc, exec, s[4:5]
	s_mov_b32 s39, s6
	s_mov_b32 s14, s8
	s_mov_b64 s[16:17], s[12:13]
	s_mov_b64 s[18:19], s[10:11]
	global_store_dwordx4 v[18:19], v[2:5], off offset:256
	s_cbranch_vccz .LBB0_77
	s_waitcnt vmcnt(0)
	s_cmpk_gt_u32 s0, 0xff
	s_cbranch_scc1 .LBB0_88
	s_barrier

; #define PG8_STAGE(bufoff, gbase, voff) do { _Pragma("unroll") for (int _i = 0; _i < 2; ++_i) \
;         __builtin_amdgcn_global_load_lds((const unsigned*)((const char*)(gbase) + (voff)[_i]), (LAS unsigned*)(lds + (bufoff) + ldsw + _i * 8192), 16, 0, 0); } while (0)
; #define PG8_LDA(dst, b, h) do { _Pragma("unroll") for (int m = 0; m < 4; ++m) _Pragma("unroll") for (int k = 0; k < 2; ++k) dst[m][k] = *(const LAS bf16x8*)(lds + PG8_SA(b, h) + aoff + m * 2048 + k * 1024); } while (0)
; #define PG8_LDB(dst, b, h) do { _Pragma("unroll") for (int n = 0; n < 2; ++n) _Pragma("unroll") for (int k = 0; k < 2; ++k) dst[n][k] = *(const LAS bf16x8*)(lds + PG8_SB(b, h) + boff + n * 2048 + k * 1024); } while (0)
; #define PG8_MMA(ai, bj, At, Bt) do { __builtin_amdgcn_s_setprio(1); _Pragma("unroll") for (int m = 0; m < 4; ++m) _Pragma("unroll") for (int n = 0; n < 2; ++n) _Pragma("unroll") for (int k = 0; k < 2; ++k) \
;         acc[ai][bj][m][n] = __builtin_amdgcn_mfma_f32_16x16x32_bf16(Bt[n][k], At[m][k], acc[ai][bj][m][n], 0, 0, 0); __builtin_amdgcn_s_setprio(0); } while (0)
; #define PG8_WAIT_L(n) asm volatile("s_waitcnt lgkmcnt(" #n ")" ::: "memory")
; #define PG8_BAR __builtin_amdgcn_s_barrier()
; #define PG8_SCHED __builtin_amdgcn_sched_barrier(0)
; template <class Epi>
; __device__ __forceinline__ void gemm_phase(LAS unsigned char* lds, const Gemm g, const StaticOrder& S, const Epi& E, const int tid) {
;     ...
;             PG8_LDB(B0, 0, 0); PG8_SCHED; PG8_LDA(At, 0, 0); PG8_STAGE(PG8_SA(1, 1), a1 + hstep, voffA);
;             PG8_WAIT_L(8); PG8_BAR; PG8_WAIT_L(0); PG8_MMA(0, 0, At, B0); PG8_BAR; PG8_SCHED;
;             PG8_LDB(B1, 0, 1); PG8_STAGE(PG8_SB(0, 0), b2, voffB);
;             PG8_BAR; PG8_WAIT_L(0); PG8_MMA(0, 1, At, B1); PG8_BAR;
;             PG8_LDA(At, 0, 1); PG8_STAGE(PG8_SA(0, 0), a2, voffA);
;             PG8_BAR; PG8_WAIT_L(0); PG8_MMA(1, 0, At, B0); PG8_BAR; PG8_SCHED;
.LBB0_119:
	s_add_u32 s20, s18, 0xfff80080
	s_addc_u32 s21, s19, -1
	s_add_i32 s50, 0, 0x10000
	v_add_u32_e32 v62, s50, v173
	ds_read_b128 v[42:45], v62
	ds_read_b128 v[46:49], v62 offset:1024
	ds_read_b128 v[58:61], v62 offset:2048
	ds_read_b128 v[62:65], v62 offset:3072
	s_cmp_eq_u32 s49, 28
	s_cselect_b32 s23, s13, s21
	s_cselect_b32 s22, s44, s20
	s_cselect_b32 s21, s11, s48
	s_cselect_b32 s20, s45, s47
	v_lshl_add_u64 v[170:171], s[18:19], 0, v[168:169]
	s_add_i32 m0, s3, 0xc000
	ds_read_b128 v[176:179], v174
	ds_read_b128 v[180:183], v174 offset:1024
	ds_read_b128 v[184:187], v174 offset:2048
	ds_read_b128 v[188:191], v174 offset:3072
	ds_read_b128 v[192:195], v174 offset:4096
	ds_read_b128 v[196:199], v174 offset:5120
	ds_read_b128 v[210:213], v174 offset:6144
	ds_read_b128 v[214:217], v174 offset:7168
	global_load_lds_dwordx4 v[170:171], off
	v_lshl_add_u64 v[170:171], s[18:19], 0, v[166:167]
	s_add_i32 m0, s3, 0xe000
	s_nop 0
	global_load_lds_dwordx4 v[170:171], off
	s_waitcnt lgkmcnt(8)
	s_barrier
	s_waitcnt lgkmcnt(0)
	s_setprio 1
	v_mfma_f32_16x16x32_bf16 v[142:145], v[42:45], v[176:179], v[142:145]
	v_mfma_f32_16x16x32_bf16 v[138:141], v[58:61], v[176:179], v[138:141]
	v_mfma_f32_16x16x32_bf16 v[126:129], v[42:45], v[184:187], v[126:129]
	v_mfma_f32_16x16x32_bf16 v[122:125], v[58:61], v[184:187], v[122:125]
	v_mfma_f32_16x16x32_bf16 v[110:113], v[42:45], v[192:195], v[110:113]
	v_mfma_f32_16x16x32_bf16 v[106:109], v[58:61], v[192:195], v[106:109]
	v_mfma_f32_16x16x32_bf16 v[94:97], v[42:45], v[210:213], v[94:97]
	v_mfma_f32_16x16x32_bf16 v[90:93], v[58:61], v[210:213], v[90:93]
	v_mfma_f32_16x16x32_bf16 v[142:145], v[46:49], v[180:183], v[142:145]
	v_mfma_f32_16x16x32_bf16 v[138:141], v[62:65], v[180:183], v[138:141]
	v_mfma_f32_16x16x32_bf16 v[126:129], v[46:49], v[188:191], v[126:129]
	v_mfma_f32_16x16x32_bf16 v[122:125], v[62:65], v[188:191], v[122:125]
	v_mfma_f32_16x16x32_bf16 v[110:113], v[46:49], v[196:199], v[110:113]
	v_mfma_f32_16x16x32_bf16 v[106:109], v[62:65], v[196:199], v[106:109]
	v_mfma_f32_16x16x32_bf16 v[94:97], v[46:49], v[214:217], v[94:97]
	v_mfma_f32_16x16x32_bf16 v[90:93], v[62:65], v[214:217], v[90:93]
	s_setprio 0
	s_barrier
	s_add_i32 s54, 0, 0x14000
	v_add_u32_e32 v170, s54, v173
	s_add_i32 s50, s50, s31
	ds_read_b128 v[218:221], v170
	ds_read_b128 v[222:225], v170 offset:1024
	ds_read_b128 v[226:229], v170 offset:2048
	ds_read_b128 v[230:233], v170 offset:3072
	v_lshl_add_u64 v[170:171], s[20:21], 0, v[0:1]
	s_mov_b32 m0, s50
	v_lshl_add_u64 v[200:201], s[20:21], 0, v[164:165]
	global_load_lds_dwordx4 v[170:171], off
	s_add_i32 m0, s50, 0x2000
	s_nop 0
	global_load_lds_dwordx4 v[200:201], off
	s_barrier
	s_waitcnt lgkmcnt(0)
	s_setprio 1
	v_mfma_f32_16x16x32_bf16 v[134:137], v[218:221], v[176:179], v[134:137]
	v_mfma_f32_16x16x32_bf16 v[130:133], v[226:229], v[176:179], v[130:133]
	v_mfma_f32_16x16x32_bf16 v[118:121], v[218:221], v[184:187], v[118:121]
	v_mfma_f32_16x16x32_bf16 v[114:117], v[226:229], v[184:187], v[114:117]
	v_mfma_f32_16x16x32_bf16 v[102:105], v[218:221], v[192:195], v[102:105]
	v_mfma_f32_16x16x32_bf16 v[98:101], v[226:229], v[192:195], v[98:101]
	v_mfma_f32_16x16x32_bf16 v[86:89], v[218:221], v[210:213], v[86:89]
	v_mfma_f32_16x16x32_bf16 v[82:85], v[226:229], v[210:213], v[82:85]
	v_mfma_f32_16x16x32_bf16 v[134:137], v[222:225], v[180:183], v[134:137]
	v_mfma_f32_16x16x32_bf16 v[130:133], v[230:233], v[180:183], v[130:133]
	v_mfma_f32_16x16x32_bf16 v[118:121], v[222:225], v[188:191], v[118:121]
	v_mfma_f32_16x16x32_bf16 v[114:117], v[230:233], v[188:191], v[114:117]
	v_mfma_f32_16x16x32_bf16 v[102:105], v[222:225], v[196:199], v[102:105]
	v_mfma_f32_16x16x32_bf16 v[98:101], v[230:233], v[196:199], v[98:101]
	v_mfma_f32_16x16x32_bf16 v[86:89], v[222:225], v[214:217], v[86:89]
	v_mfma_f32_16x16x32_bf16 v[82:85], v[230:233], v[214:217], v[82:85]
	s_setprio 0
	s_mov_b32 m0, s3
	v_lshl_add_u64 v[234:235], s[22:23], 0, v[160:161]
	s_barrier
	ds_read_b128 v[176:179], v174 offset:16384
	ds_read_b128 v[180:183], v174 offset:17408
	ds_read_b128 v[184:187], v174 offset:18432
	ds_read_b128 v[188:191], v174 offset:19456
	ds_read_b128 v[192:195], v174 offset:20480
	ds_read_b128 v[196:199], v174 offset:21504
	ds_read_b128 v[210:213], v174 offset:22528
	ds_read_b128 v[214:217], v174 offset:23552
	global_load_lds_dwordx4 v[234:235], off
	v_lshl_add_u64 v[236:237], s[22:23], 0, v[162:163]
	s_mov_b32 m0, s34
	s_nop 0
	global_load_lds_dwordx4 v[236:237], off
	s_barrier
	s_waitcnt lgkmcnt(0)
	s_setprio 1
	v_mfma_f32_16x16x32_bf16 v[78:81], v[42:45], v[176:179], v[78:81]
	v_mfma_f32_16x16x32_bf16 v[74:77], v[58:61], v[176:179], v[74:77]
	v_mfma_f32_16x16x32_bf16 v[54:57], v[42:45], v[184:187], v[54:57]
	v_mfma_f32_16x16x32_bf16 v[50:53], v[58:61], v[184:187], v[50:53]
	v_mfma_f32_16x16x32_bf16 v[30:33], v[42:45], v[192:195], v[30:33]
	v_mfma_f32_16x16x32_bf16 v[26:29], v[58:61], v[192:195], v[26:29]
	v_mfma_f32_16x16x32_bf16 v[14:17], v[42:45], v[210:213], v[14:17]
	v_mfma_f32_16x16x32_bf16 v[10:13], v[58:61], v[210:213], v[10:13]
	v_mfma_f32_16x16x32_bf16 v[78:81], v[46:49], v[180:183], v[78:81]
	v_mfma_f32_16x16x32_bf16 v[74:77], v[62:65], v[180:183], v[74:77]
	v_mfma_f32_16x16x32_bf16 v[54:57], v[46:49], v[188:191], v[54:57]
	v_mfma_f32_16x16x32_bf16 v[50:53], v[62:65], v[188:191], v[50:53]
	v_mfma_f32_16x16x32_bf16 v[30:33], v[46:49], v[196:199], v[30:33]
	v_mfma_f32_16x16x32_bf16 v[26:29], v[62:65], v[196:199], v[26:29]
	v_mfma_f32_16x16x32_bf16 v[14:17], v[46:49], v[214:217], v[14:17]
	v_mfma_f32_16x16x32_bf16 v[10:13], v[62:65], v[214:217], v[10:13]
	s_setprio 0
	s_barrier
; #define PG8_STAGE(bufoff, gbase, voff) do { _Pragma("unroll") for (int _i = 0; _i < 2; ++_i) \
;         __builtin_amdgcn_global_load_lds((const unsigned*)((const char*)(gbase) + (voff)[_i]), (LAS unsigned*)(lds + (bufoff) + ldsw + _i * 8192), 16, 0, 0); } while (0)
; #define PG8_LDA(dst, b, h) do { _Pragma("unroll") for (int m = 0; m < 4; ++m) _Pragma("unroll") for (int k = 0; k < 2; ++k) dst[m][k] = *(const LAS bf16x8*)(lds + PG8_SA(b, h) + aoff + m * 2048 + k * 1024); } while (0)
; #define PG8_LDB(dst, b, h) do { _Pragma("unroll") for (int n = 0; n < 2; ++n) _Pragma("unroll") for (int k = 0; k < 2; ++k) dst[n][k] = *(const LAS bf16x8*)(lds + PG8_SB(b, h) + boff + n * 2048 + k * 1024); } while (0)
; #define PG8_MMA(ai, bj, At, Bt) do { __builtin_amdgcn_s_setprio(1); _Pragma("unroll") for (int m = 0; m < 4; ++m) _Pragma("unroll") for (int n = 0; n < 2; ++n) _Pragma("unroll") for (int k = 0; k < 2; ++k) \
;         acc[ai][bj][m][n] = __builtin_amdgcn_mfma_f32_16x16x32_bf16(Bt[n][k], At[m][k], acc[ai][bj][m][n], 0, 0, 0); __builtin_amdgcn_s_setprio(0); } while (0)
; #define PG8_WAIT_V(n) asm volatile("s_waitcnt vmcnt(" #n ")" ::: "memory")
; #define PG8_WAIT_L(n) asm volatile("s_waitcnt lgkmcnt(" #n ")" ::: "memory")
; #define PG8_BAR __builtin_amdgcn_s_barrier()
; #define PG8_SCHED __builtin_amdgcn_sched_barrier(0)
; template <class Epi>
; __device__ __forceinline__ void gemm_phase(LAS unsigned char* lds, const Gemm g, const StaticOrder& S, const Epi& E, const int tid) {
;     ...
;             PG8_STAGE(PG8_SB(0, 1), b2 + hstep, voffB);
;             PG8_WAIT_V(6); PG8_BAR; PG8_MMA(1, 1, At, B1); PG8_BAR;
;             PG8_LDB(B0, 1, 0); PG8_SCHED; PG8_LDA(At, 1, 0); PG8_STAGE(PG8_SA(0, 1), a2 + hstep, voffA);
;             PG8_WAIT_L(8); PG8_BAR; PG8_WAIT_L(0); PG8_MMA(0, 0, At, B0); PG8_BAR; PG8_SCHED;
;             PG8_LDB(B1, 1, 1); PG8_STAGE(PG8_SB(1, 0), b3, voffB);
;             PG8_BAR; PG8_WAIT_L(0); PG8_MMA(0, 1, At, B1); PG8_BAR;
	s_add_u32 s52, s20, 0x80000
	s_addc_u32 s53, s21, 0
	s_add_i32 s50, s54, s31
	v_lshl_add_u64 v[42:43], s[52:53], 0, v[0:1]
	s_mov_b32 m0, s50
	s_nop 0
	global_load_lds_dwordx4 v[42:43], off
	v_lshl_add_u64 v[42:43], s[52:53], 0, v[164:165]
	s_add_i32 m0, s50, 0x2000
	s_nop 0
	global_load_lds_dwordx4 v[42:43], off
	s_waitcnt vmcnt(6)
	s_barrier
	s_setprio 1
	v_mfma_f32_16x16x32_bf16 v[38:41], v[218:221], v[184:187], v[38:41]
	v_mfma_f32_16x16x32_bf16 v[34:37], v[226:229], v[184:187], v[34:37]
	v_mfma_f32_16x16x32_bf16 v[22:25], v[218:221], v[192:195], v[22:25]
	v_mfma_f32_16x16x32_bf16 v[18:21], v[226:229], v[192:195], v[18:21]
	v_mfma_f32_16x16x32_bf16 v[6:9], v[218:221], v[210:213], v[6:9]
	v_mfma_f32_16x16x32_bf16 v[2:5], v[226:229], v[210:213], v[2:5]
	v_mfma_f32_16x16x32_bf16 v[42:45], v[218:221], v[176:179], v[70:73]
	v_mfma_f32_16x16x32_bf16 v[46:49], v[226:229], v[176:179], v[66:69]
	v_mfma_f32_16x16x32_bf16 v[38:41], v[222:225], v[188:191], v[38:41]
	v_mfma_f32_16x16x32_bf16 v[34:37], v[230:233], v[188:191], v[34:37]
	v_mfma_f32_16x16x32_bf16 v[22:25], v[222:225], v[196:199], v[22:25]
	v_mfma_f32_16x16x32_bf16 v[18:21], v[230:233], v[196:199], v[18:21]
	v_mfma_f32_16x16x32_bf16 v[6:9], v[222:225], v[214:217], v[6:9]
	v_mfma_f32_16x16x32_bf16 v[2:5], v[230:233], v[214:217], v[2:5]
	v_mfma_f32_16x16x32_bf16 v[42:45], v[222:225], v[180:183], v[42:45]
	v_mfma_f32_16x16x32_bf16 v[46:49], v[230:233], v[180:183], v[46:49]
	s_setprio 0
	s_add_i32 s50, 0, 0x18000
	v_add_u32_e32 v70, s50, v173
	s_barrier
	ds_read_b128 v[58:61], v70
	ds_read_b128 v[62:65], v70 offset:1024
	ds_read_b128 v[66:69], v70 offset:2048
	ds_read_b128 v[70:73], v70 offset:3072
	s_add_u32 s22, s22, 0x80000
	s_addc_u32 s23, s23, 0
	s_mov_b32 m0, s35
	v_lshl_add_u64 v[218:219], s[22:23], 0, v[160:161]
	ds_read_b128 v[176:179], v174 offset:32768
	ds_read_b128 v[180:183], v174 offset:33792
	ds_read_b128 v[184:187], v174 offset:34816
	ds_read_b128 v[188:191], v174 offset:35840
	ds_read_b128 v[192:195], v174 offset:36864
	ds_read_b128 v[196:199], v174 offset:37888
	ds_read_b128 v[210:213], v174 offset:38912
	ds_read_b128 v[214:217], v174 offset:39936
	global_load_lds_dwordx4 v[218:219], off
	v_lshl_add_u64 v[218:219], s[22:23], 0, v[162:163]
	s_mov_b32 m0, s36
	s_nop 0
	global_load_lds_dwordx4 v[218:219], off
	s_waitcnt lgkmcnt(8)
	s_barrier
	s_waitcnt lgkmcnt(0)
	s_setprio 1
	v_mfma_f32_16x16x32_bf16 v[142:145], v[58:61], v[176:179], v[142:145]
	v_mfma_f32_16x16x32_bf16 v[138:141], v[66:69], v[176:179], v[138:141]
	v_mfma_f32_16x16x32_bf16 v[126:129], v[58:61], v[184:187], v[126:129]
	v_mfma_f32_16x16x32_bf16 v[122:125], v[66:69], v[184:187], v[122:125]
	v_mfma_f32_16x16x32_bf16 v[110:113], v[58:61], v[192:195], v[110:113]
	v_mfma_f32_16x16x32_bf16 v[106:109], v[66:69], v[192:195], v[106:109]
	v_mfma_f32_16x16x32_bf16 v[94:97], v[58:61], v[210:213], v[94:97]
	v_mfma_f32_16x16x32_bf16 v[90:93], v[66:69], v[210:213], v[90:93]
	v_mfma_f32_16x16x32_bf16 v[142:145], v[62:65], v[180:183], v[142:145]
	v_mfma_f32_16x16x32_bf16 v[138:141], v[70:73], v[180:183], v[138:141]
	v_mfma_f32_16x16x32_bf16 v[126:129], v[62:65], v[188:191], v[126:129]
	v_mfma_f32_16x16x32_bf16 v[122:125], v[70:73], v[188:191], v[122:125]
	v_mfma_f32_16x16x32_bf16 v[110:113], v[62:65], v[196:199], v[110:113]
	v_mfma_f32_16x16x32_bf16 v[106:109], v[70:73], v[196:199], v[106:109]
	v_mfma_f32_16x16x32_bf16 v[94:97], v[62:65], v[214:217], v[94:97]
	v_mfma_f32_16x16x32_bf16 v[90:93], v[70:73], v[214:217], v[90:93]
	s_setprio 0
	s_barrier
	s_add_i32 s22, 0, 0x1c000
	s_add_i32 s23, s50, s31
	v_add_u32_e32 v175, s22, v173
	v_lshl_add_u64 v[170:171], v[170:171], 0, s[56:57]
	s_mov_b32 m0, s23
	ds_read_b128 v[218:221], v175
	ds_read_b128 v[222:225], v175 offset:1024
	ds_read_b128 v[226:229], v175 offset:2048
	ds_read_b128 v[230:233], v175 offset:3072
	global_load_lds_dwordx4 v[170:171], off
	v_lshl_add_u64 v[170:171], v[200:201], 0, s[56:57]
	s_add_i32 m0, s23, 0x2000
	s_nop 0
	global_load_lds_dwordx4 v[170:171], off
	s_barrier
	s_waitcnt lgkmcnt(0)
	s_setprio 1
	v_mfma_f32_16x16x32_bf16 v[134:137], v[218:221], v[176:179], v[134:137]
	v_mfma_f32_16x16x32_bf16 v[130:133], v[226:229], v[176:179], v[130:133]
	v_mfma_f32_16x16x32_bf16 v[118:121], v[218:221], v[184:187], v[118:121]
	v_mfma_f32_16x16x32_bf16 v[114:117], v[226:229], v[184:187], v[114:117]
	v_mfma_f32_16x16x32_bf16 v[102:105], v[218:221], v[192:195], v[102:105]
	v_mfma_f32_16x16x32_bf16 v[98:101], v[226:229], v[192:195], v[98:101]
	v_mfma_f32_16x16x32_bf16 v[86:89], v[218:221], v[210:213], v[86:89]
	v_mfma_f32_16x16x32_bf16 v[82:85], v[226:229], v[210:213], v[82:85]
	v_mfma_f32_16x16x32_bf16 v[134:137], v[222:225], v[180:183], v[134:137]
	v_mfma_f32_16x16x32_bf16 v[130:133], v[230:233], v[180:183], v[130:133]
	v_mfma_f32_16x16x32_bf16 v[118:121], v[222:225], v[188:191], v[118:121]
	v_mfma_f32_16x16x32_bf16 v[114:117], v[230:233], v[188:191], v[114:117]
	v_mfma_f32_16x16x32_bf16 v[102:105], v[222:225], v[196:199], v[102:105]
	v_mfma_f32_16x16x32_bf16 v[98:101], v[230:233], v[196:199], v[98:101]
	v_mfma_f32_16x16x32_bf16 v[86:89], v[222:225], v[214:217], v[86:89]
	v_mfma_f32_16x16x32_bf16 v[82:85], v[230:233], v[214:217], v[82:85]
	s_setprio 0
	s_mov_b32 m0, s39
	v_lshl_add_u64 v[170:171], v[234:235], 0, s[56:57]
	s_barrier
	ds_read_b128 v[176:179], v174 offset:49152
	ds_read_b128 v[180:183], v174 offset:50176
	ds_read_b128 v[184:187], v174 offset:51200
	ds_read_b128 v[188:191], v174 offset:52224
	ds_read_b128 v[192:195], v174 offset:53248
	ds_read_b128 v[196:199], v174 offset:54272
	ds_read_b128 v[210:213], v174 offset:55296
	ds_read_b128 v[214:217], v174 offset:56320
	global_load_lds_dwordx4 v[170:171], off
	v_lshl_add_u64 v[170:171], v[236:237], 0, s[56:57]
	s_mov_b32 m0, s40
	s_nop 0
	global_load_lds_dwordx4 v[170:171], off
	s_barrier
; __device__ __forceinline__ unsigned pk2(float lo, float hi) { f32x2 v = {lo, hi}; return __builtin_bit_cast(unsigned, __builtin_convertvector(v, bf16x2_t)); }
; __device__ __forceinline__ float bf_lo(unsigned w) { return __uint_as_float(w << 16); }
; __device__ __forceinline__ float bf_hi(unsigned w) { return __uint_as_float(w & 0xffff0000u); }
;     __device__ __forceinline__ void operator()(const f32x4 (&acc)[2][2][4][2], const Unit& u, int wr, int wc, int fr, int fq) const {
;         asm volatile("" : "+v"(fr), "+v"(fq));
;         const int row0 = u.pm * BM + wr * 64 + fr, col0 = u.pn * BM + wc * 32 + 8 * fq;
;         const float* gp = gate + (size_t)(u.pm >> 5) * 12288 + col0;
;         f32x4 gv[2][2];
; #pragma unroll
;         for (int bj = 0; bj < 2; ++bj)
; #pragma unroll
;             for (int n = 0; n < 2; ++n) gv[bj][n] = *(const f32x4*)(gp + bj * HALF + 4 * n);
; #pragma unroll
;         for (int ai = 0; ai < 2; ++ai)
; #pragma unroll
;             for (int m = 0; m < 4; ++m) {
;                 const size_t ro = (size_t)(row0 + ai * HALF + m * 16) * DM + col0;
; #pragma unroll
;                 for (int bj = 0; bj < 2; ++bj) {
;                     f32x4 r0, r1;
;                     if (RB) { const u32x4 rw = *(const u32x4*)((const bf16_t*)resid + ro + bj * HALF);
;                         r0 = (f32x4){bf_lo(rw.x), bf_hi(rw.x), bf_lo(rw.y), bf_hi(rw.y)}; r1 = (f32x4){bf_lo(rw.z), bf_hi(rw.z), bf_lo(rw.w), bf_hi(rw.w)}; }
;                     else { r0 = *(const f32x4*)((const float*)resid + ro + bj * HALF); r1 = *(const f32x4*)((const float*)resid + ro + bj * HALF + 4); }
;                     const f32x4 v0 = r0 + gv[bj][0] * acc[ai][bj][m][0], v1 = r1 + gv[bj][1] * acc[ai][bj][m][1];
;                     if (OB) { u32x4 w; w.x = pk2(v0[0], v0[1]); w.y = pk2(v0[2], v0[3]); w.z = pk2(v1[0], v1[1]); w.w = pk2(v1[2], v1[3]); *(u32x4*)((bf16_t*)out + ro + bj * HALF) = w; }
; template <class Epi>
; __device__ __forceinline__ void gemm_phase(LAS unsigned char* lds, const Gemm g, const StaticOrder& S, const Epi& E, const int tid) {
;     ...
;             PG8_LDA(At, 1, 1); PG8_STAGE(PG8_SA(1, 0), a3, voffA);
;             PG8_BAR; PG8_WAIT_L(0); PG8_MMA(1, 0, At, B0); PG8_BAR; PG8_SCHED;
;             PG8_STAGE(PG8_SB(1, 1), b3 + hstep, voffB);
;             PG8_WAIT_V(6); PG8_BAR; PG8_MMA(1, 1, At, B1); PG8_BAR;
	s_waitcnt lgkmcnt(0)
	s_setprio 1
	v_mfma_f32_16x16x32_bf16 v[78:81], v[58:61], v[176:179], v[78:81]
	v_mfma_f32_16x16x32_bf16 v[74:77], v[66:69], v[176:179], v[74:77]
	v_mfma_f32_16x16x32_bf16 v[54:57], v[58:61], v[184:187], v[54:57]
	v_mfma_f32_16x16x32_bf16 v[50:53], v[66:69], v[184:187], v[50:53]
	v_mfma_f32_16x16x32_bf16 v[30:33], v[58:61], v[192:195], v[30:33]
	v_mfma_f32_16x16x32_bf16 v[26:29], v[66:69], v[192:195], v[26:29]
	v_mfma_f32_16x16x32_bf16 v[14:17], v[58:61], v[210:213], v[14:17]
	v_mfma_f32_16x16x32_bf16 v[10:13], v[66:69], v[210:213], v[10:13]
	v_mfma_f32_16x16x32_bf16 v[78:81], v[62:65], v[180:183], v[78:81]
	v_mfma_f32_16x16x32_bf16 v[74:77], v[70:73], v[180:183], v[74:77]
	v_mfma_f32_16x16x32_bf16 v[54:57], v[62:65], v[188:191], v[54:57]
	v_mfma_f32_16x16x32_bf16 v[50:53], v[70:73], v[188:191], v[50:53]
	v_mfma_f32_16x16x32_bf16 v[30:33], v[62:65], v[196:199], v[30:33]
	v_mfma_f32_16x16x32_bf16 v[26:29], v[70:73], v[196:199], v[26:29]
	v_mfma_f32_16x16x32_bf16 v[14:17], v[62:65], v[214:217], v[14:17]
	v_mfma_f32_16x16x32_bf16 v[10:13], v[70:73], v[214:217], v[10:13]
	s_setprio 0
	s_barrier
	s_add_u32 s20, s20, 0x80080
	s_addc_u32 s21, s21, 0
	s_add_i32 s22, s22, s31
	v_lshl_add_u64 v[58:59], s[20:21], 0, v[0:1]
	s_mov_b32 m0, s22
	s_nop 0
	global_load_lds_dwordx4 v[58:59], off
	v_lshl_add_u64 v[58:59], s[20:21], 0, v[164:165]
	s_add_i32 m0, s22, 0x2000
	s_nop 0
	global_load_lds_dwordx4 v[58:59], off
	s_waitcnt vmcnt(6)
	s_barrier
	s_setprio 1
	v_mfma_f32_16x16x32_bf16 v[42:45], v[218:221], v[176:179], v[42:45]
	v_mfma_f32_16x16x32_bf16 v[70:73], v[222:225], v[180:183], v[42:45]
	v_mfma_f32_16x16x32_bf16 v[42:45], v[226:229], v[176:179], v[46:49]
	v_mfma_f32_16x16x32_bf16 v[38:41], v[218:221], v[184:187], v[38:41]
	v_mfma_f32_16x16x32_bf16 v[34:37], v[226:229], v[184:187], v[34:37]
	v_mfma_f32_16x16x32_bf16 v[22:25], v[218:221], v[192:195], v[22:25]
	v_mfma_f32_16x16x32_bf16 v[18:21], v[226:229], v[192:195], v[18:21]
	v_mfma_f32_16x16x32_bf16 v[6:9], v[218:221], v[210:213], v[6:9]
	v_mfma_f32_16x16x32_bf16 v[2:5], v[226:229], v[210:213], v[2:5]
	v_mfma_f32_16x16x32_bf16 v[66:69], v[230:233], v[180:183], v[42:45]
	v_mfma_f32_16x16x32_bf16 v[38:41], v[222:225], v[188:191], v[38:41]
	v_mfma_f32_16x16x32_bf16 v[34:37], v[230:233], v[188:191], v[34:37]
	v_mfma_f32_16x16x32_bf16 v[22:25], v[222:225], v[196:199], v[22:25]
	v_mfma_f32_16x16x32_bf16 v[18:21], v[230:233], v[196:199], v[18:21]
	v_mfma_f32_16x16x32_bf16 v[6:9], v[222:225], v[214:217], v[6:9]
	v_mfma_f32_16x16x32_bf16 v[2:5], v[230:233], v[214:217], v[2:5]
	s_setprio 0
	s_add_i32 s49, s49, 2
	s_add_u32 s47, s47, 0x100
	s_addc_u32 s48, s48, 0
	s_add_u32 s18, s18, 0x100
	s_addc_u32 s19, s19, 0
	s_cmp_gt_u32 s49, 29
	s_barrier
	s_cbranch_scc0 .LBB0_119
	s_lshl_b32 s11, s2, 8
	s_lshl_b32 s13, s43, 8
	v_mov_b32_e32 v175, v172
	v_mov_b32_e32 v42, v159
	s_add_i32 s11, s11, s37
	s_or_b32 s13, s13, s38
	s_ashr_i32 s2, s2, 5
	s_mov_b32 s43, s10
	v_lshl_add_u32 v170, v42, 3, s13
	s_mul_hi_i32 s13, s2, 0xc000
	s_mul_i32 s2, s2, 0xc000
	v_add_u32_e32 v176, s11, v175
	s_add_u32 s18, s27, s2
	v_ashrrev_i32_e32 v177, 31, v176
	s_addc_u32 s19, s28, s13
	v_ashrrev_i32_e32 v171, 31, v170
	v_lshlrev_b64 v[176:177], 11, v[176:177]
	v_lshl_add_u64 v[46:47], v[170:171], 2, s[18:19]
	v_lshl_add_u64 v[170:171], v[176:177], 0, v[170:171]
	v_lshlrev_b64 v[170:171], 1, v[170:171]
	v_lshl_add_u64 v[180:181], s[8:9], 0, v[170:171]
	global_load_dwordx4 v[58:61], v[46:47], off offset:16
	global_load_dwordx4 v[62:65], v[46:47], off
	global_load_dwordx4 v[42:45], v[46:47], off offset:528
	s_nop 0
	global_load_dwordx4 v[46:49], v[46:47], off offset:512
	s_mov_b64 s[92:93], s[8:9]
	s_mov_b64 s[94:95], s[6:7]
	global_load_dwordx4 v[184:187], v170, s[92:93]
	global_load_dwordx4 v[188:191], v170, s[92:93] offset:256
	s_add_u32 s92, s92, 0x10000
	s_addc_u32 s93, s93, 0
	global_load_dwordx4 v[192:195], v170, s[92:93]
	global_load_dwordx4 v[196:199], v170, s[92:93] offset:256
	s_add_u32 s92, s92, 0x10000
	s_addc_u32 s93, s93, 0
	global_load_dwordx4 v[210:213], v170, s[92:93]
	global_load_dwordx4 v[214:217], v170, s[92:93] offset:256
	s_add_u32 s92, s92, 0x10000
	s_addc_u32 s93, s93, 0
	global_load_dwordx4 v[218:221], v170, s[92:93]
	global_load_dwordx4 v[222:225], v170, s[92:93] offset:256
	s_add_u32 s92, s92, 0x50000
	s_addc_u32 s93, s93, 0
	global_load_dwordx4 v[226:229], v170, s[92:93]
	global_load_dwordx4 v[230:233], v170, s[92:93] offset:256
	s_add_u32 s92, s92, 0x10000
	s_addc_u32 s93, s93, 0
	global_load_dwordx4 v[234:237], v170, s[92:93]
	s_waitcnt vmcnt(10)
	v_lshlrev_b32_e32 v176, 16, v184
	v_and_b32_e32 v177, 0xffff0000, v184
	v_lshlrev_b32_e32 v178, 16, v185
	v_and_b32_e32 v179, 0xffff0000, v185
	v_lshlrev_b32_e32 v180, 16, v186
	v_and_b32_e32 v181, 0xffff0000, v186
	v_lshlrev_b32_e32 v182, 16, v187
	v_and_b32_e32 v183, 0xffff0000, v187
	v_pk_fma_f32 v[142:143], v[142:143], v[62:63], v[176:177]
	v_pk_fma_f32 v[144:145], v[144:145], v[64:65], v[178:179]
	v_pk_fma_f32 v[138:139], v[138:139], v[58:59], v[180:181]
	v_pk_fma_f32 v[140:141], v[140:141], v[60:61], v[182:183]
	global_load_dwordx4 v[184:187], v170, s[92:93] offset:256
	v_cvt_pk_bf16_f32 v142, v142, v143
	v_cvt_pk_bf16_f32 v143, v144, v145
	v_cvt_pk_bf16_f32 v144, v138, v139
	v_cvt_pk_bf16_f32 v145, v140, v141
	global_store_dwordx4 v170, v[142:145], s[94:95]
	s_waitcnt vmcnt(11)
; __device__ __forceinline__ unsigned pk2(float lo, float hi) { f32x2 v = {lo, hi}; return __builtin_bit_cast(unsigned, __builtin_convertvector(v, bf16x2_t)); }
; __device__ __forceinline__ float bf_lo(unsigned w) { return __uint_as_float(w << 16); }
; __device__ __forceinline__ float bf_hi(unsigned w) { return __uint_as_float(w & 0xffff0000u); }
;     __device__ __forceinline__ void operator()(const f32x4 (&acc)[2][2][4][2], const Unit& u, int wr, int wc, int fr, int fq) const {
;     ...
;             for (int m = 0; m < 4; ++m) {
;                 const size_t ro = (size_t)(row0 + ai * HALF + m * 16) * DM + col0;
; #pragma unroll
;                 for (int bj = 0; bj < 2; ++bj) {
;                     f32x4 r0, r1;
;                     if (RB) { const u32x4 rw = *(const u32x4*)((const bf16_t*)resid + ro + bj * HALF);
;                         r0 = (f32x4){bf_lo(rw.x), bf_hi(rw.x), bf_lo(rw.y), bf_hi(rw.y)}; r1 = (f32x4){bf_lo(rw.z), bf_hi(rw.z), bf_lo(rw.w), bf_hi(rw.w)}; }
;                     else { r0 = *(const f32x4*)((const float*)resid + ro + bj * HALF); r1 = *(const f32x4*)((const float*)resid + ro + bj * HALF + 4); }
;                     const f32x4 v0 = r0 + gv[bj][0] * acc[ai][bj][m][0], v1 = r1 + gv[bj][1] * acc[ai][bj][m][1];
;                     if (OB) { u32x4 w; w.x = pk2(v0[0], v0[1]); w.y = pk2(v0[2], v0[3]); w.z = pk2(v1[0], v1[1]); w.w = pk2(v1[2], v1[3]); *(u32x4*)((bf16_t*)out + ro + bj * HALF) = w; }
;                     else { *(f32x4*)((float*)out + ro + bj * HALF) = v0; *(f32x4*)((float*)out + ro + bj * HALF + 4) = v1; }
;                 }
	v_lshlrev_b32_e32 v176, 16, v188
	v_and_b32_e32 v177, 0xffff0000, v188
	v_lshlrev_b32_e32 v178, 16, v189
	v_and_b32_e32 v179, 0xffff0000, v189
	v_lshlrev_b32_e32 v180, 16, v190
	v_and_b32_e32 v181, 0xffff0000, v190
	v_lshlrev_b32_e32 v182, 16, v191
	v_and_b32_e32 v183, 0xffff0000, v191
	v_pk_fma_f32 v[134:135], v[134:135], v[46:47], v[176:177]
	v_pk_fma_f32 v[136:137], v[136:137], v[48:49], v[178:179]
	v_pk_fma_f32 v[130:131], v[130:131], v[42:43], v[180:181]
	v_pk_fma_f32 v[132:133], v[132:133], v[44:45], v[182:183]
	s_add_u32 s92, s92, 0x10000
	s_addc_u32 s93, s93, 0
	global_load_dwordx4 v[188:191], v170, s[92:93]
	v_cvt_pk_bf16_f32 v134, v134, v135
	v_cvt_pk_bf16_f32 v135, v136, v137
	v_cvt_pk_bf16_f32 v136, v130, v131
	v_cvt_pk_bf16_f32 v137, v132, v133
	global_store_dwordx4 v170, v[134:137], s[94:95] offset:256
	s_waitcnt vmcnt(12)
	v_lshlrev_b32_e32 v176, 16, v192
	v_and_b32_e32 v177, 0xffff0000, v192
	v_lshlrev_b32_e32 v178, 16, v193
	v_and_b32_e32 v179, 0xffff0000, v193
	v_lshlrev_b32_e32 v180, 16, v194
	v_and_b32_e32 v181, 0xffff0000, v194
	v_lshlrev_b32_e32 v182, 16, v195
	v_and_b32_e32 v183, 0xffff0000, v195
	v_pk_fma_f32 v[126:127], v[126:127], v[62:63], v[176:177]
	v_pk_fma_f32 v[128:129], v[128:129], v[64:65], v[178:179]
	v_pk_fma_f32 v[122:123], v[122:123], v[58:59], v[180:181]
	v_pk_fma_f32 v[124:125], v[124:125], v[60:61], v[182:183]
	global_load_dwordx4 v[192:195], v170, s[92:93] offset:256
	s_add_u32 s94, s94, 0x10000
	s_addc_u32 s95, s95, 0
	v_cvt_pk_bf16_f32 v126, v126, v127
	v_cvt_pk_bf16_f32 v127, v128, v129
	v_cvt_pk_bf16_f32 v128, v122, v123
	v_cvt_pk_bf16_f32 v129, v124, v125
	global_store_dwordx4 v170, v[126:129], s[94:95]
	s_waitcnt vmcnt(13)
	v_lshlrev_b32_e32 v176, 16, v196
	v_and_b32_e32 v177, 0xffff0000, v196
	v_lshlrev_b32_e32 v178, 16, v197
	v_and_b32_e32 v179, 0xffff0000, v197
	v_lshlrev_b32_e32 v180, 16, v198
	v_and_b32_e32 v181, 0xffff0000, v198
	v_lshlrev_b32_e32 v182, 16, v199
	v_and_b32_e32 v183, 0xffff0000, v199
	v_pk_fma_f32 v[118:119], v[118:119], v[46:47], v[176:177]
	v_pk_fma_f32 v[120:121], v[120:121], v[48:49], v[178:179]
	v_pk_fma_f32 v[114:115], v[114:115], v[42:43], v[180:181]
	v_pk_fma_f32 v[116:117], v[116:117], v[44:45], v[182:183]
	s_add_u32 s92, s92, 0x10000
	s_addc_u32 s93, s93, 0
	global_load_dwordx4 v[196:199], v170, s[92:93]
	v_cvt_pk_bf16_f32 v118, v118, v119
	v_cvt_pk_bf16_f32 v119, v120, v121
	v_cvt_pk_bf16_f32 v120, v114, v115
	v_cvt_pk_bf16_f32 v121, v116, v117
	global_store_dwordx4 v170, v[118:121], s[94:95] offset:256
	s_waitcnt vmcnt(14)
	v_lshlrev_b32_e32 v176, 16, v210
	v_and_b32_e32 v177, 0xffff0000, v210
	v_lshlrev_b32_e32 v178, 16, v211
	v_and_b32_e32 v179, 0xffff0000, v211
	v_lshlrev_b32_e32 v180, 16, v212
	v_and_b32_e32 v181, 0xffff0000, v212
	v_lshlrev_b32_e32 v182, 16, v213
	v_and_b32_e32 v183, 0xffff0000, v213
	v_pk_fma_f32 v[110:111], v[110:111], v[62:63], v[176:177]
	v_pk_fma_f32 v[112:113], v[112:113], v[64:65], v[178:179]
	v_pk_fma_f32 v[106:107], v[106:107], v[58:59], v[180:181]
	v_pk_fma_f32 v[108:109], v[108:109], v[60:61], v[182:183]
	global_load_dwordx4 v[210:213], v170, s[92:93] offset:256
	s_add_u32 s94, s94, 0x10000
	s_addc_u32 s95, s95, 0
	v_cvt_pk_bf16_f32 v110, v110, v111
	v_cvt_pk_bf16_f32 v111, v112, v113
	v_cvt_pk_bf16_f32 v112, v106, v107
	v_cvt_pk_bf16_f32 v113, v108, v109
	global_store_dwordx4 v170, v[110:113], s[94:95]
	s_waitcnt vmcnt(15)
	v_lshlrev_b32_e32 v176, 16, v214
	v_and_b32_e32 v177, 0xffff0000, v214
	v_lshlrev_b32_e32 v178, 16, v215
	v_and_b32_e32 v179, 0xffff0000, v215
	v_lshlrev_b32_e32 v180, 16, v216
	v_and_b32_e32 v181, 0xffff0000, v216
	v_lshlrev_b32_e32 v182, 16, v217
	v_and_b32_e32 v183, 0xffff0000, v217
	v_pk_fma_f32 v[102:103], v[102:103], v[46:47], v[176:177]
	v_pk_fma_f32 v[104:105], v[104:105], v[48:49], v[178:179]
	v_pk_fma_f32 v[98:99], v[98:99], v[42:43], v[180:181]
	v_pk_fma_f32 v[100:101], v[100:101], v[44:45], v[182:183]
	v_cvt_pk_bf16_f32 v102, v102, v103
	v_cvt_pk_bf16_f32 v103, v104, v105
	v_cvt_pk_bf16_f32 v104, v98, v99
	v_cvt_pk_bf16_f32 v105, v100, v101
	global_store_dwordx4 v170, v[102:105], s[94:95] offset:256
	s_waitcnt vmcnt(15)
	v_lshlrev_b32_e32 v176, 16, v218
	v_and_b32_e32 v177, 0xffff0000, v218
	v_lshlrev_b32_e32 v178, 16, v219
	v_and_b32_e32 v179, 0xffff0000, v219
	v_lshlrev_b32_e32 v180, 16, v220
	v_and_b32_e32 v181, 0xffff0000, v220
	v_lshlrev_b32_e32 v182, 16, v221
	v_and_b32_e32 v183, 0xffff0000, v221
	v_pk_fma_f32 v[94:95], v[94:95], v[62:63], v[176:177]
	v_pk_fma_f32 v[96:97], v[96:97], v[64:65], v[178:179]
	v_pk_fma_f32 v[90:91], v[90:91], v[58:59], v[180:181]
	v_pk_fma_f32 v[92:93], v[92:93], v[60:61], v[182:183]
	s_add_u32 s94, s94, 0x10000
	s_addc_u32 s95, s95, 0
	v_cvt_pk_bf16_f32 v94, v94, v95
	v_cvt_pk_bf16_f32 v95, v96, v97
	v_cvt_pk_bf16_f32 v96, v90, v91
	v_cvt_pk_bf16_f32 v97, v92, v93
	global_store_dwordx4 v170, v[94:97], s[94:95]
	s_waitcnt vmcnt(15)
	v_lshlrev_b32_e32 v176, 16, v222
	v_and_b32_e32 v177, 0xffff0000, v222
	v_lshlrev_b32_e32 v178, 16, v223
	v_and_b32_e32 v179, 0xffff0000, v223
	v_lshlrev_b32_e32 v180, 16, v224
	v_and_b32_e32 v181, 0xffff0000, v224
	v_lshlrev_b32_e32 v182, 16, v225
	v_and_b32_e32 v183, 0xffff0000, v225
	v_pk_fma_f32 v[86:87], v[86:87], v[46:47], v[176:177]
	v_pk_fma_f32 v[88:89], v[88:89], v[48:49], v[178:179]
	v_pk_fma_f32 v[82:83], v[82:83], v[42:43], v[180:181]
	v_pk_fma_f32 v[84:85], v[84:85], v[44:45], v[182:183]
	v_cvt_pk_bf16_f32 v86, v86, v87
	v_cvt_pk_bf16_f32 v87, v88, v89
	v_cvt_pk_bf16_f32 v88, v82, v83
	v_cvt_pk_bf16_f32 v89, v84, v85
	global_store_dwordx4 v170, v[86:89], s[94:95] offset:256
	s_waitcnt vmcnt(15)
; __device__ __forceinline__ unsigned pk2(float lo, float hi) { f32x2 v = {lo, hi}; return __builtin_bit_cast(unsigned, __builtin_convertvector(v, bf16x2_t)); }
; __device__ __forceinline__ float bf_lo(unsigned w) { return __uint_as_float(w << 16); }
; __device__ __forceinline__ float bf_hi(unsigned w) { return __uint_as_float(w & 0xffff0000u); }
; #define PG8_WAIT_V(n) asm volatile("s_waitcnt vmcnt(" #n ")" ::: "memory")
; #define PG8_BAR __builtin_amdgcn_s_barrier()
;     __device__ __forceinline__ void operator()(const f32x4 (&acc)[2][2][4][2], const Unit& u, int wr, int wc, int fr, int fq) const {
;     ...
;             for (int m = 0; m < 4; ++m) {
;                 const size_t ro = (size_t)(row0 + ai * HALF + m * 16) * DM + col0;
; #pragma unroll
;                 for (int bj = 0; bj < 2; ++bj) {
;                     f32x4 r0, r1;
;                     if (RB) { const u32x4 rw = *(const u32x4*)((const bf16_t*)resid + ro + bj * HALF);
;                         r0 = (f32x4){bf_lo(rw.x), bf_hi(rw.x), bf_lo(rw.y), bf_hi(rw.y)}; r1 = (f32x4){bf_lo(rw.z), bf_hi(rw.z), bf_lo(rw.w), bf_hi(rw.w)}; }
;                     else { r0 = *(const f32x4*)((const float*)resid + ro + bj * HALF); r1 = *(const f32x4*)((const float*)resid + ro + bj * HALF + 4); }
;                     const f32x4 v0 = r0 + gv[bj][0] * acc[ai][bj][m][0], v1 = r1 + gv[bj][1] * acc[ai][bj][m][1];
;                     if (OB) { u32x4 w; w.x = pk2(v0[0], v0[1]); w.y = pk2(v0[2], v0[3]); w.z = pk2(v1[0], v1[1]); w.w = pk2(v1[2], v1[3]); *(u32x4*)((bf16_t*)out + ro + bj * HALF) = w; }
;                     else { *(f32x4*)((float*)out + ro + bj * HALF) = v0; *(f32x4*)((float*)out + ro + bj * HALF + 4) = v1; }
;                 }
; template <class Epi>
; __device__ __forceinline__ void gemm_phase(LAS unsigned char* lds, const Gemm g, const StaticOrder& S, const Epi& E, const int tid) {
;     ...
;         if (!has_next) break;
; #pragma unroll
;         for (int a = 0; a < 2; ++a)
; #pragma unroll
;             for (int b = 0; b < 2; ++b)
; #pragma unroll
;                 for (int m = 0; m < 4; ++m)
; #pragma unroll
;                     for (int n = 0; n < 2; ++n) acc[a][b][m][n] = (f32x4){0.f, 0.f, 0.f, 0.f};
;         cur = nxt; cA = nA; cB = nB; ++ui;
;     }
;     PG8_WAIT_V(0);
;     if (wr == 0) PG8_BAR;
;     PG8_BAR;
	v_lshlrev_b32_e32 v176, 16, v226
	v_and_b32_e32 v177, 0xffff0000, v226
	v_lshlrev_b32_e32 v178, 16, v227
	v_and_b32_e32 v179, 0xffff0000, v227
	v_lshlrev_b32_e32 v180, 16, v228
	v_and_b32_e32 v181, 0xffff0000, v228
	v_lshlrev_b32_e32 v182, 16, v229
	v_and_b32_e32 v183, 0xffff0000, v229
	v_pk_fma_f32 v[78:79], v[78:79], v[62:63], v[176:177]
	v_pk_fma_f32 v[80:81], v[80:81], v[64:65], v[178:179]
	v_pk_fma_f32 v[74:75], v[74:75], v[58:59], v[180:181]
	v_pk_fma_f32 v[76:77], v[76:77], v[60:61], v[182:183]
	s_add_u32 s94, s94, 0x50000
	s_addc_u32 s95, s95, 0
	v_cvt_pk_bf16_f32 v78, v78, v79
	v_cvt_pk_bf16_f32 v79, v80, v81
	v_cvt_pk_bf16_f32 v80, v74, v75
	v_cvt_pk_bf16_f32 v81, v76, v77
	global_store_dwordx4 v170, v[78:81], s[94:95]
	s_waitcnt vmcnt(15)
	v_lshlrev_b32_e32 v176, 16, v230
	v_and_b32_e32 v177, 0xffff0000, v230
	v_lshlrev_b32_e32 v178, 16, v231
	v_and_b32_e32 v179, 0xffff0000, v231
	v_lshlrev_b32_e32 v180, 16, v232
	v_and_b32_e32 v181, 0xffff0000, v232
	v_lshlrev_b32_e32 v182, 16, v233
	v_and_b32_e32 v183, 0xffff0000, v233
	v_pk_fma_f32 v[70:71], v[70:71], v[46:47], v[176:177]
	v_pk_fma_f32 v[72:73], v[72:73], v[48:49], v[178:179]
	v_pk_fma_f32 v[66:67], v[66:67], v[42:43], v[180:181]
	v_pk_fma_f32 v[68:69], v[68:69], v[44:45], v[182:183]
	v_cvt_pk_bf16_f32 v70, v70, v71
	v_cvt_pk_bf16_f32 v71, v72, v73
	v_cvt_pk_bf16_f32 v72, v66, v67
	v_cvt_pk_bf16_f32 v73, v68, v69
	global_store_dwordx4 v170, v[70:73], s[94:95] offset:256
	s_waitcnt vmcnt(15)
	v_lshlrev_b32_e32 v176, 16, v234
	v_and_b32_e32 v177, 0xffff0000, v234
	v_lshlrev_b32_e32 v178, 16, v235
	v_and_b32_e32 v179, 0xffff0000, v235
	v_lshlrev_b32_e32 v180, 16, v236
	v_and_b32_e32 v181, 0xffff0000, v236
	v_lshlrev_b32_e32 v182, 16, v237
	v_and_b32_e32 v183, 0xffff0000, v237
	v_pk_fma_f32 v[54:55], v[54:55], v[62:63], v[176:177]
	v_pk_fma_f32 v[56:57], v[56:57], v[64:65], v[178:179]
	v_pk_fma_f32 v[50:51], v[50:51], v[58:59], v[180:181]
	v_pk_fma_f32 v[52:53], v[52:53], v[60:61], v[182:183]
	s_add_u32 s94, s94, 0x10000
	s_addc_u32 s95, s95, 0
	v_cvt_pk_bf16_f32 v54, v54, v55
	v_cvt_pk_bf16_f32 v55, v56, v57
	v_cvt_pk_bf16_f32 v56, v50, v51
	v_cvt_pk_bf16_f32 v57, v52, v53
	global_store_dwordx4 v170, v[54:57], s[94:95]
	s_waitcnt vmcnt(15)
	v_lshlrev_b32_e32 v176, 16, v184
	v_and_b32_e32 v177, 0xffff0000, v184
	v_lshlrev_b32_e32 v178, 16, v185
	v_and_b32_e32 v179, 0xffff0000, v185
	v_lshlrev_b32_e32 v180, 16, v186
	v_and_b32_e32 v181, 0xffff0000, v186
	v_lshlrev_b32_e32 v182, 16, v187
	v_and_b32_e32 v183, 0xffff0000, v187
	v_pk_fma_f32 v[38:39], v[38:39], v[46:47], v[176:177]
	v_pk_fma_f32 v[40:41], v[40:41], v[48:49], v[178:179]
	v_pk_fma_f32 v[34:35], v[34:35], v[42:43], v[180:181]
	v_pk_fma_f32 v[36:37], v[36:37], v[44:45], v[182:183]
	v_cvt_pk_bf16_f32 v38, v38, v39
	v_cvt_pk_bf16_f32 v39, v40, v41
	v_cvt_pk_bf16_f32 v40, v34, v35
	v_cvt_pk_bf16_f32 v41, v36, v37
	global_store_dwordx4 v170, v[38:41], s[94:95] offset:256
	s_waitcnt vmcnt(14)
	v_lshlrev_b32_e32 v176, 16, v188
	v_and_b32_e32 v177, 0xffff0000, v188
	v_lshlrev_b32_e32 v178, 16, v189
	v_and_b32_e32 v179, 0xffff0000, v189
	v_lshlrev_b32_e32 v180, 16, v190
	v_and_b32_e32 v181, 0xffff0000, v190
	v_lshlrev_b32_e32 v182, 16, v191
	v_and_b32_e32 v183, 0xffff0000, v191
	v_pk_fma_f32 v[30:31], v[30:31], v[62:63], v[176:177]
	v_pk_fma_f32 v[32:33], v[32:33], v[64:65], v[178:179]
	v_pk_fma_f32 v[26:27], v[26:27], v[58:59], v[180:181]
	v_pk_fma_f32 v[28:29], v[28:29], v[60:61], v[182:183]
	s_add_u32 s94, s94, 0x10000
	s_addc_u32 s95, s95, 0
	v_cvt_pk_bf16_f32 v30, v30, v31
	v_cvt_pk_bf16_f32 v31, v32, v33
	v_cvt_pk_bf16_f32 v32, v26, v27
	v_cvt_pk_bf16_f32 v33, v28, v29
	global_store_dwordx4 v170, v[30:33], s[94:95]
	s_waitcnt vmcnt(13)
	v_lshlrev_b32_e32 v176, 16, v192
	v_and_b32_e32 v177, 0xffff0000, v192
	v_lshlrev_b32_e32 v178, 16, v193
	v_and_b32_e32 v179, 0xffff0000, v193
	v_lshlrev_b32_e32 v180, 16, v194
	v_and_b32_e32 v181, 0xffff0000, v194
	v_lshlrev_b32_e32 v182, 16, v195
	v_and_b32_e32 v183, 0xffff0000, v195
	v_pk_fma_f32 v[22:23], v[22:23], v[46:47], v[176:177]
	v_pk_fma_f32 v[24:25], v[24:25], v[48:49], v[178:179]
	v_pk_fma_f32 v[18:19], v[18:19], v[42:43], v[180:181]
	v_pk_fma_f32 v[20:21], v[20:21], v[44:45], v[182:183]
	v_cvt_pk_bf16_f32 v22, v22, v23
	v_cvt_pk_bf16_f32 v23, v24, v25
	v_cvt_pk_bf16_f32 v24, v18, v19
	v_cvt_pk_bf16_f32 v25, v20, v21
	global_store_dwordx4 v170, v[22:25], s[94:95] offset:256
	s_waitcnt vmcnt(12)
	v_lshlrev_b32_e32 v176, 16, v196
	v_and_b32_e32 v177, 0xffff0000, v196
	v_lshlrev_b32_e32 v178, 16, v197
	v_and_b32_e32 v179, 0xffff0000, v197
	v_lshlrev_b32_e32 v180, 16, v198
	v_and_b32_e32 v181, 0xffff0000, v198
	v_lshlrev_b32_e32 v182, 16, v199
	v_and_b32_e32 v183, 0xffff0000, v199
	v_pk_fma_f32 v[14:15], v[14:15], v[62:63], v[176:177]
	v_pk_fma_f32 v[16:17], v[16:17], v[64:65], v[178:179]
	v_pk_fma_f32 v[10:11], v[10:11], v[58:59], v[180:181]
	v_pk_fma_f32 v[12:13], v[12:13], v[60:61], v[182:183]
	s_add_u32 s94, s94, 0x10000
	s_addc_u32 s95, s95, 0
	v_cvt_pk_bf16_f32 v14, v14, v15
	v_cvt_pk_bf16_f32 v15, v16, v17
	v_cvt_pk_bf16_f32 v16, v10, v11
	v_cvt_pk_bf16_f32 v17, v12, v13
	global_store_dwordx4 v170, v[14:17], s[94:95]
	s_waitcnt vmcnt(11)
	v_lshlrev_b32_e32 v176, 16, v210
	v_and_b32_e32 v177, 0xffff0000, v210
	v_lshlrev_b32_e32 v178, 16, v211
	v_and_b32_e32 v179, 0xffff0000, v211
	v_lshlrev_b32_e32 v180, 16, v212
	v_and_b32_e32 v181, 0xffff0000, v212
	v_lshlrev_b32_e32 v182, 16, v213
	v_and_b32_e32 v183, 0xffff0000, v213
	v_pk_fma_f32 v[6:7], v[6:7], v[46:47], v[176:177]
	v_pk_fma_f32 v[8:9], v[8:9], v[48:49], v[178:179]
	v_pk_fma_f32 v[2:3], v[2:3], v[42:43], v[180:181]
	v_pk_fma_f32 v[4:5], v[4:5], v[44:45], v[182:183]
	v_cvt_pk_bf16_f32 v6, v6, v7
	v_cvt_pk_bf16_f32 v7, v8, v9
	v_cvt_pk_bf16_f32 v8, v2, v3
	v_cvt_pk_bf16_f32 v9, v4, v5
	global_store_dwordx4 v170, v[6:9], s[94:95] offset:256
	s_mov_b32 s2, s12
	s_mov_b64 s[20:21], s[14:15]
	s_mov_b64 s[18:19], s[16:17]
	s_and_b64 vcc, exec, s[4:5]
	s_nop 1
	s_cbranch_vccz .LBB0_112
	s_waitcnt vmcnt(0)
	s_cmpk_gt_u32 s29, 0xff
	s_cbranch_scc1 .LBB0_123
	s_barrier

; #define PG8_STAGE(bufoff, gbase, voff) do { _Pragma("unroll") for (int _i = 0; _i < 2; ++_i) \
;         __builtin_amdgcn_global_load_lds((const unsigned*)((const char*)(gbase) + (voff)[_i]), (LAS unsigned*)(lds + (bufoff) + ldsw + _i * 8192), 16, 0, 0); } while (0)
; #define PG8_LDA(dst, b, h) do { _Pragma("unroll") for (int m = 0; m < 4; ++m) _Pragma("unroll") for (int k = 0; k < 2; ++k) dst[m][k] = *(const LAS bf16x8*)(lds + PG8_SA(b, h) + aoff + m * 2048 + k * 1024); } while (0)
; #define PG8_LDB(dst, b, h) do { _Pragma("unroll") for (int n = 0; n < 2; ++n) _Pragma("unroll") for (int k = 0; k < 2; ++k) dst[n][k] = *(const LAS bf16x8*)(lds + PG8_SB(b, h) + boff + n * 2048 + k * 1024); } while (0)
; #define PG8_MMA(ai, bj, At, Bt) do { __builtin_amdgcn_s_setprio(1); _Pragma("unroll") for (int m = 0; m < 4; ++m) _Pragma("unroll") for (int n = 0; n < 2; ++n) _Pragma("unroll") for (int k = 0; k < 2; ++k) \
;         acc[ai][bj][m][n] = __builtin_amdgcn_mfma_f32_16x16x32_bf16(Bt[n][k], At[m][k], acc[ai][bj][m][n], 0, 0, 0); __builtin_amdgcn_s_setprio(0); } while (0)
; #define PG8_WAIT_L(n) asm volatile("s_waitcnt lgkmcnt(" #n ")" ::: "memory")
; #define PG8_BAR __builtin_amdgcn_s_barrier()
; #define PG8_SCHED __builtin_amdgcn_sched_barrier(0)
; template <class Epi>
; __device__ __forceinline__ void gemm_phase(LAS unsigned char* lds, const Gemm g, const StaticOrder& S, const Epi& E, const int tid) {
;     ...
;             PG8_LDB(B0, 0, 0); PG8_SCHED; PG8_LDA(At, 0, 0); PG8_STAGE(PG8_SA(1, 1), a1 + hstep, voffA);
;             PG8_WAIT_L(8); PG8_BAR; PG8_WAIT_L(0); PG8_MMA(0, 0, At, B0); PG8_BAR; PG8_SCHED;
;             PG8_LDB(B1, 0, 1); PG8_STAGE(PG8_SB(0, 0), b2, voffB);
;             PG8_BAR; PG8_WAIT_L(0); PG8_MMA(0, 1, At, B1); PG8_BAR;
;             PG8_LDA(At, 0, 1); PG8_STAGE(PG8_SA(0, 0), a2, voffA);
;             PG8_BAR; PG8_WAIT_L(0); PG8_MMA(1, 0, At, B0); PG8_BAR; PG8_SCHED;
.LBB0_141:
	s_add_u32 s20, s18, 0xfff80080
	s_addc_u32 s21, s19, -1
	s_add_i32 s50, 0, 0x10000
	v_add_u32_e32 v86, s50, v173
	ds_read_b128 v[66:69], v86
	ds_read_b128 v[70:73], v86 offset:1024
	ds_read_b128 v[82:85], v86 offset:2048
	ds_read_b128 v[86:89], v86 offset:3072
	s_cmp_eq_u32 s49, 28
	s_cselect_b32 s23, s13, s21
	s_cselect_b32 s22, s44, s20
	s_cselect_b32 s21, s11, s48
	s_cselect_b32 s20, s45, s47
	v_lshl_add_u64 v[170:171], s[18:19], 0, v[168:169]
	s_add_i32 m0, s3, 0xc000
	ds_read_b128 v[176:179], v174
	ds_read_b128 v[180:183], v174 offset:1024
	ds_read_b128 v[184:187], v174 offset:2048
	ds_read_b128 v[188:191], v174 offset:3072
	ds_read_b128 v[192:195], v174 offset:4096
	ds_read_b128 v[196:199], v174 offset:5120
	ds_read_b128 v[210:213], v174 offset:6144
	ds_read_b128 v[214:217], v174 offset:7168
	global_load_lds_dwordx4 v[170:171], off
	v_lshl_add_u64 v[170:171], s[18:19], 0, v[166:167]
	s_add_i32 m0, s3, 0xe000
	s_nop 0
	global_load_lds_dwordx4 v[170:171], off
	s_waitcnt lgkmcnt(8)
	s_barrier
	s_waitcnt lgkmcnt(0)
	s_setprio 1
	v_mfma_f32_16x16x32_bf16 v[142:145], v[66:69], v[176:179], v[142:145]
	v_mfma_f32_16x16x32_bf16 v[138:141], v[82:85], v[176:179], v[138:141]
	v_mfma_f32_16x16x32_bf16 v[126:129], v[66:69], v[184:187], v[126:129]
	v_mfma_f32_16x16x32_bf16 v[122:125], v[82:85], v[184:187], v[122:125]
	v_mfma_f32_16x16x32_bf16 v[110:113], v[66:69], v[192:195], v[110:113]
	v_mfma_f32_16x16x32_bf16 v[106:109], v[82:85], v[192:195], v[106:109]
	v_mfma_f32_16x16x32_bf16 v[94:97], v[66:69], v[210:213], v[94:97]
	v_mfma_f32_16x16x32_bf16 v[90:93], v[82:85], v[210:213], v[90:93]
	v_mfma_f32_16x16x32_bf16 v[142:145], v[70:73], v[180:183], v[142:145]
	v_mfma_f32_16x16x32_bf16 v[138:141], v[86:89], v[180:183], v[138:141]
	v_mfma_f32_16x16x32_bf16 v[126:129], v[70:73], v[188:191], v[126:129]
	v_mfma_f32_16x16x32_bf16 v[122:125], v[86:89], v[188:191], v[122:125]
	v_mfma_f32_16x16x32_bf16 v[110:113], v[70:73], v[196:199], v[110:113]
	v_mfma_f32_16x16x32_bf16 v[106:109], v[86:89], v[196:199], v[106:109]
	v_mfma_f32_16x16x32_bf16 v[94:97], v[70:73], v[214:217], v[94:97]
	v_mfma_f32_16x16x32_bf16 v[90:93], v[86:89], v[214:217], v[90:93]
	s_setprio 0
	s_barrier
	s_add_i32 s54, 0, 0x14000
	v_add_u32_e32 v170, s54, v173
	s_add_i32 s50, s50, s31
	ds_read_b128 v[218:221], v170
	ds_read_b128 v[222:225], v170 offset:1024
	ds_read_b128 v[226:229], v170 offset:2048
	ds_read_b128 v[230:233], v170 offset:3072
	v_lshl_add_u64 v[170:171], s[20:21], 0, v[0:1]
	s_mov_b32 m0, s50
	v_lshl_add_u64 v[200:201], s[20:21], 0, v[164:165]
	global_load_lds_dwordx4 v[170:171], off
	s_add_i32 m0, s50, 0x2000
	s_nop 0
	global_load_lds_dwordx4 v[200:201], off
	s_barrier
	s_waitcnt lgkmcnt(0)
	s_setprio 1
	v_mfma_f32_16x16x32_bf16 v[134:137], v[218:221], v[176:179], v[134:137]
	v_mfma_f32_16x16x32_bf16 v[130:133], v[226:229], v[176:179], v[130:133]
	v_mfma_f32_16x16x32_bf16 v[118:121], v[218:221], v[184:187], v[118:121]
	v_mfma_f32_16x16x32_bf16 v[114:117], v[226:229], v[184:187], v[114:117]
	v_mfma_f32_16x16x32_bf16 v[102:105], v[218:221], v[192:195], v[102:105]
	v_mfma_f32_16x16x32_bf16 v[98:101], v[226:229], v[192:195], v[98:101]
	v_mfma_f32_16x16x32_bf16 v[78:81], v[218:221], v[210:213], v[78:81]
	v_mfma_f32_16x16x32_bf16 v[74:77], v[226:229], v[210:213], v[74:77]
	v_mfma_f32_16x16x32_bf16 v[134:137], v[222:225], v[180:183], v[134:137]
	v_mfma_f32_16x16x32_bf16 v[130:133], v[230:233], v[180:183], v[130:133]
	v_mfma_f32_16x16x32_bf16 v[118:121], v[222:225], v[188:191], v[118:121]
	v_mfma_f32_16x16x32_bf16 v[114:117], v[230:233], v[188:191], v[114:117]
	v_mfma_f32_16x16x32_bf16 v[102:105], v[222:225], v[196:199], v[102:105]
	v_mfma_f32_16x16x32_bf16 v[98:101], v[230:233], v[196:199], v[98:101]
	v_mfma_f32_16x16x32_bf16 v[78:81], v[222:225], v[214:217], v[78:81]
	v_mfma_f32_16x16x32_bf16 v[74:77], v[230:233], v[214:217], v[74:77]
	s_setprio 0
	s_mov_b32 m0, s3
	v_lshl_add_u64 v[234:235], s[22:23], 0, v[160:161]
	s_barrier
	ds_read_b128 v[176:179], v174 offset:16384
	ds_read_b128 v[180:183], v174 offset:17408
	ds_read_b128 v[184:187], v174 offset:18432
	ds_read_b128 v[188:191], v174 offset:19456
	ds_read_b128 v[192:195], v174 offset:20480
	ds_read_b128 v[196:199], v174 offset:21504
	ds_read_b128 v[210:213], v174 offset:22528
	ds_read_b128 v[214:217], v174 offset:23552
	global_load_lds_dwordx4 v[234:235], off
	v_lshl_add_u64 v[236:237], s[22:23], 0, v[162:163]
	s_mov_b32 m0, s34
	s_nop 0
	global_load_lds_dwordx4 v[236:237], off
	s_barrier
	s_waitcnt lgkmcnt(0)
	s_setprio 1
	v_mfma_f32_16x16x32_bf16 v[62:65], v[66:69], v[176:179], v[62:65]
	v_mfma_f32_16x16x32_bf16 v[58:61], v[82:85], v[176:179], v[58:61]
	v_mfma_f32_16x16x32_bf16 v[46:49], v[66:69], v[184:187], v[46:49]
	v_mfma_f32_16x16x32_bf16 v[42:45], v[82:85], v[184:187], v[42:45]
	v_mfma_f32_16x16x32_bf16 v[30:33], v[66:69], v[192:195], v[30:33]
	v_mfma_f32_16x16x32_bf16 v[26:29], v[82:85], v[192:195], v[26:29]
	v_mfma_f32_16x16x32_bf16 v[14:17], v[66:69], v[210:213], v[14:17]
	v_mfma_f32_16x16x32_bf16 v[10:13], v[82:85], v[210:213], v[10:13]
	v_mfma_f32_16x16x32_bf16 v[62:65], v[70:73], v[180:183], v[62:65]
	v_mfma_f32_16x16x32_bf16 v[58:61], v[86:89], v[180:183], v[58:61]
	v_mfma_f32_16x16x32_bf16 v[46:49], v[70:73], v[188:191], v[46:49]
	v_mfma_f32_16x16x32_bf16 v[42:45], v[86:89], v[188:191], v[42:45]
	v_mfma_f32_16x16x32_bf16 v[30:33], v[70:73], v[196:199], v[30:33]
	v_mfma_f32_16x16x32_bf16 v[26:29], v[86:89], v[196:199], v[26:29]
	v_mfma_f32_16x16x32_bf16 v[14:17], v[70:73], v[214:217], v[14:17]
	v_mfma_f32_16x16x32_bf16 v[10:13], v[86:89], v[214:217], v[10:13]
	s_setprio 0
	s_barrier
; #define PG8_STAGE(bufoff, gbase, voff) do { _Pragma("unroll") for (int _i = 0; _i < 2; ++_i) \
;         __builtin_amdgcn_global_load_lds((const unsigned*)((const char*)(gbase) + (voff)[_i]), (LAS unsigned*)(lds + (bufoff) + ldsw + _i * 8192), 16, 0, 0); } while (0)
; #define PG8_LDA(dst, b, h) do { _Pragma("unroll") for (int m = 0; m < 4; ++m) _Pragma("unroll") for (int k = 0; k < 2; ++k) dst[m][k] = *(const LAS bf16x8*)(lds + PG8_SA(b, h) + aoff + m * 2048 + k * 1024); } while (0)
; #define PG8_LDB(dst, b, h) do { _Pragma("unroll") for (int n = 0; n < 2; ++n) _Pragma("unroll") for (int k = 0; k < 2; ++k) dst[n][k] = *(const LAS bf16x8*)(lds + PG8_SB(b, h) + boff + n * 2048 + k * 1024); } while (0)
; #define PG8_MMA(ai, bj, At, Bt) do { __builtin_amdgcn_s_setprio(1); _Pragma("unroll") for (int m = 0; m < 4; ++m) _Pragma("unroll") for (int n = 0; n < 2; ++n) _Pragma("unroll") for (int k = 0; k < 2; ++k) \
;         acc[ai][bj][m][n] = __builtin_amdgcn_mfma_f32_16x16x32_bf16(Bt[n][k], At[m][k], acc[ai][bj][m][n], 0, 0, 0); __builtin_amdgcn_s_setprio(0); } while (0)
; #define PG8_WAIT_V(n) asm volatile("s_waitcnt vmcnt(" #n ")" ::: "memory")
; #define PG8_WAIT_L(n) asm volatile("s_waitcnt lgkmcnt(" #n ")" ::: "memory")
; #define PG8_BAR __builtin_amdgcn_s_barrier()
; #define PG8_SCHED __builtin_amdgcn_sched_barrier(0)
; template <class Epi>
; __device__ __forceinline__ void gemm_phase(LAS unsigned char* lds, const Gemm g, const StaticOrder& S, const Epi& E, const int tid) {
;     ...
;             PG8_STAGE(PG8_SB(0, 1), b2 + hstep, voffB);
;             PG8_WAIT_V(6); PG8_BAR; PG8_MMA(1, 1, At, B1); PG8_BAR;
;             PG8_LDB(B0, 1, 0); PG8_SCHED; PG8_LDA(At, 1, 0); PG8_STAGE(PG8_SA(0, 1), a2 + hstep, voffA);
;             PG8_WAIT_L(8); PG8_BAR; PG8_WAIT_L(0); PG8_MMA(0, 0, At, B0); PG8_BAR; PG8_SCHED;
;             PG8_LDB(B1, 1, 1); PG8_STAGE(PG8_SB(1, 0), b3, voffB);
;             PG8_BAR; PG8_WAIT_L(0); PG8_MMA(0, 1, At, B1); PG8_BAR;
	s_add_u32 s52, s20, 0x80000
	s_addc_u32 s53, s21, 0
	s_add_i32 s50, s54, s31
	v_lshl_add_u64 v[66:67], s[52:53], 0, v[0:1]
	s_mov_b32 m0, s50
	s_nop 0
	global_load_lds_dwordx4 v[66:67], off
	v_lshl_add_u64 v[66:67], s[52:53], 0, v[164:165]
	s_add_i32 m0, s50, 0x2000
	s_nop 0
	global_load_lds_dwordx4 v[66:67], off
	s_waitcnt vmcnt(6)
	s_barrier
	s_setprio 1
	v_mfma_f32_16x16x32_bf16 v[54:57], v[218:221], v[176:179], v[54:57]
	v_mfma_f32_16x16x32_bf16 v[50:53], v[226:229], v[176:179], v[50:53]
	v_mfma_f32_16x16x32_bf16 v[38:41], v[218:221], v[184:187], v[38:41]
	v_mfma_f32_16x16x32_bf16 v[34:37], v[226:229], v[184:187], v[34:37]
	v_mfma_f32_16x16x32_bf16 v[22:25], v[218:221], v[192:195], v[22:25]
	v_mfma_f32_16x16x32_bf16 v[18:21], v[226:229], v[192:195], v[18:21]
	v_mfma_f32_16x16x32_bf16 v[6:9], v[218:221], v[210:213], v[6:9]
	v_mfma_f32_16x16x32_bf16 v[2:5], v[226:229], v[210:213], v[2:5]
	v_mfma_f32_16x16x32_bf16 v[54:57], v[222:225], v[180:183], v[54:57]
	v_mfma_f32_16x16x32_bf16 v[50:53], v[230:233], v[180:183], v[50:53]
	v_mfma_f32_16x16x32_bf16 v[38:41], v[222:225], v[188:191], v[38:41]
	v_mfma_f32_16x16x32_bf16 v[34:37], v[230:233], v[188:191], v[34:37]
	v_mfma_f32_16x16x32_bf16 v[22:25], v[222:225], v[196:199], v[22:25]
	v_mfma_f32_16x16x32_bf16 v[18:21], v[230:233], v[196:199], v[18:21]
	v_mfma_f32_16x16x32_bf16 v[6:9], v[222:225], v[214:217], v[6:9]
	v_mfma_f32_16x16x32_bf16 v[2:5], v[230:233], v[214:217], v[2:5]
	s_setprio 0
	s_add_i32 s50, 0, 0x18000
	v_add_u32_e32 v86, s50, v173
	s_barrier
	ds_read_b128 v[66:69], v86
	ds_read_b128 v[70:73], v86 offset:1024
	ds_read_b128 v[82:85], v86 offset:2048
	ds_read_b128 v[86:89], v86 offset:3072
	s_add_u32 s22, s22, 0x80000
	s_addc_u32 s23, s23, 0
	s_mov_b32 m0, s35
	v_lshl_add_u64 v[218:219], s[22:23], 0, v[160:161]
	ds_read_b128 v[176:179], v174 offset:32768
	ds_read_b128 v[180:183], v174 offset:33792
	ds_read_b128 v[184:187], v174 offset:34816
	ds_read_b128 v[188:191], v174 offset:35840
	ds_read_b128 v[192:195], v174 offset:36864
	ds_read_b128 v[196:199], v174 offset:37888
	ds_read_b128 v[210:213], v174 offset:38912
	ds_read_b128 v[214:217], v174 offset:39936
	global_load_lds_dwordx4 v[218:219], off
	v_lshl_add_u64 v[218:219], s[22:23], 0, v[162:163]
	s_mov_b32 m0, s36
	s_nop 0
	global_load_lds_dwordx4 v[218:219], off
	s_waitcnt lgkmcnt(8)
	s_barrier
	s_waitcnt lgkmcnt(0)
	s_setprio 1
	v_mfma_f32_16x16x32_bf16 v[142:145], v[66:69], v[176:179], v[142:145]
	v_mfma_f32_16x16x32_bf16 v[138:141], v[82:85], v[176:179], v[138:141]
	v_mfma_f32_16x16x32_bf16 v[126:129], v[66:69], v[184:187], v[126:129]
	v_mfma_f32_16x16x32_bf16 v[122:125], v[82:85], v[184:187], v[122:125]
	v_mfma_f32_16x16x32_bf16 v[110:113], v[66:69], v[192:195], v[110:113]
	v_mfma_f32_16x16x32_bf16 v[106:109], v[82:85], v[192:195], v[106:109]
	v_mfma_f32_16x16x32_bf16 v[94:97], v[66:69], v[210:213], v[94:97]
	v_mfma_f32_16x16x32_bf16 v[90:93], v[82:85], v[210:213], v[90:93]
	v_mfma_f32_16x16x32_bf16 v[142:145], v[70:73], v[180:183], v[142:145]
	v_mfma_f32_16x16x32_bf16 v[138:141], v[86:89], v[180:183], v[138:141]
	v_mfma_f32_16x16x32_bf16 v[126:129], v[70:73], v[188:191], v[126:129]
	v_mfma_f32_16x16x32_bf16 v[122:125], v[86:89], v[188:191], v[122:125]
	v_mfma_f32_16x16x32_bf16 v[110:113], v[70:73], v[196:199], v[110:113]
	v_mfma_f32_16x16x32_bf16 v[106:109], v[86:89], v[196:199], v[106:109]
	v_mfma_f32_16x16x32_bf16 v[94:97], v[70:73], v[214:217], v[94:97]
	v_mfma_f32_16x16x32_bf16 v[90:93], v[86:89], v[214:217], v[90:93]
	s_setprio 0
	s_barrier
	s_add_i32 s22, 0, 0x1c000
	s_add_i32 s23, s50, s31
	v_add_u32_e32 v175, s22, v173
	v_lshl_add_u64 v[170:171], v[170:171], 0, s[56:57]
	s_mov_b32 m0, s23
	ds_read_b128 v[218:221], v175
	ds_read_b128 v[222:225], v175 offset:1024
	ds_read_b128 v[226:229], v175 offset:2048
	ds_read_b128 v[230:233], v175 offset:3072
	global_load_lds_dwordx4 v[170:171], off
	v_lshl_add_u64 v[170:171], v[200:201], 0, s[56:57]
	s_add_i32 m0, s23, 0x2000
	s_nop 0
	global_load_lds_dwordx4 v[170:171], off
	s_barrier
	s_waitcnt lgkmcnt(0)
	s_setprio 1
	v_mfma_f32_16x16x32_bf16 v[134:137], v[218:221], v[176:179], v[134:137]
	v_mfma_f32_16x16x32_bf16 v[130:133], v[226:229], v[176:179], v[130:133]
	v_mfma_f32_16x16x32_bf16 v[118:121], v[218:221], v[184:187], v[118:121]
	v_mfma_f32_16x16x32_bf16 v[114:117], v[226:229], v[184:187], v[114:117]
	v_mfma_f32_16x16x32_bf16 v[102:105], v[218:221], v[192:195], v[102:105]
	v_mfma_f32_16x16x32_bf16 v[98:101], v[226:229], v[192:195], v[98:101]
	v_mfma_f32_16x16x32_bf16 v[78:81], v[218:221], v[210:213], v[78:81]
	v_mfma_f32_16x16x32_bf16 v[74:77], v[226:229], v[210:213], v[74:77]
	v_mfma_f32_16x16x32_bf16 v[134:137], v[222:225], v[180:183], v[134:137]
	v_mfma_f32_16x16x32_bf16 v[130:133], v[230:233], v[180:183], v[130:133]
	v_mfma_f32_16x16x32_bf16 v[118:121], v[222:225], v[188:191], v[118:121]
	v_mfma_f32_16x16x32_bf16 v[114:117], v[230:233], v[188:191], v[114:117]
	v_mfma_f32_16x16x32_bf16 v[102:105], v[222:225], v[196:199], v[102:105]
	v_mfma_f32_16x16x32_bf16 v[98:101], v[230:233], v[196:199], v[98:101]
	v_mfma_f32_16x16x32_bf16 v[78:81], v[222:225], v[214:217], v[78:81]
	v_mfma_f32_16x16x32_bf16 v[74:77], v[230:233], v[214:217], v[74:77]
	s_setprio 0
	s_mov_b32 m0, s39
	v_lshl_add_u64 v[170:171], v[234:235], 0, s[56:57]
	s_barrier
	ds_read_b128 v[176:179], v174 offset:49152
	ds_read_b128 v[180:183], v174 offset:50176
	ds_read_b128 v[184:187], v174 offset:51200
	ds_read_b128 v[188:191], v174 offset:52224
	ds_read_b128 v[192:195], v174 offset:53248
	ds_read_b128 v[196:199], v174 offset:54272
	ds_read_b128 v[210:213], v174 offset:55296
	ds_read_b128 v[214:217], v174 offset:56320
	global_load_lds_dwordx4 v[170:171], off
	v_lshl_add_u64 v[170:171], v[236:237], 0, s[56:57]
	s_mov_b32 m0, s40
	s_nop 0
	global_load_lds_dwordx4 v[170:171], off
	s_barrier
; __device__ __forceinline__ unsigned pk2(float lo, float hi) { f32x2 v = {lo, hi}; return __builtin_bit_cast(unsigned, __builtin_convertvector(v, bf16x2_t)); }
; __device__ __forceinline__ float bf_lo(unsigned w) { return __uint_as_float(w << 16); }
;     __device__ __forceinline__ void operator()(const f32x4 (&acc)[2][2][4][2], const Unit& u, int wr, int wc, int fr, int fq) const {
;         asm volatile("" : "+v"(fr), "+v"(fq));
;         const int row0 = u.pm * BM + wr * 64 + fr, col0 = u.pn * BM + wc * 32 + 8 * fq;
;         const float* gp = gate + (size_t)(u.pm >> 5) * 12288 + col0;
;         f32x4 gv[2][2];
; #pragma unroll
;         for (int bj = 0; bj < 2; ++bj)
; #pragma unroll
;             for (int n = 0; n < 2; ++n) gv[bj][n] = *(const f32x4*)(gp + bj * HALF + 4 * n);
; #pragma unroll
;         for (int ai = 0; ai < 2; ++ai)
; #pragma unroll
;             for (int m = 0; m < 4; ++m) {
;                 const size_t ro = (size_t)(row0 + ai * HALF + m * 16) * DM + col0;
; #pragma unroll
;                 for (int bj = 0; bj < 2; ++bj) {
;                     f32x4 r0, r1;
;                     if (RB) { const u32x4 rw = *(const u32x4*)((const bf16_t*)resid + ro + bj * HALF);
;                         r0 = (f32x4){bf_lo(rw.x), bf_hi(rw.x), bf_lo(rw.y), bf_hi(rw.y)}; r1 = (f32x4){bf_lo(rw.z), bf_hi(rw.z), bf_lo(rw.w), bf_hi(rw.w)}; }
;                     else { r0 = *(const f32x4*)((const float*)resid + ro + bj * HALF); r1 = *(const f32x4*)((const float*)resid + ro + bj * HALF + 4); }
;                     const f32x4 v0 = r0 + gv[bj][0] * acc[ai][bj][m][0], v1 = r1 + gv[bj][1] * acc[ai][bj][m][1];
;                     if (OB) { u32x4 w; w.x = pk2(v0[0], v0[1]); w.y = pk2(v0[2], v0[3]); w.z = pk2(v1[0], v1[1]); w.w = pk2(v1[2], v1[3]); *(u32x4*)((bf16_t*)out + ro + bj * HALF) = w; }
;                     else { *(f32x4*)((float*)out + ro + bj * HALF) = v0; *(f32x4*)((float*)out + ro + bj * HALF + 4) = v1; }
; template <class Epi>
; __device__ __forceinline__ void gemm_phase(LAS unsigned char* lds, const Gemm g, const StaticOrder& S, const Epi& E, const int tid) {
;     ...
;             PG8_LDA(At, 1, 1); PG8_STAGE(PG8_SA(1, 0), a3, voffA);
;             PG8_BAR; PG8_WAIT_L(0); PG8_MMA(1, 0, At, B0); PG8_BAR; PG8_SCHED;
;             PG8_STAGE(PG8_SB(1, 1), b3 + hstep, voffB);
;             PG8_WAIT_V(6); PG8_BAR; PG8_MMA(1, 1, At, B1); PG8_BAR;
	s_waitcnt lgkmcnt(0)
	s_setprio 1
	v_mfma_f32_16x16x32_bf16 v[62:65], v[66:69], v[176:179], v[62:65]
	v_mfma_f32_16x16x32_bf16 v[58:61], v[82:85], v[176:179], v[58:61]
	v_mfma_f32_16x16x32_bf16 v[46:49], v[66:69], v[184:187], v[46:49]
	v_mfma_f32_16x16x32_bf16 v[42:45], v[82:85], v[184:187], v[42:45]
	v_mfma_f32_16x16x32_bf16 v[30:33], v[66:69], v[192:195], v[30:33]
	v_mfma_f32_16x16x32_bf16 v[26:29], v[82:85], v[192:195], v[26:29]
	v_mfma_f32_16x16x32_bf16 v[14:17], v[66:69], v[210:213], v[14:17]
	v_mfma_f32_16x16x32_bf16 v[10:13], v[82:85], v[210:213], v[10:13]
	v_mfma_f32_16x16x32_bf16 v[62:65], v[70:73], v[180:183], v[62:65]
	v_mfma_f32_16x16x32_bf16 v[58:61], v[86:89], v[180:183], v[58:61]
	v_mfma_f32_16x16x32_bf16 v[46:49], v[70:73], v[188:191], v[46:49]
	v_mfma_f32_16x16x32_bf16 v[42:45], v[86:89], v[188:191], v[42:45]
	v_mfma_f32_16x16x32_bf16 v[30:33], v[70:73], v[196:199], v[30:33]
	v_mfma_f32_16x16x32_bf16 v[26:29], v[86:89], v[196:199], v[26:29]
	v_mfma_f32_16x16x32_bf16 v[14:17], v[70:73], v[214:217], v[14:17]
	v_mfma_f32_16x16x32_bf16 v[10:13], v[86:89], v[214:217], v[10:13]
	s_setprio 0
	s_barrier
	s_add_u32 s20, s20, 0x80080
	s_addc_u32 s21, s21, 0
	s_add_i32 s22, s22, s31
	v_lshl_add_u64 v[66:67], s[20:21], 0, v[0:1]
	s_mov_b32 m0, s22
	s_nop 0
	global_load_lds_dwordx4 v[66:67], off
	v_lshl_add_u64 v[66:67], s[20:21], 0, v[164:165]
	s_add_i32 m0, s22, 0x2000
	s_nop 0
	global_load_lds_dwordx4 v[66:67], off
	s_waitcnt vmcnt(6)
	s_barrier
	s_setprio 1
	v_mfma_f32_16x16x32_bf16 v[54:57], v[218:221], v[176:179], v[54:57]
	v_mfma_f32_16x16x32_bf16 v[50:53], v[226:229], v[176:179], v[50:53]
	v_mfma_f32_16x16x32_bf16 v[38:41], v[218:221], v[184:187], v[38:41]
	v_mfma_f32_16x16x32_bf16 v[34:37], v[226:229], v[184:187], v[34:37]
	v_mfma_f32_16x16x32_bf16 v[22:25], v[218:221], v[192:195], v[22:25]
	v_mfma_f32_16x16x32_bf16 v[18:21], v[226:229], v[192:195], v[18:21]
	v_mfma_f32_16x16x32_bf16 v[6:9], v[218:221], v[210:213], v[6:9]
	v_mfma_f32_16x16x32_bf16 v[2:5], v[226:229], v[210:213], v[2:5]
	v_mfma_f32_16x16x32_bf16 v[54:57], v[222:225], v[180:183], v[54:57]
	v_mfma_f32_16x16x32_bf16 v[50:53], v[230:233], v[180:183], v[50:53]
	v_mfma_f32_16x16x32_bf16 v[38:41], v[222:225], v[188:191], v[38:41]
	v_mfma_f32_16x16x32_bf16 v[34:37], v[230:233], v[188:191], v[34:37]
	v_mfma_f32_16x16x32_bf16 v[22:25], v[222:225], v[196:199], v[22:25]
	v_mfma_f32_16x16x32_bf16 v[18:21], v[230:233], v[196:199], v[18:21]
	v_mfma_f32_16x16x32_bf16 v[6:9], v[222:225], v[214:217], v[6:9]
	v_mfma_f32_16x16x32_bf16 v[2:5], v[230:233], v[214:217], v[2:5]
	s_setprio 0
	s_add_i32 s49, s49, 2
	s_add_u32 s47, s47, 0x100
	s_addc_u32 s48, s48, 0
	s_add_u32 s18, s18, 0x100
	s_addc_u32 s19, s19, 0
	s_cmp_gt_u32 s49, 29
	s_barrier
	s_cbranch_scc0 .LBB0_141
	s_lshl_b32 s11, s2, 8
	s_lshl_b32 s13, s43, 8
	v_mov_b32_e32 v66, v172
	v_mov_b32_e32 v175, v159
	s_add_i32 s11, s11, s37
	s_or_b32 s13, s13, s38
	s_ashr_i32 s2, s2, 5
	s_mov_b32 s43, s10
	v_lshl_add_u32 v170, v66, 3, s13
	s_mul_hi_i32 s13, s2, 0xc000
	s_mul_i32 s2, s2, 0xc000
	v_add_u32_e32 v176, s11, v175
	s_add_u32 s18, s27, s2
	v_ashrrev_i32_e32 v177, 31, v176
	s_addc_u32 s19, s28, s13
	v_ashrrev_i32_e32 v171, 31, v170
	v_lshlrev_b64 v[176:177], 11, v[176:177]
	v_lshl_add_u64 v[70:71], v[170:171], 2, s[18:19]
	v_lshl_add_u64 v[170:171], v[176:177], 0, v[170:171]
	v_lshl_add_u64 v[184:185], v[170:171], 2, s[8:9]
	global_load_dwordx4 v[82:85], v[70:71], off offset:16
	global_load_dwordx4 v[86:89], v[70:71], off
	global_load_dwordx4 v[66:69], v[70:71], off offset:528
	s_nop 0
	global_load_dwordx4 v[70:73], v[70:71], off offset:512
	v_lshlrev_b32_e32 v175, 2, v170
	v_lshlrev_b32_e32 v200, 1, v170
	s_mov_b64 s[92:93], s[8:9]
	s_mov_b64 s[94:95], s[6:7]
	global_load_dwordx4 v[176:179], v175, s[92:93]
	global_load_dwordx4 v[180:183], v175, s[92:93] offset:16
	global_load_dwordx4 v[184:187], v175, s[92:93] offset:512
	global_load_dwordx4 v[188:191], v175, s[92:93] offset:528
	s_add_u32 s92, s92, 0x20000
	s_addc_u32 s93, s93, 0
	global_load_dwordx4 v[192:195], v175, s[92:93]
	global_load_dwordx4 v[196:199], v175, s[92:93] offset:16
	global_load_dwordx4 v[210:213], v175, s[92:93] offset:512
	global_load_dwordx4 v[214:217], v175, s[92:93] offset:528
	s_add_u32 s92, s92, 0x20000
	s_addc_u32 s93, s93, 0
	global_load_dwordx4 v[218:221], v175, s[92:93]
	global_load_dwordx4 v[222:225], v175, s[92:93] offset:16
	global_load_dwordx4 v[226:229], v175, s[92:93] offset:512
	global_load_dwordx4 v[230:233], v175, s[92:93] offset:528
	s_waitcnt vmcnt(10)
	v_pk_fma_f32 v[142:143], v[142:143], v[86:87], v[176:177]
	v_pk_fma_f32 v[144:145], v[144:145], v[88:89], v[178:179]
	v_pk_fma_f32 v[138:139], v[138:139], v[82:83], v[180:181]
	v_pk_fma_f32 v[140:141], v[140:141], v[84:85], v[182:183]
	s_add_u32 s92, s92, 0x20000
	s_addc_u32 s93, s93, 0
	global_load_dwordx4 v[176:179], v175, s[92:93]
	global_load_dwordx4 v[180:183], v175, s[92:93] offset:16
	v_cvt_pk_bf16_f32 v142, v142, v143
	v_cvt_pk_bf16_f32 v143, v144, v145
	v_cvt_pk_bf16_f32 v144, v138, v139
	v_cvt_pk_bf16_f32 v145, v140, v141
	global_store_dwordx4 v200, v[142:145], s[94:95]
	s_waitcnt vmcnt(11)
	v_pk_fma_f32 v[134:135], v[134:135], v[70:71], v[184:185]
	v_pk_fma_f32 v[136:137], v[136:137], v[72:73], v[186:187]
	v_pk_fma_f32 v[130:131], v[130:131], v[66:67], v[188:189]
	v_pk_fma_f32 v[132:133], v[132:133], v[68:69], v[190:191]
	global_load_dwordx4 v[184:187], v175, s[92:93] offset:512
	global_load_dwordx4 v[188:191], v175, s[92:93] offset:528
	v_cvt_pk_bf16_f32 v134, v134, v135
	v_cvt_pk_bf16_f32 v135, v136, v137
	v_cvt_pk_bf16_f32 v136, v130, v131
	v_cvt_pk_bf16_f32 v137, v132, v133
	global_store_dwordx4 v200, v[134:137], s[94:95] offset:256
	s_waitcnt vmcnt(12)
; __device__ __forceinline__ unsigned pk2(float lo, float hi) { f32x2 v = {lo, hi}; return __builtin_bit_cast(unsigned, __builtin_convertvector(v, bf16x2_t)); }
; __device__ __forceinline__ float bf_lo(unsigned w) { return __uint_as_float(w << 16); }
; __device__ __forceinline__ float bf_hi(unsigned w) { return __uint_as_float(w & 0xffff0000u); }
;     __device__ __forceinline__ void operator()(const f32x4 (&acc)[2][2][4][2], const Unit& u, int wr, int wc, int fr, int fq) const {
;     ...
;             for (int m = 0; m < 4; ++m) {
;                 const size_t ro = (size_t)(row0 + ai * HALF + m * 16) * DM + col0;
; #pragma unroll
;                 for (int bj = 0; bj < 2; ++bj) {
;                     f32x4 r0, r1;
;                     if (RB) { const u32x4 rw = *(const u32x4*)((const bf16_t*)resid + ro + bj * HALF);
;                         r0 = (f32x4){bf_lo(rw.x), bf_hi(rw.x), bf_lo(rw.y), bf_hi(rw.y)}; r1 = (f32x4){bf_lo(rw.z), bf_hi(rw.z), bf_lo(rw.w), bf_hi(rw.w)}; }
;                     else { r0 = *(const f32x4*)((const float*)resid + ro + bj * HALF); r1 = *(const f32x4*)((const float*)resid + ro + bj * HALF + 4); }
;                     const f32x4 v0 = r0 + gv[bj][0] * acc[ai][bj][m][0], v1 = r1 + gv[bj][1] * acc[ai][bj][m][1];
;                     if (OB) { u32x4 w; w.x = pk2(v0[0], v0[1]); w.y = pk2(v0[2], v0[3]); w.z = pk2(v1[0], v1[1]); w.w = pk2(v1[2], v1[3]); *(u32x4*)((bf16_t*)out + ro + bj * HALF) = w; }
;                     else { *(f32x4*)((float*)out + ro + bj * HALF) = v0; *(f32x4*)((float*)out + ro + bj * HALF + 4) = v1; }
;                 }
	v_pk_fma_f32 v[126:127], v[126:127], v[86:87], v[192:193]
	v_pk_fma_f32 v[128:129], v[128:129], v[88:89], v[194:195]
	v_pk_fma_f32 v[122:123], v[122:123], v[82:83], v[196:197]
	v_pk_fma_f32 v[124:125], v[124:125], v[84:85], v[198:199]
	s_add_u32 s92, s92, 0xa0000
	s_addc_u32 s93, s93, 0
	global_load_dwordx4 v[192:195], v175, s[92:93]
	global_load_dwordx4 v[196:199], v175, s[92:93] offset:16
	s_add_u32 s94, s94, 0x10000
	s_addc_u32 s95, s95, 0
	v_cvt_pk_bf16_f32 v126, v126, v127
	v_cvt_pk_bf16_f32 v127, v128, v129
	v_cvt_pk_bf16_f32 v128, v122, v123
	v_cvt_pk_bf16_f32 v129, v124, v125
	global_store_dwordx4 v200, v[126:129], s[94:95]
	s_waitcnt vmcnt(13)
	v_pk_fma_f32 v[118:119], v[118:119], v[70:71], v[210:211]
	v_pk_fma_f32 v[120:121], v[120:121], v[72:73], v[212:213]
	v_pk_fma_f32 v[114:115], v[114:115], v[66:67], v[214:215]
	v_pk_fma_f32 v[116:117], v[116:117], v[68:69], v[216:217]
	global_load_dwordx4 v[210:213], v175, s[92:93] offset:512
	global_load_dwordx4 v[214:217], v175, s[92:93] offset:528
	v_cvt_pk_bf16_f32 v118, v118, v119
	v_cvt_pk_bf16_f32 v119, v120, v121
	v_cvt_pk_bf16_f32 v120, v114, v115
	v_cvt_pk_bf16_f32 v121, v116, v117
	global_store_dwordx4 v200, v[118:121], s[94:95] offset:256
	s_waitcnt vmcnt(14)
	v_pk_fma_f32 v[110:111], v[110:111], v[86:87], v[218:219]
	v_pk_fma_f32 v[112:113], v[112:113], v[88:89], v[220:221]
	v_pk_fma_f32 v[106:107], v[106:107], v[82:83], v[222:223]
	v_pk_fma_f32 v[108:109], v[108:109], v[84:85], v[224:225]
	s_add_u32 s92, s92, 0x20000
	s_addc_u32 s93, s93, 0
	global_load_dwordx4 v[218:221], v175, s[92:93]
	global_load_dwordx4 v[222:225], v175, s[92:93] offset:16
	s_add_u32 s94, s94, 0x10000
	s_addc_u32 s95, s95, 0
	v_cvt_pk_bf16_f32 v110, v110, v111
	v_cvt_pk_bf16_f32 v111, v112, v113
	v_cvt_pk_bf16_f32 v112, v106, v107
	v_cvt_pk_bf16_f32 v113, v108, v109
	global_store_dwordx4 v200, v[110:113], s[94:95]
	s_waitcnt vmcnt(15)
	v_pk_fma_f32 v[102:103], v[102:103], v[70:71], v[226:227]
	v_pk_fma_f32 v[104:105], v[104:105], v[72:73], v[228:229]
	v_pk_fma_f32 v[98:99], v[98:99], v[66:67], v[230:231]
	v_pk_fma_f32 v[100:101], v[100:101], v[68:69], v[232:233]
	global_load_dwordx4 v[226:229], v175, s[92:93] offset:512
	global_load_dwordx4 v[230:233], v175, s[92:93] offset:528
	v_cvt_pk_bf16_f32 v102, v102, v103
	v_cvt_pk_bf16_f32 v103, v104, v105
	v_cvt_pk_bf16_f32 v104, v98, v99
	v_cvt_pk_bf16_f32 v105, v100, v101
	global_store_dwordx4 v200, v[102:105], s[94:95] offset:256
	s_waitcnt vmcnt(16)
	v_pk_fma_f32 v[94:95], v[94:95], v[86:87], v[176:177]
	v_pk_fma_f32 v[96:97], v[96:97], v[88:89], v[178:179]
	v_pk_fma_f32 v[90:91], v[90:91], v[82:83], v[180:181]
	v_pk_fma_f32 v[92:93], v[92:93], v[84:85], v[182:183]
	s_add_u32 s92, s92, 0x20000
	s_addc_u32 s93, s93, 0
	global_load_dwordx4 v[176:179], v175, s[92:93]
	global_load_dwordx4 v[180:183], v175, s[92:93] offset:16
	s_add_u32 s94, s94, 0x10000
	s_addc_u32 s95, s95, 0
	v_cvt_pk_bf16_f32 v94, v94, v95
	v_cvt_pk_bf16_f32 v95, v96, v97
	v_cvt_pk_bf16_f32 v96, v90, v91
	v_cvt_pk_bf16_f32 v97, v92, v93
	global_store_dwordx4 v200, v[94:97], s[94:95]
	s_waitcnt vmcnt(16)
	v_pk_fma_f32 v[78:79], v[78:79], v[70:71], v[184:185]
	v_pk_fma_f32 v[80:81], v[80:81], v[72:73], v[186:187]
	v_pk_fma_f32 v[74:75], v[74:75], v[66:67], v[188:189]
	v_pk_fma_f32 v[76:77], v[76:77], v[68:69], v[190:191]
	global_load_dwordx4 v[184:187], v175, s[92:93] offset:512
	global_load_dwordx4 v[188:191], v175, s[92:93] offset:528
	v_cvt_pk_bf16_f32 v78, v78, v79
	v_cvt_pk_bf16_f32 v79, v80, v81
	v_cvt_pk_bf16_f32 v80, v74, v75
	v_cvt_pk_bf16_f32 v81, v76, v77
	global_store_dwordx4 v200, v[78:81], s[94:95] offset:256
	s_waitcnt vmcnt(16)
; __device__ __forceinline__ unsigned pk2(float lo, float hi) { f32x2 v = {lo, hi}; return __builtin_bit_cast(unsigned, __builtin_convertvector(v, bf16x2_t)); }
; __device__ __forceinline__ float bf_lo(unsigned w) { return __uint_as_float(w << 16); }
; __device__ __forceinline__ float bf_hi(unsigned w) { return __uint_as_float(w & 0xffff0000u); }
; #define PG8_WAIT_V(n) asm volatile("s_waitcnt vmcnt(" #n ")" ::: "memory")
; #define PG8_BAR __builtin_amdgcn_s_barrier()
;     __device__ __forceinline__ void operator()(const f32x4 (&acc)[2][2][4][2], const Unit& u, int wr, int wc, int fr, int fq) const {
;     ...
;             for (int m = 0; m < 4; ++m) {
;                 const size_t ro = (size_t)(row0 + ai * HALF + m * 16) * DM + col0;
; #pragma unroll
;                 for (int bj = 0; bj < 2; ++bj) {
;                     f32x4 r0, r1;
;                     if (RB) { const u32x4 rw = *(const u32x4*)((const bf16_t*)resid + ro + bj * HALF);
;                         r0 = (f32x4){bf_lo(rw.x), bf_hi(rw.x), bf_lo(rw.y), bf_hi(rw.y)}; r1 = (f32x4){bf_lo(rw.z), bf_hi(rw.z), bf_lo(rw.w), bf_hi(rw.w)}; }
;                     else { r0 = *(const f32x4*)((const float*)resid + ro + bj * HALF); r1 = *(const f32x4*)((const float*)resid + ro + bj * HALF + 4); }
;                     const f32x4 v0 = r0 + gv[bj][0] * acc[ai][bj][m][0], v1 = r1 + gv[bj][1] * acc[ai][bj][m][1];
;                     if (OB) { u32x4 w; w.x = pk2(v0[0], v0[1]); w.y = pk2(v0[2], v0[3]); w.z = pk2(v1[0], v1[1]); w.w = pk2(v1[2], v1[3]); *(u32x4*)((bf16_t*)out + ro + bj * HALF) = w; }
;                     else { *(f32x4*)((float*)out + ro + bj * HALF) = v0; *(f32x4*)((float*)out + ro + bj * HALF + 4) = v1; }
;                 }
; template <class Epi>
; __device__ __forceinline__ void gemm_phase(LAS unsigned char* lds, const Gemm g, const StaticOrder& S, const Epi& E, const int tid) {
;     ...
;         if (!has_next) break;
; #pragma unroll
;         for (int a = 0; a < 2; ++a)
; #pragma unroll
;             for (int b = 0; b < 2; ++b)
; #pragma unroll
;                 for (int m = 0; m < 4; ++m)
; #pragma unroll
;                     for (int n = 0; n < 2; ++n) acc[a][b][m][n] = (f32x4){0.f, 0.f, 0.f, 0.f};
;         cur = nxt; cA = nA; cB = nB; ++ui;
;     }
;     PG8_WAIT_V(0);
;     if (wr == 0) PG8_BAR;
;     PG8_BAR;
	v_pk_fma_f32 v[62:63], v[62:63], v[86:87], v[192:193]
	v_pk_fma_f32 v[64:65], v[64:65], v[88:89], v[194:195]
	v_pk_fma_f32 v[58:59], v[58:59], v[82:83], v[196:197]
	v_pk_fma_f32 v[60:61], v[60:61], v[84:85], v[198:199]
	s_add_u32 s92, s92, 0x20000
	s_addc_u32 s93, s93, 0
	global_load_dwordx4 v[192:195], v175, s[92:93]
	global_load_dwordx4 v[196:199], v175, s[92:93] offset:16
	s_add_u32 s94, s94, 0x50000
	s_addc_u32 s95, s95, 0
	v_cvt_pk_bf16_f32 v62, v62, v63
	v_cvt_pk_bf16_f32 v63, v64, v65
	v_cvt_pk_bf16_f32 v64, v58, v59
	v_cvt_pk_bf16_f32 v65, v60, v61
	global_store_dwordx4 v200, v[62:65], s[94:95]
	s_waitcnt vmcnt(16)
	v_pk_fma_f32 v[54:55], v[54:55], v[70:71], v[210:211]
	v_pk_fma_f32 v[56:57], v[56:57], v[72:73], v[212:213]
	v_pk_fma_f32 v[50:51], v[50:51], v[66:67], v[214:215]
	v_pk_fma_f32 v[52:53], v[52:53], v[68:69], v[216:217]
	global_load_dwordx4 v[210:213], v175, s[92:93] offset:512
	global_load_dwordx4 v[214:217], v175, s[92:93] offset:528
	v_cvt_pk_bf16_f32 v54, v54, v55
	v_cvt_pk_bf16_f32 v55, v56, v57
	v_cvt_pk_bf16_f32 v56, v50, v51
	v_cvt_pk_bf16_f32 v57, v52, v53
	global_store_dwordx4 v200, v[54:57], s[94:95] offset:256
	s_waitcnt vmcnt(16)
	v_pk_fma_f32 v[46:47], v[46:47], v[86:87], v[218:219]
	v_pk_fma_f32 v[48:49], v[48:49], v[88:89], v[220:221]
	v_pk_fma_f32 v[42:43], v[42:43], v[82:83], v[222:223]
	v_pk_fma_f32 v[44:45], v[44:45], v[84:85], v[224:225]
	s_add_u32 s94, s94, 0x10000
	s_addc_u32 s95, s95, 0
	v_cvt_pk_bf16_f32 v46, v46, v47
	v_cvt_pk_bf16_f32 v47, v48, v49
	v_cvt_pk_bf16_f32 v48, v42, v43
	v_cvt_pk_bf16_f32 v49, v44, v45
	global_store_dwordx4 v200, v[46:49], s[94:95]
	s_waitcnt vmcnt(14)
	v_pk_fma_f32 v[38:39], v[38:39], v[70:71], v[226:227]
	v_pk_fma_f32 v[40:41], v[40:41], v[72:73], v[228:229]
	v_pk_fma_f32 v[34:35], v[34:35], v[66:67], v[230:231]
	v_pk_fma_f32 v[36:37], v[36:37], v[68:69], v[232:233]
	v_cvt_pk_bf16_f32 v38, v38, v39
	v_cvt_pk_bf16_f32 v39, v40, v41
	v_cvt_pk_bf16_f32 v40, v34, v35
	v_cvt_pk_bf16_f32 v41, v36, v37
	global_store_dwordx4 v200, v[38:41], s[94:95] offset:256
	s_waitcnt vmcnt(12)
	v_pk_fma_f32 v[30:31], v[30:31], v[86:87], v[176:177]
	v_pk_fma_f32 v[32:33], v[32:33], v[88:89], v[178:179]
	v_pk_fma_f32 v[26:27], v[26:27], v[82:83], v[180:181]
	v_pk_fma_f32 v[28:29], v[28:29], v[84:85], v[182:183]
	s_add_u32 s94, s94, 0x10000
	s_addc_u32 s95, s95, 0
	v_cvt_pk_bf16_f32 v30, v30, v31
	v_cvt_pk_bf16_f32 v31, v32, v33
	v_cvt_pk_bf16_f32 v32, v26, v27
	v_cvt_pk_bf16_f32 v33, v28, v29
	global_store_dwordx4 v200, v[30:33], s[94:95]
	s_waitcnt vmcnt(10)
	v_pk_fma_f32 v[22:23], v[22:23], v[70:71], v[184:185]
	v_pk_fma_f32 v[24:25], v[24:25], v[72:73], v[186:187]
	v_pk_fma_f32 v[18:19], v[18:19], v[66:67], v[188:189]
	v_pk_fma_f32 v[20:21], v[20:21], v[68:69], v[190:191]
	v_cvt_pk_bf16_f32 v22, v22, v23
	v_cvt_pk_bf16_f32 v23, v24, v25
	v_cvt_pk_bf16_f32 v24, v18, v19
	v_cvt_pk_bf16_f32 v25, v20, v21
	global_store_dwordx4 v200, v[22:25], s[94:95] offset:256
	s_waitcnt vmcnt(8)
	v_pk_fma_f32 v[14:15], v[14:15], v[86:87], v[192:193]
	v_pk_fma_f32 v[16:17], v[16:17], v[88:89], v[194:195]
	v_pk_fma_f32 v[10:11], v[10:11], v[82:83], v[196:197]
	v_pk_fma_f32 v[12:13], v[12:13], v[84:85], v[198:199]
	s_add_u32 s94, s94, 0x10000
	s_addc_u32 s95, s95, 0
	v_cvt_pk_bf16_f32 v14, v14, v15
	v_cvt_pk_bf16_f32 v15, v16, v17
	v_cvt_pk_bf16_f32 v16, v10, v11
	v_cvt_pk_bf16_f32 v17, v12, v13
	global_store_dwordx4 v200, v[14:17], s[94:95]
	s_waitcnt vmcnt(6)
	v_pk_fma_f32 v[6:7], v[6:7], v[70:71], v[210:211]
	v_pk_fma_f32 v[8:9], v[8:9], v[72:73], v[212:213]
	v_pk_fma_f32 v[2:3], v[2:3], v[66:67], v[214:215]
	v_pk_fma_f32 v[4:5], v[4:5], v[68:69], v[216:217]
	v_cvt_pk_bf16_f32 v6, v6, v7
	v_cvt_pk_bf16_f32 v7, v8, v9
	v_cvt_pk_bf16_f32 v8, v2, v3
	v_cvt_pk_bf16_f32 v9, v4, v5
	global_store_dwordx4 v200, v[6:9], s[94:95] offset:256
	s_mov_b32 s2, s12
	s_mov_b64 s[20:21], s[14:15]
	s_mov_b64 s[18:19], s[16:17]
	s_and_b64 vcc, exec, s[4:5]
	s_nop 1
	s_cbranch_vccz .LBB0_134
	s_waitcnt vmcnt(0)
	s_cmpk_gt_u32 s29, 0xff
	s_cbranch_scc1 .LBB0_145
	s_barrier

; #define PG8_STAGE(bufoff, gbase, voff) do { _Pragma("unroll") for (int _i = 0; _i < 2; ++_i) \
;         __builtin_amdgcn_global_load_lds((const unsigned*)((const char*)(gbase) + (voff)[_i]), (LAS unsigned*)(lds + (bufoff) + ldsw + _i * 8192), 16, 0, 0); } while (0)
; #define PG8_LDA(dst, b, h) do { _Pragma("unroll") for (int m = 0; m < 4; ++m) _Pragma("unroll") for (int k = 0; k < 2; ++k) dst[m][k] = *(const LAS bf16x8*)(lds + PG8_SA(b, h) + aoff + m * 2048 + k * 1024); } while (0)
; #define PG8_LDB(dst, b, h) do { _Pragma("unroll") for (int n = 0; n < 2; ++n) _Pragma("unroll") for (int k = 0; k < 2; ++k) dst[n][k] = *(const LAS bf16x8*)(lds + PG8_SB(b, h) + boff + n * 2048 + k * 1024); } while (0)
; #define PG8_MMA(ai, bj, At, Bt) do { __builtin_amdgcn_s_setprio(1); _Pragma("unroll") for (int m = 0; m < 4; ++m) _Pragma("unroll") for (int n = 0; n < 2; ++n) _Pragma("unroll") for (int k = 0; k < 2; ++k) \
;         acc[ai][bj][m][n] = __builtin_amdgcn_mfma_f32_16x16x32_bf16(Bt[n][k], At[m][k], acc[ai][bj][m][n], 0, 0, 0); __builtin_amdgcn_s_setprio(0); } while (0)
; #define PG8_WAIT_L(n) asm volatile("s_waitcnt lgkmcnt(" #n ")" ::: "memory")
; #define PG8_BAR __builtin_amdgcn_s_barrier()
; #define PG8_SCHED __builtin_amdgcn_sched_barrier(0)
; template <class Epi>
; __device__ __forceinline__ void gemm_phase(LAS unsigned char* lds, const Gemm g, const StaticOrder& S, const Epi& E, const int tid) {
;     ...
;             const char* a1 = cA + (size_t)(t + 1) * kstep;
;             const char* a2 = last ? nA : cA + (size_t)(t + 2) * kstep; const char* b2 = last ? nB : cB + (size_t)(t + 2) * kstep;
;             const char* a3 = a2 + kstep; const char* b3 = b2 + kstep;
;             PG8_LDB(B0, 0, 0); PG8_SCHED; PG8_LDA(At, 0, 0); PG8_STAGE(PG8_SA(1, 1), a1 + hstep, voffA);
;             PG8_WAIT_L(8); PG8_BAR; PG8_WAIT_L(0); PG8_MMA(0, 0, At, B0); PG8_BAR; PG8_SCHED;
;             PG8_LDB(B1, 0, 1); PG8_STAGE(PG8_SB(0, 0), b2, voffB);
;             PG8_BAR; PG8_WAIT_L(0); PG8_MMA(0, 1, At, B1); PG8_BAR;
;             PG8_LDA(At, 0, 1); PG8_STAGE(PG8_SA(0, 0), a2, voffA);
;             PG8_BAR; PG8_WAIT_L(0); PG8_MMA(1, 0, At, B0); PG8_BAR; PG8_SCHED;
.LBB0_286:
	s_add_u32 s8, s6, 0xfff80080
	s_addc_u32 s9, s7, -1
	s_add_i32 s37, 0, 0x10000
	v_add_u32_e32 v0, s37, v210
	ds_read_b128 v[130:133], v0
	ds_read_b128 v[134:137], v0 offset:1024
	ds_read_b128 v[138:141], v0 offset:2048
	ds_read_b128 v[142:145], v0 offset:3072
	s_cmp_eq_u32 s36, 28
	s_cselect_b32 s35, s3, s9
	s_cselect_b32 s34, s27, s8
	s_cselect_b32 s9, s25, s72
	s_cselect_b32 s8, s50, s66
	v_lshl_add_u64 v[200:201], s[6:7], 0, v[170:171]
	s_add_i32 m0, s21, 0xc000
	ds_read_b128 v[172:175], v211
	ds_read_b128 v[176:179], v211 offset:1024
	ds_read_b128 v[180:183], v211 offset:2048
	ds_read_b128 v[184:187], v211 offset:3072
	ds_read_b128 v[188:191], v211 offset:4096
	ds_read_b128 v[192:195], v211 offset:5120
	ds_read_b128 v[196:199], v211 offset:6144
	ds_read_b128 v[212:215], v211 offset:7168
	global_load_lds_dwordx4 v[200:201], off
	v_lshl_add_u64 v[200:201], s[6:7], 0, v[168:169]
	s_add_i32 m0, s21, 0xe000
	s_nop 0
	global_load_lds_dwordx4 v[200:201], off
	s_waitcnt lgkmcnt(8)
	s_barrier
	s_waitcnt lgkmcnt(0)
	s_setprio 1
	v_mfma_f32_16x16x32_bf16 v[126:129], v[130:133], v[172:175], v[126:129]
	v_mfma_f32_16x16x32_bf16 v[122:125], v[138:141], v[172:175], v[122:125]
	v_mfma_f32_16x16x32_bf16 v[118:121], v[130:133], v[180:183], v[118:121]
	v_mfma_f32_16x16x32_bf16 v[114:117], v[138:141], v[180:183], v[114:117]
	v_mfma_f32_16x16x32_bf16 v[102:105], v[130:133], v[188:191], v[102:105]
	v_mfma_f32_16x16x32_bf16 v[98:101], v[138:141], v[188:191], v[98:101]
	v_mfma_f32_16x16x32_bf16 v[86:89], v[130:133], v[196:199], v[86:89]
	v_mfma_f32_16x16x32_bf16 v[82:85], v[138:141], v[196:199], v[82:85]
	v_mfma_f32_16x16x32_bf16 v[126:129], v[134:137], v[176:179], v[126:129]
	v_mfma_f32_16x16x32_bf16 v[122:125], v[142:145], v[176:179], v[122:125]
	v_mfma_f32_16x16x32_bf16 v[118:121], v[134:137], v[184:187], v[118:121]
	v_mfma_f32_16x16x32_bf16 v[114:117], v[142:145], v[184:187], v[114:117]
	v_mfma_f32_16x16x32_bf16 v[102:105], v[134:137], v[192:195], v[102:105]
	v_mfma_f32_16x16x32_bf16 v[98:101], v[142:145], v[192:195], v[98:101]
	v_mfma_f32_16x16x32_bf16 v[86:89], v[134:137], v[212:215], v[86:89]
	v_mfma_f32_16x16x32_bf16 v[82:85], v[142:145], v[212:215], v[82:85]
	s_setprio 0
	s_barrier
	s_add_i32 s73, 0, 0x14000
	s_add_i32 s37, s37, s39
	v_add_u32_e32 v0, s73, v210
	v_lshl_add_u64 v[200:201], s[8:9], 0, v[162:163]
	s_mov_b32 m0, s37
	ds_read_b128 v[216:219], v0
	ds_read_b128 v[220:223], v0 offset:1024
	ds_read_b128 v[224:227], v0 offset:2048
	ds_read_b128 v[228:231], v0 offset:3072
	global_load_lds_dwordx4 v[200:201], off
	v_lshl_add_u64 v[232:233], s[8:9], 0, v[166:167]
	s_add_i32 m0, s37, 0x2000
	s_nop 0
	global_load_lds_dwordx4 v[232:233], off
	s_barrier
	s_waitcnt lgkmcnt(0)
	s_setprio 1
	v_mfma_f32_16x16x32_bf16 v[110:113], v[216:219], v[172:175], v[110:113]
	v_mfma_f32_16x16x32_bf16 v[106:109], v[224:227], v[172:175], v[106:109]
	v_mfma_f32_16x16x32_bf16 v[94:97], v[216:219], v[180:183], v[94:97]
	v_mfma_f32_16x16x32_bf16 v[90:93], v[224:227], v[180:183], v[90:93]
	v_mfma_f32_16x16x32_bf16 v[78:81], v[216:219], v[188:191], v[78:81]
	v_mfma_f32_16x16x32_bf16 v[74:77], v[224:227], v[188:191], v[74:77]
	v_mfma_f32_16x16x32_bf16 v[70:73], v[216:219], v[196:199], v[70:73]
	v_mfma_f32_16x16x32_bf16 v[66:69], v[224:227], v[196:199], v[66:69]
	v_mfma_f32_16x16x32_bf16 v[110:113], v[220:223], v[176:179], v[110:113]
	v_mfma_f32_16x16x32_bf16 v[106:109], v[228:231], v[176:179], v[106:109]
	v_mfma_f32_16x16x32_bf16 v[94:97], v[220:223], v[184:187], v[94:97]
	v_mfma_f32_16x16x32_bf16 v[90:93], v[228:231], v[184:187], v[90:93]
	v_mfma_f32_16x16x32_bf16 v[78:81], v[220:223], v[192:195], v[78:81]
	v_mfma_f32_16x16x32_bf16 v[74:77], v[228:231], v[192:195], v[74:77]
	v_mfma_f32_16x16x32_bf16 v[70:73], v[220:223], v[212:215], v[70:73]
	v_mfma_f32_16x16x32_bf16 v[66:69], v[228:231], v[212:215], v[66:69]
	s_setprio 0
	s_mov_b32 m0, s21
	v_lshl_add_u64 v[234:235], s[34:35], 0, v[160:161]
	s_barrier
	ds_read_b128 v[172:175], v211 offset:16384
	ds_read_b128 v[176:179], v211 offset:17408
	ds_read_b128 v[180:183], v211 offset:18432
	ds_read_b128 v[184:187], v211 offset:19456
	ds_read_b128 v[188:191], v211 offset:20480
	ds_read_b128 v[192:195], v211 offset:21504
	ds_read_b128 v[196:199], v211 offset:22528
	ds_read_b128 v[212:215], v211 offset:23552
	global_load_lds_dwordx4 v[234:235], off
	v_lshl_add_u64 v[236:237], s[34:35], 0, v[164:165]
	s_mov_b32 m0, s40
	s_nop 0
	global_load_lds_dwordx4 v[236:237], off
	s_barrier
	s_waitcnt lgkmcnt(0)
	s_setprio 1
	v_mfma_f32_16x16x32_bf16 v[62:65], v[130:133], v[172:175], v[62:65]
	v_mfma_f32_16x16x32_bf16 v[58:61], v[138:141], v[172:175], v[58:61]
	v_mfma_f32_16x16x32_bf16 v[54:57], v[130:133], v[180:183], v[54:57]
	v_mfma_f32_16x16x32_bf16 v[50:53], v[138:141], v[180:183], v[50:53]
	v_mfma_f32_16x16x32_bf16 v[38:41], v[130:133], v[188:191], v[38:41]
	v_mfma_f32_16x16x32_bf16 v[34:37], v[138:141], v[188:191], v[34:37]
	v_mfma_f32_16x16x32_bf16 v[22:25], v[130:133], v[196:199], v[22:25]
	v_mfma_f32_16x16x32_bf16 v[18:21], v[138:141], v[196:199], v[18:21]
	v_mfma_f32_16x16x32_bf16 v[62:65], v[134:137], v[176:179], v[62:65]
	v_mfma_f32_16x16x32_bf16 v[58:61], v[142:145], v[176:179], v[58:61]
	v_mfma_f32_16x16x32_bf16 v[54:57], v[134:137], v[184:187], v[54:57]
	v_mfma_f32_16x16x32_bf16 v[50:53], v[142:145], v[184:187], v[50:53]
	v_mfma_f32_16x16x32_bf16 v[38:41], v[134:137], v[192:195], v[38:41]
	v_mfma_f32_16x16x32_bf16 v[34:37], v[142:145], v[192:195], v[34:37]
	v_mfma_f32_16x16x32_bf16 v[22:25], v[134:137], v[212:215], v[22:25]
	v_mfma_f32_16x16x32_bf16 v[18:21], v[142:145], v[212:215], v[18:21]
	s_setprio 0
	s_barrier
; #define PG8_STAGE(bufoff, gbase, voff) do { _Pragma("unroll") for (int _i = 0; _i < 2; ++_i) \
;         __builtin_amdgcn_global_load_lds((const unsigned*)((const char*)(gbase) + (voff)[_i]), (LAS unsigned*)(lds + (bufoff) + ldsw + _i * 8192), 16, 0, 0); } while (0)
; #define PG8_LDA(dst, b, h) do { _Pragma("unroll") for (int m = 0; m < 4; ++m) _Pragma("unroll") for (int k = 0; k < 2; ++k) dst[m][k] = *(const LAS bf16x8*)(lds + PG8_SA(b, h) + aoff + m * 2048 + k * 1024); } while (0)
; #define PG8_LDB(dst, b, h) do { _Pragma("unroll") for (int n = 0; n < 2; ++n) _Pragma("unroll") for (int k = 0; k < 2; ++k) dst[n][k] = *(const LAS bf16x8*)(lds + PG8_SB(b, h) + boff + n * 2048 + k * 1024); } while (0)
; #define PG8_MMA(ai, bj, At, Bt) do { __builtin_amdgcn_s_setprio(1); _Pragma("unroll") for (int m = 0; m < 4; ++m) _Pragma("unroll") for (int n = 0; n < 2; ++n) _Pragma("unroll") for (int k = 0; k < 2; ++k) \
;         acc[ai][bj][m][n] = __builtin_amdgcn_mfma_f32_16x16x32_bf16(Bt[n][k], At[m][k], acc[ai][bj][m][n], 0, 0, 0); __builtin_amdgcn_s_setprio(0); } while (0)
; #define PG8_WAIT_V(n) asm volatile("s_waitcnt vmcnt(" #n ")" ::: "memory")
; #define PG8_WAIT_L(n) asm volatile("s_waitcnt lgkmcnt(" #n ")" ::: "memory")
; #define PG8_BAR __builtin_amdgcn_s_barrier()
; #define PG8_SCHED __builtin_amdgcn_sched_barrier(0)
; template <class Epi>
; __device__ __forceinline__ void gemm_phase(LAS unsigned char* lds, const Gemm g, const StaticOrder& S, const Epi& E, const int tid) {
;     ...
;             PG8_STAGE(PG8_SB(0, 1), b2 + hstep, voffB);
;             PG8_WAIT_V(6); PG8_BAR; PG8_MMA(1, 1, At, B1); PG8_BAR;
;             PG8_LDB(B0, 1, 0); PG8_SCHED; PG8_LDA(At, 1, 0); PG8_STAGE(PG8_SA(0, 1), a2 + hstep, voffA);
;             PG8_WAIT_L(8); PG8_BAR; PG8_WAIT_L(0); PG8_MMA(0, 0, At, B0); PG8_BAR; PG8_SCHED;
;             PG8_LDB(B1, 1, 1); PG8_STAGE(PG8_SB(1, 0), b3, voffB);
;             PG8_BAR; PG8_WAIT_L(0); PG8_MMA(0, 1, At, B1); PG8_BAR;
	s_add_u32 s74, s8, 0x80000
	s_addc_u32 s75, s9, 0
	s_add_i32 s37, s73, s39
	v_lshl_add_u64 v[130:131], s[74:75], 0, v[162:163]
	s_mov_b32 m0, s37
	s_nop 0
	global_load_lds_dwordx4 v[130:131], off
	v_lshl_add_u64 v[130:131], s[74:75], 0, v[166:167]
	s_add_i32 m0, s37, 0x2000
	s_nop 0
	global_load_lds_dwordx4 v[130:131], off
	s_waitcnt vmcnt(6)
	s_barrier
	s_setprio 1
	v_mfma_f32_16x16x32_bf16 v[46:49], v[216:219], v[172:175], v[46:49]
	v_mfma_f32_16x16x32_bf16 v[42:45], v[224:227], v[172:175], v[42:45]
	v_mfma_f32_16x16x32_bf16 v[30:33], v[216:219], v[180:183], v[30:33]
	v_mfma_f32_16x16x32_bf16 v[26:29], v[224:227], v[180:183], v[26:29]
	v_mfma_f32_16x16x32_bf16 v[14:17], v[216:219], v[188:191], v[14:17]
	v_mfma_f32_16x16x32_bf16 v[10:13], v[224:227], v[188:191], v[10:13]
	v_mfma_f32_16x16x32_bf16 v[6:9], v[216:219], v[196:199], v[6:9]
	v_mfma_f32_16x16x32_bf16 v[2:5], v[224:227], v[196:199], v[2:5]
	v_mfma_f32_16x16x32_bf16 v[46:49], v[220:223], v[176:179], v[46:49]
	v_mfma_f32_16x16x32_bf16 v[42:45], v[228:231], v[176:179], v[42:45]
	v_mfma_f32_16x16x32_bf16 v[30:33], v[220:223], v[184:187], v[30:33]
	v_mfma_f32_16x16x32_bf16 v[26:29], v[228:231], v[184:187], v[26:29]
	v_mfma_f32_16x16x32_bf16 v[14:17], v[220:223], v[192:195], v[14:17]
	v_mfma_f32_16x16x32_bf16 v[10:13], v[228:231], v[192:195], v[10:13]
	v_mfma_f32_16x16x32_bf16 v[6:9], v[220:223], v[212:215], v[6:9]
	v_mfma_f32_16x16x32_bf16 v[2:5], v[228:231], v[212:215], v[2:5]
	s_setprio 0
	s_add_i32 s37, 0, 0x18000
	v_add_u32_e32 v0, s37, v210
	s_barrier
	ds_read_b128 v[130:133], v0
	ds_read_b128 v[134:137], v0 offset:1024
	ds_read_b128 v[138:141], v0 offset:2048
	ds_read_b128 v[142:145], v0 offset:3072
	s_add_u32 s34, s34, 0x80000
	s_addc_u32 s35, s35, 0
	s_mov_b32 m0, s41
	v_lshl_add_u64 v[216:217], s[34:35], 0, v[160:161]
	ds_read_b128 v[172:175], v211 offset:32768
	ds_read_b128 v[176:179], v211 offset:33792
	ds_read_b128 v[180:183], v211 offset:34816
	ds_read_b128 v[184:187], v211 offset:35840
	ds_read_b128 v[188:191], v211 offset:36864
	ds_read_b128 v[192:195], v211 offset:37888
	ds_read_b128 v[196:199], v211 offset:38912
	ds_read_b128 v[212:215], v211 offset:39936
	global_load_lds_dwordx4 v[216:217], off
	v_lshl_add_u64 v[216:217], s[34:35], 0, v[164:165]
	s_mov_b32 m0, s42
	s_nop 0
	global_load_lds_dwordx4 v[216:217], off
	s_waitcnt lgkmcnt(8)
	s_barrier
	s_waitcnt lgkmcnt(0)
	s_setprio 1
	v_mfma_f32_16x16x32_bf16 v[126:129], v[130:133], v[172:175], v[126:129]
	v_mfma_f32_16x16x32_bf16 v[122:125], v[138:141], v[172:175], v[122:125]
	v_mfma_f32_16x16x32_bf16 v[118:121], v[130:133], v[180:183], v[118:121]
	v_mfma_f32_16x16x32_bf16 v[114:117], v[138:141], v[180:183], v[114:117]
	v_mfma_f32_16x16x32_bf16 v[102:105], v[130:133], v[188:191], v[102:105]
	v_mfma_f32_16x16x32_bf16 v[98:101], v[138:141], v[188:191], v[98:101]
	v_mfma_f32_16x16x32_bf16 v[86:89], v[130:133], v[196:199], v[86:89]
	v_mfma_f32_16x16x32_bf16 v[82:85], v[138:141], v[196:199], v[82:85]
	v_mfma_f32_16x16x32_bf16 v[126:129], v[134:137], v[176:179], v[126:129]
	v_mfma_f32_16x16x32_bf16 v[122:125], v[142:145], v[176:179], v[122:125]
	v_mfma_f32_16x16x32_bf16 v[118:121], v[134:137], v[184:187], v[118:121]
	v_mfma_f32_16x16x32_bf16 v[114:117], v[142:145], v[184:187], v[114:117]
	v_mfma_f32_16x16x32_bf16 v[102:105], v[134:137], v[192:195], v[102:105]
	v_mfma_f32_16x16x32_bf16 v[98:101], v[142:145], v[192:195], v[98:101]
	v_mfma_f32_16x16x32_bf16 v[86:89], v[134:137], v[212:215], v[86:89]
	v_mfma_f32_16x16x32_bf16 v[82:85], v[142:145], v[212:215], v[82:85]
	s_setprio 0
	s_barrier
	s_add_i32 s34, 0, 0x1c000
	s_add_i32 s35, s37, s39
	v_add_u32_e32 v0, s34, v210
	v_lshl_add_u64 v[200:201], v[200:201], 0, s[56:57]
	s_mov_b32 m0, s35
	ds_read_b128 v[216:219], v0
	ds_read_b128 v[220:223], v0 offset:1024
	ds_read_b128 v[224:227], v0 offset:2048
	ds_read_b128 v[228:231], v0 offset:3072
	global_load_lds_dwordx4 v[200:201], off
	v_lshl_add_u64 v[200:201], v[232:233], 0, s[56:57]
	s_add_i32 m0, s35, 0x2000
	s_nop 0
	global_load_lds_dwordx4 v[200:201], off
	s_barrier
	s_waitcnt lgkmcnt(0)
	s_setprio 1
	v_mfma_f32_16x16x32_bf16 v[110:113], v[216:219], v[172:175], v[110:113]
	v_mfma_f32_16x16x32_bf16 v[106:109], v[224:227], v[172:175], v[106:109]
	v_mfma_f32_16x16x32_bf16 v[94:97], v[216:219], v[180:183], v[94:97]
	v_mfma_f32_16x16x32_bf16 v[90:93], v[224:227], v[180:183], v[90:93]
	v_mfma_f32_16x16x32_bf16 v[78:81], v[216:219], v[188:191], v[78:81]
	v_mfma_f32_16x16x32_bf16 v[74:77], v[224:227], v[188:191], v[74:77]
	v_mfma_f32_16x16x32_bf16 v[70:73], v[216:219], v[196:199], v[70:73]
	v_mfma_f32_16x16x32_bf16 v[66:69], v[224:227], v[196:199], v[66:69]
	v_mfma_f32_16x16x32_bf16 v[110:113], v[220:223], v[176:179], v[110:113]
	v_mfma_f32_16x16x32_bf16 v[106:109], v[228:231], v[176:179], v[106:109]
	v_mfma_f32_16x16x32_bf16 v[94:97], v[220:223], v[184:187], v[94:97]
	v_mfma_f32_16x16x32_bf16 v[90:93], v[228:231], v[184:187], v[90:93]
	v_mfma_f32_16x16x32_bf16 v[78:81], v[220:223], v[192:195], v[78:81]
	v_mfma_f32_16x16x32_bf16 v[74:77], v[228:231], v[192:195], v[74:77]
	v_mfma_f32_16x16x32_bf16 v[70:73], v[220:223], v[212:215], v[70:73]
	v_mfma_f32_16x16x32_bf16 v[66:69], v[228:231], v[212:215], v[66:69]
	s_setprio 0
	s_mov_b32 m0, s49
	v_lshl_add_u64 v[200:201], v[234:235], 0, s[56:57]
	s_barrier
; __device__ __forceinline__ unsigned pk2(float lo, float hi) { f32x2 v = {lo, hi}; return __builtin_bit_cast(unsigned, __builtin_convertvector(v, bf16x2_t)); }
; #define PG8_STAGE(bufoff, gbase, voff) do { _Pragma("unroll") for (int _i = 0; _i < 2; ++_i) \
;         __builtin_amdgcn_global_load_lds((const unsigned*)((const char*)(gbase) + (voff)[_i]), (LAS unsigned*)(lds + (bufoff) + ldsw + _i * 8192), 16, 0, 0); } while (0)
;     __device__ __forceinline__ void operator()(const f32x4 (&acc)[2][2][4][2], const Unit& u, int wr, int wc, int fr, int fq) const {
;     ...
;         const int type = (u.pn >> 2) % 3, grp = u.pn / 12;
;         const int row0 = u.pm * BM + wr * 64 + fr, col0 = u.pn * BM + wc * 32 + 8 * fq;
;         if (type == 2) {
; #pragma unroll
;             for (int ai = 0; ai < 2; ++ai)
; #pragma unroll
;                 for (int m = 0; m < 4; ++m) {
;                     bf16_t* rowp = O + ((size_t)(2 * u.pn) * MTOK + (row0 + ai * HALF + m * 16)) * 128 + wc * 32 + 8 * fq;
; #pragma unroll
;                     for (int bj = 0; bj < 2; ++bj) { const f32x4 v0 = acc[ai][bj][m][0], v1 = acc[ai][bj][m][1];
;                         u32x4 w; w.x = pk2(v0[0], v0[1]); w.y = pk2(v0[2], v0[3]); w.z = pk2(v1[0], v1[1]); w.w = pk2(v1[2], v1[3]); *(u32x4*)(rowp + (size_t)bj * MTOK * 128) = w; }
;                 }
;             return;
;         }
; #pragma unroll
;         for (int ai = 0; ai < 2; ++ai)
; #pragma unroll
;             for (int m = 0; m < 4; ++m)
; #pragma unroll
;                 for (int bj = 0; bj < 2; ++bj) {
;                     const f32x4 a = acc[ai][bj][m][0], b = acc[ai][bj][m][1];
;                     float s = (a[0] * a[0] + a[1] * a[1]) + (a[2] * a[2] + a[3] * a[3]) + (b[0] * b[0] + b[1] * b[1]) + (b[2] * b[2] + b[3] * b[3]);
;                     s += __shfl_xor(s, 16); s += __shfl_xor(s, 32);
;                     if (fq == 0) T[((wr * 128 + ai * 64 + m * 16 + fr) * 2 + bj) * 4 + wc] = s;
; template <class Epi>
; __device__ __forceinline__ void gemm_phase(LAS unsigned char* lds, const Gemm g, const StaticOrder& S, const Epi& E, const int tid) {
;     ...
;             PG8_LDA(At, 1, 1); PG8_STAGE(PG8_SA(1, 0), a3, voffA);
;             PG8_BAR; PG8_WAIT_L(0); PG8_MMA(1, 0, At, B0); PG8_BAR; PG8_SCHED;
;             PG8_STAGE(PG8_SB(1, 1), b3 + hstep, voffB);
;             PG8_WAIT_V(6); PG8_BAR; PG8_MMA(1, 1, At, B1); PG8_BAR;
;         }
	ds_read_b128 v[172:175], v211 offset:49152
	ds_read_b128 v[176:179], v211 offset:50176
	ds_read_b128 v[180:183], v211 offset:51200
	ds_read_b128 v[184:187], v211 offset:52224
	ds_read_b128 v[188:191], v211 offset:53248
	ds_read_b128 v[192:195], v211 offset:54272
	ds_read_b128 v[196:199], v211 offset:55296
	ds_read_b128 v[212:215], v211 offset:56320
	global_load_lds_dwordx4 v[200:201], off
	v_lshl_add_u64 v[200:201], v[236:237], 0, s[56:57]
	s_mov_b32 m0, s52
	s_nop 0
	global_load_lds_dwordx4 v[200:201], off
	s_barrier
	s_waitcnt lgkmcnt(0)
	s_setprio 1
	v_mfma_f32_16x16x32_bf16 v[62:65], v[130:133], v[172:175], v[62:65]
	v_mfma_f32_16x16x32_bf16 v[58:61], v[138:141], v[172:175], v[58:61]
	v_mfma_f32_16x16x32_bf16 v[54:57], v[130:133], v[180:183], v[54:57]
	v_mfma_f32_16x16x32_bf16 v[50:53], v[138:141], v[180:183], v[50:53]
	v_mfma_f32_16x16x32_bf16 v[38:41], v[130:133], v[188:191], v[38:41]
	v_mfma_f32_16x16x32_bf16 v[34:37], v[138:141], v[188:191], v[34:37]
	v_mfma_f32_16x16x32_bf16 v[22:25], v[130:133], v[196:199], v[22:25]
	v_mfma_f32_16x16x32_bf16 v[18:21], v[138:141], v[196:199], v[18:21]
	v_mfma_f32_16x16x32_bf16 v[62:65], v[134:137], v[176:179], v[62:65]
	v_mfma_f32_16x16x32_bf16 v[58:61], v[142:145], v[176:179], v[58:61]
	v_mfma_f32_16x16x32_bf16 v[54:57], v[134:137], v[184:187], v[54:57]
	v_mfma_f32_16x16x32_bf16 v[50:53], v[142:145], v[184:187], v[50:53]
	v_mfma_f32_16x16x32_bf16 v[38:41], v[134:137], v[192:195], v[38:41]
	v_mfma_f32_16x16x32_bf16 v[34:37], v[142:145], v[192:195], v[34:37]
	v_mfma_f32_16x16x32_bf16 v[22:25], v[134:137], v[212:215], v[22:25]
	v_mfma_f32_16x16x32_bf16 v[18:21], v[142:145], v[212:215], v[18:21]
	s_setprio 0
	s_barrier
	s_add_u32 s8, s8, 0x80080
	s_addc_u32 s9, s9, 0
	s_add_i32 s34, s34, s39
	v_lshl_add_u64 v[130:131], s[8:9], 0, v[162:163]
	s_mov_b32 m0, s34
	s_nop 0
	global_load_lds_dwordx4 v[130:131], off
	v_lshl_add_u64 v[130:131], s[8:9], 0, v[166:167]
	s_add_i32 m0, s34, 0x2000
	s_nop 0
	global_load_lds_dwordx4 v[130:131], off
	s_waitcnt vmcnt(6)
	s_barrier
	s_setprio 1
	v_mfma_f32_16x16x32_bf16 v[46:49], v[216:219], v[172:175], v[46:49]
	v_mfma_f32_16x16x32_bf16 v[42:45], v[224:227], v[172:175], v[42:45]
	v_mfma_f32_16x16x32_bf16 v[30:33], v[216:219], v[180:183], v[30:33]
	v_mfma_f32_16x16x32_bf16 v[26:29], v[224:227], v[180:183], v[26:29]
	v_mfma_f32_16x16x32_bf16 v[14:17], v[216:219], v[188:191], v[14:17]
	v_mfma_f32_16x16x32_bf16 v[10:13], v[224:227], v[188:191], v[10:13]
	v_mfma_f32_16x16x32_bf16 v[6:9], v[216:219], v[196:199], v[6:9]
	v_mfma_f32_16x16x32_bf16 v[2:5], v[224:227], v[196:199], v[2:5]
	v_mfma_f32_16x16x32_bf16 v[46:49], v[220:223], v[176:179], v[46:49]
	v_mfma_f32_16x16x32_bf16 v[42:45], v[228:231], v[176:179], v[42:45]
	v_mfma_f32_16x16x32_bf16 v[30:33], v[220:223], v[184:187], v[30:33]
	v_mfma_f32_16x16x32_bf16 v[26:29], v[228:231], v[184:187], v[26:29]
	v_mfma_f32_16x16x32_bf16 v[14:17], v[220:223], v[192:195], v[14:17]
	v_mfma_f32_16x16x32_bf16 v[10:13], v[228:231], v[192:195], v[10:13]
	v_mfma_f32_16x16x32_bf16 v[6:9], v[220:223], v[212:215], v[6:9]
	v_mfma_f32_16x16x32_bf16 v[2:5], v[228:231], v[212:215], v[2:5]
	s_setprio 0
	s_add_i32 s36, s36, 2
	s_add_u32 s66, s66, 0x100
	s_addc_u32 s72, s72, 0
	s_add_u32 s6, s6, 0x100
	s_addc_u32 s7, s7, 0
	s_cmp_gt_u32 s36, 29
	s_barrier
	s_cbranch_scc0 .LBB0_286
	s_ashr_i32 s3, s20, 2
	s_mul_hi_i32 s6, s3, 0x55555556
	s_lshr_b32 s7, s6, 31
	s_add_i32 s6, s6, s7
	s_mul_i32 s6, s6, 3
	s_lshl_b32 s2, s2, 8
	v_mov_b32_e32 v138, v159
	v_mov_b32_e32 v0, v209
	s_sub_i32 s6, s3, s6
	s_add_i32 s2, s2, s47
	s_cmp_eq_u32 s6, 2
	v_add_u32_e32 v174, s2, v138
	v_lshlrev_b32_e32 v172, 3, v0
	s_mov_b64 s[2:3], -1
	s_cbranch_scc1 .LBB0_376
	v_mul_f32_e32 v132, v127, v127
	v_mul_f32_e32 v133, v129, v129
	v_fmac_f32_e32 v132, v126, v126
	v_fmac_f32_e32 v133, v128, v128
	v_and_b32_e32 v131, 64, v204
	v_add_f32_e32 v132, v132, v133
	v_mul_f32_e32 v133, v123, v123
	v_xor_b32_e32 v130, 16, v204
	v_add_u32_e32 v131, 64, v131
	v_fmac_f32_e32 v133, v122, v122
	v_cmp_lt_i32_e32 vcc, v130, v131
	v_add_f32_e32 v132, v132, v133
	v_mul_f32_e32 v133, v125, v125
	v_cndmask_b32_e32 v130, v204, v130, vcc
	v_fmac_f32_e32 v133, v124, v124
	v_lshlrev_b32_e32 v130, 2, v130
	v_add_f32_e32 v132, v133, v132
	ds_bpermute_b32 v133, v130, v132
	v_xor_b32_e32 v134, 32, v204
	v_cmp_lt_i32_e32 vcc, v134, v131
	v_lshlrev_b32_e32 v175, 5, v138
	s_waitcnt lgkmcnt(0)
	v_add_f32_e32 v132, v132, v133
	v_cndmask_b32_e32 v131, v204, v134, vcc
	v_lshlrev_b32_e32 v212, 2, v131
	ds_bpermute_b32 v133, v212, v132
	v_cmp_eq_u32_e32 vcc, 0, v0
	v_add_u32_e32 v131, s63, v175
	s_and_saveexec_b64 s[2:3], vcc
	s_cbranch_execz .LBB0_290
	s_waitcnt lgkmcnt(0)
	v_add_f32_e32 v132, v132, v133
	ds_write_b32 v131, v132
